# speedup vs baseline: 1.0077x; 1.0077x over previous
; #define TILE_RC(w_, brow_, bcol_) do { const int wg_ = ((w_) & 7) * qx + ((w_) >> 3); const int gid_ = wg_ / nig; \
;     brow_ = (gid_ * 8 + ((wg_ % nig) & 7)) * 256; bcol_ = ((wg_ % nig) >> 3) * 256; } while (0)
; #define ISSUE7(brow_, bcol_) do { \
;     STAGE_BX(SB_OFF(0, 0), 0, 0, bcol_); STAGE_AX(SA_OFF(0, 0), 0, 0, brow_); STAGE_BX(SB_OFF(0, 1), 1, 0, bcol_); STAGE_AX(SA_OFF(0, 1), 1, 0, brow_); \
;     STAGE_BX(SB_OFF(1, 0), 0, 1, bcol_); STAGE_AX(SA_OFF(1, 0), 0, 1, brow_); STAGE_BX(SB_OFF(1, 1), 1, 1, bcol_); } while (0)
; template <int EPI, int N, int K>
; __device__ __forceinline__ void gemm_phase(const bf16_t* __restrict__ A, const bf16_t* __restrict__ Bt, const EpiArgs ea) {
;     ...
;     const int c0 = bcol + wc * 64 + fr * 4;
;     const int wn = w + gridDim.x;
;     if (EPI == EPI_RES) {
;       if (wn < nwg) { int nbrow, nbcol; TILE_RC(wn, nbrow, nbcol); ISSUE7(nbrow, nbcol); }
; #pragma unroll
;       for (int ai = 0; ai < 2; ++ai)
; #pragma unroll
;         for (int m = 0; m < 4; ++m)
; #pragma unroll
;           for (int j = 0; j < 4; ++j) {
;             const int row = brow + ai * 128 + wr * 64 + m * 16 + fq * 4 + j;
;             const u32x2 x2 = *(const u32x2*)(ea.outb + (size_t)row * DM + c0);
.LBB0_393:
	s_or_b64 exec, exec, s[2:3]
	s_and_b32 s2, s12, 0xffffff00
	v_readlane_b32 vcc_lo, v236, 14
	v_readlane_b32 vcc_hi, v236, 15
	v_add_u32_e32 v226, s31, v146
	v_add_u32_e32 v227, s2, v145
	v_lshlrev_b32_e32 v226, 12, v226
	v_lshl_add_u32 v226, v227, 1, v226
	s_nop 3
	global_load_dwordx2 v[162:163], v226, vcc
	v_add_u32_e32 v227, 0x1000, v226
	global_load_dwordx2 v[164:165], v227, vcc
	v_add_u32_e32 v228, 0x2000, v226
	global_load_dwordx2 v[166:167], v228, vcc
	v_add_u32_e32 v227, 0x3000, v226
	global_load_dwordx2 v[168:169], v227, vcc
	v_add_u32_e32 v228, 0x10000, v226
	global_load_dwordx2 v[170:171], v228, vcc
	v_add_u32_e32 v227, 0x11000, v226
	global_load_dwordx2 v[172:173], v227, vcc
	v_add_u32_e32 v228, 0x12000, v226
	global_load_dwordx2 v[174:175], v228, vcc
	v_add_u32_e32 v227, 0x13000, v226
	global_load_dwordx2 v[176:177], v227, vcc
	v_add_u32_e32 v228, 0x20000, v226
	global_load_dwordx2 v[178:179], v228, vcc
	v_add_u32_e32 v227, 0x21000, v226
	global_load_dwordx2 v[180:181], v227, vcc
	v_add_u32_e32 v228, 0x22000, v226
	global_load_dwordx2 v[182:183], v228, vcc
	v_add_u32_e32 v227, 0x23000, v226
	global_load_dwordx2 v[184:185], v227, vcc
	v_add_u32_e32 v228, 0x30000, v226
	global_load_dwordx2 v[186:187], v228, vcc
	v_add_u32_e32 v227, 0x31000, v226
	global_load_dwordx2 v[188:189], v227, vcc
	v_add_u32_e32 v228, 0x32000, v226
	global_load_dwordx2 v[190:191], v228, vcc
	v_add_u32_e32 v227, 0x33000, v226
	global_load_dwordx2 v[192:193], v227, vcc
	v_add_u32_e32 v228, 0x80000, v226
	global_load_dwordx2 v[194:195], v228, vcc
	v_add_u32_e32 v227, 0x81000, v226
	global_load_dwordx2 v[196:197], v227, vcc
	v_add_u32_e32 v228, 0x82000, v226
	global_load_dwordx2 v[198:199], v228, vcc
	v_add_u32_e32 v227, 0x83000, v226
	global_load_dwordx2 v[200:201], v227, vcc
	v_add_u32_e32 v228, 0x90000, v226
	global_load_dwordx2 v[202:203], v228, vcc
	v_add_u32_e32 v227, 0x91000, v226
	global_load_dwordx2 v[204:205], v227, vcc
	v_add_u32_e32 v228, 0x92000, v226
	global_load_dwordx2 v[206:207], v228, vcc
	v_add_u32_e32 v227, 0x93000, v226
	global_load_dwordx2 v[208:209], v227, vcc
	v_add_u32_e32 v228, 0xa0000, v226
	global_load_dwordx2 v[210:211], v228, vcc
	v_add_u32_e32 v227, 0xa1000, v226
	global_load_dwordx2 v[212:213], v227, vcc
	v_add_u32_e32 v228, 0xa2000, v226
	global_load_dwordx2 v[214:215], v228, vcc
	v_add_u32_e32 v227, 0xa3000, v226
	global_load_dwordx2 v[216:217], v227, vcc
	v_add_u32_e32 v228, 0xb0000, v226
	global_load_dwordx2 v[218:219], v228, vcc
	v_add_u32_e32 v227, 0xb1000, v226
	global_load_dwordx2 v[220:221], v227, vcc
	v_add_u32_e32 v228, 0xb2000, v226
	global_load_dwordx2 v[222:223], v228, vcc
	v_add_u32_e32 v227, 0xb3000, v226
	global_load_dwordx2 v[224:225], v227, vcc
	s_add_i32 s30, s30, s33
	s_cmpk_gt_i32 s30, 0x1ff
	s_cselect_b64 s[12:13], -1, 0
	s_and_b64 vcc, exec, s[12:13]
	s_cbranch_vccnz .Lres_a_last
	s_lshl_b32 s3, s30, 6
	s_and_b32 s3, s3, 0x1c0
	s_ashr_i32 s34, s30, 3
	s_add_i32 s3, s3, s34
	s_ashr_i32 s34, s3, 31
	s_lshr_b32 s34, s34, 26
	s_add_i32 s34, s3, s34
	s_and_b32 s35, s34, 0xffffffc0
	s_sub_i32 s3, s3, s35
	s_lshl_b32 s34, s34, 17
	s_lshl_b32 s35, s3, 20
	s_lshl_b32 s3, s3, 17
	s_and_b32 s34, s34, 0xff800000
	s_and_b32 s35, s35, 0x700000
	s_and_b32 s3, s3, 0xfff00000
	s_mov_b32 m0, s15
	s_nop 0
	buffer_load_dwordx4 v144, s[76:79], s3 offen lds
	s_or_b32 s34, s35, s34
	s_or_b32 s35, s3, 0x80000
	s_mov_b32 m0, s16
	s_nop 0
	buffer_load_dwordx4 v144, s[76:79], s35 offen lds
	s_mov_b32 s62, s50
	s_mov_b32 s63, s51
	s_mov_b32 m0, s14
	s_nop 0
	buffer_load_dwordx4 v131, s[60:63], s34 offen lds
	s_or_b32 s35, s34, 0x40000
	s_mov_b32 m0, s17
	s_nop 0
	buffer_load_dwordx4 v131, s[60:63], s35 offen lds
	s_or_b32 s35, s3, 0x2000
	s_mov_b32 m0, s18
	s_nop 0
	buffer_load_dwordx4 v144, s[76:79], s35 offen lds
	s_or_b32 s35, s3, 0x82000
	s_mov_b32 m0, s19
	s_nop 0
	buffer_load_dwordx4 v144, s[76:79], s35 offen lds
	s_or_b32 s35, s34, 0x80000
	s_mov_b32 m0, s20
	s_nop 0
	buffer_load_dwordx4 v131, s[60:63], s35 offen lds
	s_or_b32 s35, s34, 0xc0000
	s_mov_b32 m0, s21
	s_nop 0
	buffer_load_dwordx4 v131, s[60:63], s35 offen lds
	s_or_b32 s35, s3, 0x80
	s_mov_b32 m0, s22
	s_nop 0
	buffer_load_dwordx4 v144, s[76:79], s35 offen lds
	s_or_b32 s35, s3, 0x80080
	s_mov_b32 m0, s23
	s_nop 0
	buffer_load_dwordx4 v144, s[76:79], s35 offen lds
	s_or_b32 s35, s34, 0x80
	s_mov_b32 m0, s24
	s_nop 0
	buffer_load_dwordx4 v131, s[60:63], s35 offen lds
	s_or_b32 s34, s34, 0x40080
	s_mov_b32 m0, s25
	s_nop 0
	buffer_load_dwordx4 v131, s[60:63], s34 offen lds
	s_or_b32 s34, s3, 0x2080
	s_mov_b32 m0, s26
	s_nop 0
	buffer_load_dwordx4 v144, s[76:79], s34 offen lds
	s_or_b32 s3, s3, 0x82080
	s_mov_b32 m0, s27
	s_nop 0
	buffer_load_dwordx4 v144, s[76:79], s3 offen lds
	s_waitcnt vmcnt(14)
; __device__ __forceinline__ float row16_sum(float v) { DPP_ADD(v, 0x128); DPP_ADD(v, 0x124); DPP_ADD(v, 0x122); DPP_ADD(v, 0x121); return v; }
; template <int EPI, int N, int K>
; __device__ __forceinline__ void gemm_phase(const bf16_t* __restrict__ A, const bf16_t* __restrict__ Bt, const EpiArgs ea) {
;     ...
;           for (int j = 0; j < 4; ++j) {
;             const int row = brow + ai * 128 + wr * 64 + m * 16 + fq * 4 + j;
;             const u32x2 x2 = *(const u32x2*)(ea.outb + (size_t)row * DM + c0);
;             float4 xn;
;             xn.x = __builtin_bit_cast(float, x2[0] << 16) + acc[ai][0][m][0][j]; xn.y = __builtin_bit_cast(float, x2[0] & 0xffff0000u) + acc[ai][0][m][1][j];
;             xn.z = __builtin_bit_cast(float, x2[1] << 16) + acc[ai][1][m][0][j]; xn.w = __builtin_bit_cast(float, x2[1] & 0xffff0000u) + acc[ai][1][m][1][j];
;             u32x2 o = {pk2(xn.x, xn.y), pk2(xn.z, xn.w)};
;             st_wt(ea.outb + (size_t)row * DM + c0, o);
;             float ss = xn.x * xn.x + xn.y * xn.y + xn.z * xn.z + xn.w * xn.w;
;             ss = row16_sum(ss);
;             if (fr == 0) __hip_atomic_fetch_add(ea.rowsq_out + row, (rsq_t)(ss * RSQ_SCALE), __ATOMIC_RELAXED, __HIP_MEMORY_SCOPE_AGENT);
.LBB0_395:
	v_add_u32_e32 v134, s2, v145
	v_add_u32_e32 v132, s31, v146
	v_readlane_b32 s2, v236, 14
	v_ashrrev_i32_e32 v135, 31, v134
	v_readlane_b32 s3, v236, 15
	v_ashrrev_i32_e32 v133, 31, v132
	v_lshlrev_b64 v[136:137], 12, v[132:133]
	v_lshl_add_u64 v[134:135], v[134:135], 1, s[2:3]
	v_lshl_add_u64 v[136:137], v[134:135], 0, v[136:137]
	v_mov_b32_e32 v160, v116
	v_mov_b32_e32 v161, v112
	v_mov_b32_e32 v116, 0
	v_mov_b32_e32 v156, v162
	v_mov_b32_e32 v157, v163
	v_lshlrev_b32_e32 v158, 16, v156
	v_and_b32_e32 v159, 0xffff0000, v156
	v_pk_add_f32 v[158:159], v[160:161], v[158:159]
	v_lshlrev_b32_e32 v156, 16, v157
	v_and_b32_e32 v157, 0xffff0000, v157
	v_mov_b32_e32 v160, v124
	v_mov_b32_e32 v161, v120
	v_pk_add_f32 v[156:157], v[160:161], v[156:157]
	v_cvt_pk_bf16_f32 v160, v158, v159
	v_cvt_pk_bf16_f32 v161, v156, v157
	global_store_dwordx2 v[136:137], v[160:161], off sc1
	v_pk_mul_f32 v[136:137], v[158:159], v[158:159]
	v_pk_mul_f32 v[156:157], v[156:157], v[156:157]
	v_add_f32_e32 v112, v136, v137
	v_add_f32_e32 v112, v156, v112
	v_add_f32_e32 v112, v157, v112
	s_nop 1
	v_add_f32_dpp v112, v112, v112 row_ror:8 row_mask:0xf bank_mask:0xf bound_ctrl:1
	s_nop 1
	v_add_f32_dpp v112, v112, v112 row_ror:4 row_mask:0xf bank_mask:0xf bound_ctrl:1
	s_nop 1
	v_add_f32_dpp v112, v112, v112 row_ror:2 row_mask:0xf bank_mask:0xf bound_ctrl:1
	s_nop 1
	v_mov_b32_dpp v116, v112 row_ror:1 row_mask:0xf bank_mask:0xf
	s_and_saveexec_b64 s[2:3], s[10:11]
	s_cbranch_execz .LBB0_397
	v_add_f32_e32 v112, v112, v116
	v_mul_f32_e32 v112, 0x49800000, v112
	v_trunc_f32_e32 v112, v112
	v_mul_f32_e32 v116, 0x2f800000, v112
	v_floor_f32_e32 v116, v116
	v_fmac_f32_e32 v112, 0xcf800000, v116
	v_cvt_u32_f32_e32 v136, v112
	v_cvt_u32_f32_e32 v137, v116
	v_lshl_add_u64 v[156:157], v[132:133], 3, s[0:1]
	global_atomic_add_x2 v[156:157], v[136:137], off
.LBB0_397:
	s_or_b64 exec, exec, s[2:3]
	v_add_u32_e32 v136, 1, v132
	v_ashrrev_i32_e32 v137, 31, v136
	v_lshlrev_b64 v[156:157], 12, v[136:137]
	v_lshl_add_u64 v[156:157], v[134:135], 0, v[156:157]
	v_mov_b32_e32 v112, v117
	v_mov_b32_e32 v120, v125
	v_mov_b32_e32 v158, v164
	v_mov_b32_e32 v159, v165
	v_lshlrev_b32_e32 v160, 16, v158
	v_and_b32_e32 v161, 0xffff0000, v158
	v_pk_add_f32 v[112:113], v[112:113], v[160:161]
	v_lshlrev_b32_e32 v116, 16, v159
	v_and_b32_e32 v117, 0xffff0000, v159
	v_pk_add_f32 v[116:117], v[120:121], v[116:117]
	v_cvt_pk_bf16_f32 v120, v112, v113
	v_pk_mul_f32 v[112:113], v[112:113], v[112:113]
	v_cvt_pk_bf16_f32 v121, v116, v117
	v_pk_mul_f32 v[116:117], v[116:117], v[116:117]
	v_add_f32_e32 v112, v112, v113
	v_add_f32_e32 v112, v116, v112
	v_add_f32_e32 v112, v117, v112
	v_mov_b32_e32 v113, 0
	global_store_dwordx2 v[156:157], v[120:121], off sc1
	v_add_f32_dpp v112, v112, v112 row_ror:8 row_mask:0xf bank_mask:0xf bound_ctrl:1
	s_nop 1
	v_add_f32_dpp v112, v112, v112 row_ror:4 row_mask:0xf bank_mask:0xf bound_ctrl:1
	s_nop 1
	v_add_f32_dpp v112, v112, v112 row_ror:2 row_mask:0xf bank_mask:0xf bound_ctrl:1
	s_nop 1
	v_mov_b32_dpp v113, v112 row_ror:1 row_mask:0xf bank_mask:0xf
	s_and_saveexec_b64 s[2:3], s[10:11]
	s_cbranch_execz .LBB0_399
	v_add_f32_e32 v112, v112, v113
	v_mul_f32_e32 v112, 0x49800000, v112
	v_trunc_f32_e32 v112, v112
	v_mul_f32_e32 v113, 0x2f800000, v112
	v_floor_f32_e32 v113, v113
	v_fmac_f32_e32 v112, 0xcf800000, v113
	v_cvt_u32_f32_e32 v112, v112
	v_cvt_u32_f32_e32 v113, v113
	v_lshl_add_u64 v[116:117], v[136:137], 3, s[0:1]
	global_atomic_add_x2 v[116:117], v[112:113], off
.LBB0_399:
	s_or_b64 exec, exec, s[2:3]
	v_add_u32_e32 v112, 2, v132
	v_ashrrev_i32_e32 v113, 31, v112
	v_lshlrev_b64 v[116:117], 12, v[112:113]
	v_lshl_add_u64 v[116:117], v[134:135], 0, v[116:117]
	v_mov_b32_e32 v136, v118
	v_mov_b32_e32 v137, v114
	v_mov_b32_e32 v120, v166
	v_mov_b32_e32 v121, v167
	v_lshlrev_b32_e32 v124, 16, v120
	v_and_b32_e32 v125, 0xffff0000, v120
	v_pk_add_f32 v[124:125], v[136:137], v[124:125]
	v_lshlrev_b32_e32 v120, 16, v121
	v_and_b32_e32 v121, 0xffff0000, v121
	v_mov_b32_e32 v136, v126
	v_mov_b32_e32 v137, v122
	v_pk_add_f32 v[120:121], v[136:137], v[120:121]
	v_cvt_pk_bf16_f32 v136, v124, v125
	v_cvt_pk_bf16_f32 v137, v120, v121
	global_store_dwordx2 v[116:117], v[136:137], off sc1
	v_pk_mul_f32 v[116:117], v[124:125], v[124:125]
	v_pk_mul_f32 v[120:121], v[120:121], v[120:121]
	v_add_f32_e32 v114, v116, v117
	v_add_f32_e32 v114, v120, v114
	v_add_f32_e32 v114, v121, v114
	v_mov_b32_e32 v116, 0
	s_nop 0
	v_add_f32_dpp v114, v114, v114 row_ror:8 row_mask:0xf bank_mask:0xf bound_ctrl:1
	s_nop 1
	v_add_f32_dpp v114, v114, v114 row_ror:4 row_mask:0xf bank_mask:0xf bound_ctrl:1
	s_nop 1
	v_add_f32_dpp v114, v114, v114 row_ror:2 row_mask:0xf bank_mask:0xf bound_ctrl:1
	s_nop 1
	v_mov_b32_dpp v116, v114 row_ror:1 row_mask:0xf bank_mask:0xf
	s_and_saveexec_b64 s[2:3], s[10:11]
	s_cbranch_execz .LBB0_401
	v_add_f32_e32 v114, v114, v116
	v_mul_f32_e32 v114, 0x49800000, v114
	v_trunc_f32_e32 v114, v114
	v_mul_f32_e32 v116, 0x2f800000, v114
	v_floor_f32_e32 v117, v116
	v_fmac_f32_e32 v114, 0xcf800000, v117
	v_cvt_u32_f32_e32 v116, v114
	v_cvt_u32_f32_e32 v117, v117
	v_lshl_add_u64 v[112:113], v[112:113], 3, s[0:1]
	global_atomic_add_x2 v[112:113], v[116:117], off
; __device__ __forceinline__ float row16_sum(float v) { DPP_ADD(v, 0x128); DPP_ADD(v, 0x124); DPP_ADD(v, 0x122); DPP_ADD(v, 0x121); return v; }
; template <int EPI, int N, int K>
; __device__ __forceinline__ void gemm_phase(const bf16_t* __restrict__ A, const bf16_t* __restrict__ Bt, const EpiArgs ea) {
;     ...
;           for (int j = 0; j < 4; ++j) {
;             const int row = brow + ai * 128 + wr * 64 + m * 16 + fq * 4 + j;
;             const u32x2 x2 = *(const u32x2*)(ea.outb + (size_t)row * DM + c0);
;             float4 xn;
;             xn.x = __builtin_bit_cast(float, x2[0] << 16) + acc[ai][0][m][0][j]; xn.y = __builtin_bit_cast(float, x2[0] & 0xffff0000u) + acc[ai][0][m][1][j];
;             xn.z = __builtin_bit_cast(float, x2[1] << 16) + acc[ai][1][m][0][j]; xn.w = __builtin_bit_cast(float, x2[1] & 0xffff0000u) + acc[ai][1][m][1][j];
;             u32x2 o = {pk2(xn.x, xn.y), pk2(xn.z, xn.w)};
;             st_wt(ea.outb + (size_t)row * DM + c0, o);
;             float ss = xn.x * xn.x + xn.y * xn.y + xn.z * xn.z + xn.w * xn.w;
;             ss = row16_sum(ss);
;             if (fr == 0) __hip_atomic_fetch_add(ea.rowsq_out + row, (rsq_t)(ss * RSQ_SCALE), __ATOMIC_RELAXED, __HIP_MEMORY_SCOPE_AGENT);
.LBB0_401:
	s_or_b64 exec, exec, s[2:3]
	v_add_u32_e32 v112, 3, v132
	v_ashrrev_i32_e32 v113, 31, v112
	v_lshlrev_b64 v[116:117], 12, v[112:113]
	v_lshl_add_u64 v[116:117], v[134:135], 0, v[116:117]
	v_mov_b32_e32 v114, v119
	v_mov_b32_e32 v122, v127
	v_mov_b32_e32 v120, v168
	v_mov_b32_e32 v121, v169
	v_lshlrev_b32_e32 v118, 16, v120
	v_and_b32_e32 v119, 0xffff0000, v120
	v_lshlrev_b32_e32 v120, 16, v121
	v_and_b32_e32 v121, 0xffff0000, v121
	v_pk_add_f32 v[114:115], v[114:115], v[118:119]
	v_pk_add_f32 v[118:119], v[122:123], v[120:121]
	v_cvt_pk_bf16_f32 v120, v114, v115
	v_pk_mul_f32 v[114:115], v[114:115], v[114:115]
	v_cvt_pk_bf16_f32 v121, v118, v119
	v_pk_mul_f32 v[118:119], v[118:119], v[118:119]
	v_add_f32_e32 v114, v114, v115
	v_add_f32_e32 v114, v118, v114
	v_add_f32_e32 v114, v119, v114
	v_mov_b32_e32 v115, 0
	global_store_dwordx2 v[116:117], v[120:121], off sc1
	v_add_f32_dpp v114, v114, v114 row_ror:8 row_mask:0xf bank_mask:0xf bound_ctrl:1
	s_nop 1
	v_add_f32_dpp v114, v114, v114 row_ror:4 row_mask:0xf bank_mask:0xf bound_ctrl:1
	s_nop 1
	v_add_f32_dpp v114, v114, v114 row_ror:2 row_mask:0xf bank_mask:0xf bound_ctrl:1
	s_nop 1
	v_mov_b32_dpp v115, v114 row_ror:1 row_mask:0xf bank_mask:0xf
	s_and_saveexec_b64 s[2:3], s[10:11]
	s_cbranch_execz .LBB0_403
	v_add_f32_e32 v114, v114, v115
	v_mul_f32_e32 v114, 0x49800000, v114
	v_trunc_f32_e32 v114, v114
	v_mul_f32_e32 v115, 0x2f800000, v114
	v_floor_f32_e32 v115, v115
	v_fmac_f32_e32 v114, 0xcf800000, v115
	v_cvt_u32_f32_e32 v114, v114
	v_cvt_u32_f32_e32 v115, v115
	v_lshl_add_u64 v[112:113], v[112:113], 3, s[0:1]
	global_atomic_add_x2 v[112:113], v[114:115], off
.LBB0_403:
	s_or_b64 exec, exec, s[2:3]
	v_add_u32_e32 v112, 16, v132
	v_ashrrev_i32_e32 v113, 31, v112
	v_lshlrev_b64 v[114:115], 12, v[112:113]
	v_lshl_add_u64 v[114:115], v[134:135], 0, v[114:115]
	v_mov_b32_e32 v120, v100
	v_mov_b32_e32 v121, v96
	v_mov_b32_e32 v100, 0
	v_mov_b32_e32 v116, v170
	v_mov_b32_e32 v117, v171
	v_lshlrev_b32_e32 v118, 16, v116
	v_and_b32_e32 v119, 0xffff0000, v116
	v_pk_add_f32 v[118:119], v[120:121], v[118:119]
	v_lshlrev_b32_e32 v116, 16, v117
	v_and_b32_e32 v117, 0xffff0000, v117
	v_mov_b32_e32 v120, v108
	v_mov_b32_e32 v121, v104
	v_pk_add_f32 v[116:117], v[120:121], v[116:117]
	v_cvt_pk_bf16_f32 v120, v118, v119
	v_cvt_pk_bf16_f32 v121, v116, v117
	global_store_dwordx2 v[114:115], v[120:121], off sc1
	v_pk_mul_f32 v[114:115], v[118:119], v[118:119]
	v_pk_mul_f32 v[116:117], v[116:117], v[116:117]
	v_add_f32_e32 v96, v114, v115
	v_add_f32_e32 v96, v116, v96
	v_add_f32_e32 v96, v117, v96
	s_nop 1
	v_add_f32_dpp v96, v96, v96 row_ror:8 row_mask:0xf bank_mask:0xf bound_ctrl:1
	s_nop 1
	v_add_f32_dpp v96, v96, v96 row_ror:4 row_mask:0xf bank_mask:0xf bound_ctrl:1
	s_nop 1
	v_add_f32_dpp v96, v96, v96 row_ror:2 row_mask:0xf bank_mask:0xf bound_ctrl:1
	s_nop 1
	v_mov_b32_dpp v100, v96 row_ror:1 row_mask:0xf bank_mask:0xf
	s_and_saveexec_b64 s[2:3], s[10:11]
	s_cbranch_execz .LBB0_405
	v_add_f32_e32 v96, v96, v100
	v_mul_f32_e32 v96, 0x49800000, v96
	v_trunc_f32_e32 v96, v96
	v_mul_f32_e32 v100, 0x2f800000, v96
	v_floor_f32_e32 v100, v100
	v_fmac_f32_e32 v96, 0xcf800000, v100
	v_cvt_u32_f32_e32 v114, v96
	v_cvt_u32_f32_e32 v115, v100
	v_lshl_add_u64 v[112:113], v[112:113], 3, s[0:1]
	global_atomic_add_x2 v[112:113], v[114:115], off
.LBB0_405:
	s_or_b64 exec, exec, s[2:3]
	v_add_u32_e32 v112, 17, v132
	v_ashrrev_i32_e32 v113, 31, v112
	v_lshlrev_b64 v[114:115], 12, v[112:113]
	v_lshl_add_u64 v[114:115], v[134:135], 0, v[114:115]
	v_mov_b32_e32 v96, v101
	v_mov_b32_e32 v104, v109
	v_mov_b32_e32 v116, v172
	v_mov_b32_e32 v117, v173
	v_lshlrev_b32_e32 v118, 16, v116
	v_and_b32_e32 v119, 0xffff0000, v116
	v_pk_add_f32 v[96:97], v[96:97], v[118:119]
	v_lshlrev_b32_e32 v100, 16, v117
	v_and_b32_e32 v101, 0xffff0000, v117
	v_pk_add_f32 v[100:101], v[104:105], v[100:101]
	v_cvt_pk_bf16_f32 v104, v96, v97
	v_pk_mul_f32 v[96:97], v[96:97], v[96:97]
	v_cvt_pk_bf16_f32 v105, v100, v101
	v_pk_mul_f32 v[100:101], v[100:101], v[100:101]
	v_add_f32_e32 v96, v96, v97
	v_add_f32_e32 v96, v100, v96
	v_add_f32_e32 v96, v101, v96
	v_mov_b32_e32 v97, 0
	global_store_dwordx2 v[114:115], v[104:105], off sc1
	v_add_f32_dpp v96, v96, v96 row_ror:8 row_mask:0xf bank_mask:0xf bound_ctrl:1
	s_nop 1
	v_add_f32_dpp v96, v96, v96 row_ror:4 row_mask:0xf bank_mask:0xf bound_ctrl:1
	s_nop 1
	v_add_f32_dpp v96, v96, v96 row_ror:2 row_mask:0xf bank_mask:0xf bound_ctrl:1
	s_nop 1
	v_mov_b32_dpp v97, v96 row_ror:1 row_mask:0xf bank_mask:0xf
	s_and_saveexec_b64 s[2:3], s[10:11]
	s_cbranch_execz .LBB0_407
	v_add_f32_e32 v96, v96, v97
	v_mul_f32_e32 v96, 0x49800000, v96
	v_trunc_f32_e32 v96, v96
	v_mul_f32_e32 v97, 0x2f800000, v96
	v_floor_f32_e32 v97, v97
	v_fmac_f32_e32 v96, 0xcf800000, v97
	v_cvt_u32_f32_e32 v96, v96
	v_cvt_u32_f32_e32 v97, v97
	v_lshl_add_u64 v[100:101], v[112:113], 3, s[0:1]
	global_atomic_add_x2 v[100:101], v[96:97], off
; __device__ __forceinline__ float row16_sum(float v) { DPP_ADD(v, 0x128); DPP_ADD(v, 0x124); DPP_ADD(v, 0x122); DPP_ADD(v, 0x121); return v; }
; template <int EPI, int N, int K>
; __device__ __forceinline__ void gemm_phase(const bf16_t* __restrict__ A, const bf16_t* __restrict__ Bt, const EpiArgs ea) {
;     ...
;           for (int j = 0; j < 4; ++j) {
;             const int row = brow + ai * 128 + wr * 64 + m * 16 + fq * 4 + j;
;             const u32x2 x2 = *(const u32x2*)(ea.outb + (size_t)row * DM + c0);
;             float4 xn;
;             xn.x = __builtin_bit_cast(float, x2[0] << 16) + acc[ai][0][m][0][j]; xn.y = __builtin_bit_cast(float, x2[0] & 0xffff0000u) + acc[ai][0][m][1][j];
;             xn.z = __builtin_bit_cast(float, x2[1] << 16) + acc[ai][1][m][0][j]; xn.w = __builtin_bit_cast(float, x2[1] & 0xffff0000u) + acc[ai][1][m][1][j];
;             u32x2 o = {pk2(xn.x, xn.y), pk2(xn.z, xn.w)};
;             st_wt(ea.outb + (size_t)row * DM + c0, o);
;             float ss = xn.x * xn.x + xn.y * xn.y + xn.z * xn.z + xn.w * xn.w;
;             ss = row16_sum(ss);
;             if (fr == 0) __hip_atomic_fetch_add(ea.rowsq_out + row, (rsq_t)(ss * RSQ_SCALE), __ATOMIC_RELAXED, __HIP_MEMORY_SCOPE_AGENT);
.LBB0_407:
	s_or_b64 exec, exec, s[2:3]
	v_add_u32_e32 v96, 18, v132
	v_ashrrev_i32_e32 v97, 31, v96
	v_lshlrev_b64 v[100:101], 12, v[96:97]
	v_lshl_add_u64 v[100:101], v[134:135], 0, v[100:101]
	v_mov_b32_e32 v112, v102
	v_mov_b32_e32 v113, v98
	v_mov_b32_e32 v104, v174
	v_mov_b32_e32 v105, v175
	v_lshlrev_b32_e32 v108, 16, v104
	v_and_b32_e32 v109, 0xffff0000, v104
	v_pk_add_f32 v[108:109], v[112:113], v[108:109]
	v_lshlrev_b32_e32 v104, 16, v105
	v_and_b32_e32 v105, 0xffff0000, v105
	v_mov_b32_e32 v112, v110
	v_mov_b32_e32 v113, v106
	v_pk_add_f32 v[104:105], v[112:113], v[104:105]
	v_cvt_pk_bf16_f32 v112, v108, v109
	v_cvt_pk_bf16_f32 v113, v104, v105
	global_store_dwordx2 v[100:101], v[112:113], off sc1
	v_pk_mul_f32 v[100:101], v[108:109], v[108:109]
	v_pk_mul_f32 v[104:105], v[104:105], v[104:105]
	v_add_f32_e32 v98, v100, v101
	v_add_f32_e32 v98, v104, v98
	v_add_f32_e32 v98, v105, v98
	v_mov_b32_e32 v100, 0
	s_nop 0
	v_add_f32_dpp v98, v98, v98 row_ror:8 row_mask:0xf bank_mask:0xf bound_ctrl:1
	s_nop 1
	v_add_f32_dpp v98, v98, v98 row_ror:4 row_mask:0xf bank_mask:0xf bound_ctrl:1
	s_nop 1
	v_add_f32_dpp v98, v98, v98 row_ror:2 row_mask:0xf bank_mask:0xf bound_ctrl:1
	s_nop 1
	v_mov_b32_dpp v100, v98 row_ror:1 row_mask:0xf bank_mask:0xf
	s_and_saveexec_b64 s[2:3], s[10:11]
	s_cbranch_execz .LBB0_409
	v_add_f32_e32 v98, v98, v100
	v_mul_f32_e32 v98, 0x49800000, v98
	v_trunc_f32_e32 v98, v98
	v_mul_f32_e32 v100, 0x2f800000, v98
	v_floor_f32_e32 v101, v100
	v_fmac_f32_e32 v98, 0xcf800000, v101
	v_cvt_u32_f32_e32 v100, v98
	v_cvt_u32_f32_e32 v101, v101
	v_lshl_add_u64 v[96:97], v[96:97], 3, s[0:1]
	global_atomic_add_x2 v[96:97], v[100:101], off
.LBB0_409:
	s_or_b64 exec, exec, s[2:3]
	v_add_u32_e32 v96, 19, v132
	v_ashrrev_i32_e32 v97, 31, v96
	v_lshlrev_b64 v[100:101], 12, v[96:97]
	v_lshl_add_u64 v[100:101], v[134:135], 0, v[100:101]
	v_mov_b32_e32 v98, v103
	v_mov_b32_e32 v106, v111
	v_mov_b32_e32 v104, v176
	v_mov_b32_e32 v105, v177
	v_lshlrev_b32_e32 v102, 16, v104
	v_and_b32_e32 v103, 0xffff0000, v104
	v_lshlrev_b32_e32 v104, 16, v105
	v_and_b32_e32 v105, 0xffff0000, v105
	v_pk_add_f32 v[98:99], v[98:99], v[102:103]
	v_pk_add_f32 v[102:103], v[106:107], v[104:105]
	v_cvt_pk_bf16_f32 v104, v98, v99
	v_pk_mul_f32 v[98:99], v[98:99], v[98:99]
	v_cvt_pk_bf16_f32 v105, v102, v103
	v_pk_mul_f32 v[102:103], v[102:103], v[102:103]
	v_add_f32_e32 v98, v98, v99
	v_add_f32_e32 v98, v102, v98
	v_add_f32_e32 v98, v103, v98
	v_mov_b32_e32 v99, 0
	global_store_dwordx2 v[100:101], v[104:105], off sc1
	v_add_f32_dpp v98, v98, v98 row_ror:8 row_mask:0xf bank_mask:0xf bound_ctrl:1
	s_nop 1
	v_add_f32_dpp v98, v98, v98 row_ror:4 row_mask:0xf bank_mask:0xf bound_ctrl:1
	s_nop 1
	v_add_f32_dpp v98, v98, v98 row_ror:2 row_mask:0xf bank_mask:0xf bound_ctrl:1
	s_nop 1
	v_mov_b32_dpp v99, v98 row_ror:1 row_mask:0xf bank_mask:0xf
	s_and_saveexec_b64 s[2:3], s[10:11]
	s_cbranch_execz .LBB0_411
	v_add_f32_e32 v98, v98, v99
	v_mul_f32_e32 v98, 0x49800000, v98
	v_trunc_f32_e32 v98, v98
	v_mul_f32_e32 v99, 0x2f800000, v98
	v_floor_f32_e32 v99, v99
	v_fmac_f32_e32 v98, 0xcf800000, v99
	v_cvt_u32_f32_e32 v98, v98
	v_cvt_u32_f32_e32 v99, v99
	v_lshl_add_u64 v[96:97], v[96:97], 3, s[0:1]
	global_atomic_add_x2 v[96:97], v[98:99], off
.LBB0_411:
	s_or_b64 exec, exec, s[2:3]
	v_add_u32_e32 v96, 32, v132
	v_ashrrev_i32_e32 v97, 31, v96
	v_lshlrev_b64 v[98:99], 12, v[96:97]
	v_lshl_add_u64 v[98:99], v[134:135], 0, v[98:99]
	v_mov_b32_e32 v104, v84
	v_mov_b32_e32 v105, v80
	v_mov_b32_e32 v84, 0
	v_mov_b32_e32 v100, v178
	v_mov_b32_e32 v101, v179
	v_lshlrev_b32_e32 v102, 16, v100
	v_and_b32_e32 v103, 0xffff0000, v100
	v_pk_add_f32 v[102:103], v[104:105], v[102:103]
	v_lshlrev_b32_e32 v100, 16, v101
	v_and_b32_e32 v101, 0xffff0000, v101
	v_mov_b32_e32 v104, v92
	v_mov_b32_e32 v105, v88
	v_pk_add_f32 v[100:101], v[104:105], v[100:101]
	v_cvt_pk_bf16_f32 v104, v102, v103
	v_cvt_pk_bf16_f32 v105, v100, v101
	global_store_dwordx2 v[98:99], v[104:105], off sc1
	v_pk_mul_f32 v[98:99], v[102:103], v[102:103]
	v_pk_mul_f32 v[100:101], v[100:101], v[100:101]
	v_add_f32_e32 v80, v98, v99
	v_add_f32_e32 v80, v100, v80
	v_add_f32_e32 v80, v101, v80
	s_nop 1
	v_add_f32_dpp v80, v80, v80 row_ror:8 row_mask:0xf bank_mask:0xf bound_ctrl:1
	s_nop 1
	v_add_f32_dpp v80, v80, v80 row_ror:4 row_mask:0xf bank_mask:0xf bound_ctrl:1
	s_nop 1
	v_add_f32_dpp v80, v80, v80 row_ror:2 row_mask:0xf bank_mask:0xf bound_ctrl:1
	s_nop 1
	v_mov_b32_dpp v84, v80 row_ror:1 row_mask:0xf bank_mask:0xf
	s_and_saveexec_b64 s[2:3], s[10:11]
	s_cbranch_execz .LBB0_413
	v_add_f32_e32 v80, v80, v84
	v_mul_f32_e32 v80, 0x49800000, v80
	v_trunc_f32_e32 v80, v80
	v_mul_f32_e32 v84, 0x2f800000, v80
	v_floor_f32_e32 v84, v84
	v_fmac_f32_e32 v80, 0xcf800000, v84
	v_cvt_u32_f32_e32 v98, v80
	v_cvt_u32_f32_e32 v99, v84
	v_lshl_add_u64 v[96:97], v[96:97], 3, s[0:1]
	global_atomic_add_x2 v[96:97], v[98:99], off
; __device__ __forceinline__ float row16_sum(float v) { DPP_ADD(v, 0x128); DPP_ADD(v, 0x124); DPP_ADD(v, 0x122); DPP_ADD(v, 0x121); return v; }
; template <int EPI, int N, int K>
; __device__ __forceinline__ void gemm_phase(const bf16_t* __restrict__ A, const bf16_t* __restrict__ Bt, const EpiArgs ea) {
;     ...
;           for (int j = 0; j < 4; ++j) {
;             const int row = brow + ai * 128 + wr * 64 + m * 16 + fq * 4 + j;
;             const u32x2 x2 = *(const u32x2*)(ea.outb + (size_t)row * DM + c0);
;             float4 xn;
;             xn.x = __builtin_bit_cast(float, x2[0] << 16) + acc[ai][0][m][0][j]; xn.y = __builtin_bit_cast(float, x2[0] & 0xffff0000u) + acc[ai][0][m][1][j];
;             xn.z = __builtin_bit_cast(float, x2[1] << 16) + acc[ai][1][m][0][j]; xn.w = __builtin_bit_cast(float, x2[1] & 0xffff0000u) + acc[ai][1][m][1][j];
;             u32x2 o = {pk2(xn.x, xn.y), pk2(xn.z, xn.w)};
;             st_wt(ea.outb + (size_t)row * DM + c0, o);
;             float ss = xn.x * xn.x + xn.y * xn.y + xn.z * xn.z + xn.w * xn.w;
;             ss = row16_sum(ss);
;             if (fr == 0) __hip_atomic_fetch_add(ea.rowsq_out + row, (rsq_t)(ss * RSQ_SCALE), __ATOMIC_RELAXED, __HIP_MEMORY_SCOPE_AGENT);
.LBB0_413:
	s_or_b64 exec, exec, s[2:3]
	v_add_u32_e32 v96, 33, v132
	v_ashrrev_i32_e32 v97, 31, v96
	v_lshlrev_b64 v[98:99], 12, v[96:97]
	v_lshl_add_u64 v[98:99], v[134:135], 0, v[98:99]
	v_mov_b32_e32 v80, v85
	v_mov_b32_e32 v88, v93
	v_mov_b32_e32 v100, v180
	v_mov_b32_e32 v101, v181
	v_lshlrev_b32_e32 v102, 16, v100
	v_and_b32_e32 v103, 0xffff0000, v100
	v_pk_add_f32 v[80:81], v[80:81], v[102:103]
	v_lshlrev_b32_e32 v84, 16, v101
	v_and_b32_e32 v85, 0xffff0000, v101
	v_pk_add_f32 v[84:85], v[88:89], v[84:85]
	v_cvt_pk_bf16_f32 v88, v80, v81
	v_pk_mul_f32 v[80:81], v[80:81], v[80:81]
	v_cvt_pk_bf16_f32 v89, v84, v85
	v_pk_mul_f32 v[84:85], v[84:85], v[84:85]
	v_add_f32_e32 v80, v80, v81
	v_add_f32_e32 v80, v84, v80
	v_add_f32_e32 v80, v85, v80
	v_mov_b32_e32 v81, 0
	global_store_dwordx2 v[98:99], v[88:89], off sc1
	v_add_f32_dpp v80, v80, v80 row_ror:8 row_mask:0xf bank_mask:0xf bound_ctrl:1
	s_nop 1
	v_add_f32_dpp v80, v80, v80 row_ror:4 row_mask:0xf bank_mask:0xf bound_ctrl:1
	s_nop 1
	v_add_f32_dpp v80, v80, v80 row_ror:2 row_mask:0xf bank_mask:0xf bound_ctrl:1
	s_nop 1
	v_mov_b32_dpp v81, v80 row_ror:1 row_mask:0xf bank_mask:0xf
	s_and_saveexec_b64 s[2:3], s[10:11]
	s_cbranch_execz .LBB0_415
	v_add_f32_e32 v80, v80, v81
	v_mul_f32_e32 v80, 0x49800000, v80
	v_trunc_f32_e32 v80, v80
	v_mul_f32_e32 v81, 0x2f800000, v80
	v_floor_f32_e32 v81, v81
	v_fmac_f32_e32 v80, 0xcf800000, v81
	v_cvt_u32_f32_e32 v80, v80
	v_cvt_u32_f32_e32 v81, v81
	v_lshl_add_u64 v[84:85], v[96:97], 3, s[0:1]
	global_atomic_add_x2 v[84:85], v[80:81], off
.LBB0_415:
	s_or_b64 exec, exec, s[2:3]
	v_add_u32_e32 v80, 34, v132
	v_ashrrev_i32_e32 v81, 31, v80
	v_lshlrev_b64 v[84:85], 12, v[80:81]
	v_lshl_add_u64 v[84:85], v[134:135], 0, v[84:85]
	v_mov_b32_e32 v96, v86
	v_mov_b32_e32 v97, v82
	v_mov_b32_e32 v88, v182
	v_mov_b32_e32 v89, v183
	v_lshlrev_b32_e32 v92, 16, v88
	v_and_b32_e32 v93, 0xffff0000, v88
	v_pk_add_f32 v[92:93], v[96:97], v[92:93]
	v_lshlrev_b32_e32 v88, 16, v89
	v_and_b32_e32 v89, 0xffff0000, v89
	v_mov_b32_e32 v96, v94
	v_mov_b32_e32 v97, v90
	v_pk_add_f32 v[88:89], v[96:97], v[88:89]
	v_cvt_pk_bf16_f32 v96, v92, v93
	v_cvt_pk_bf16_f32 v97, v88, v89
	global_store_dwordx2 v[84:85], v[96:97], off sc1
	v_pk_mul_f32 v[84:85], v[92:93], v[92:93]
	v_pk_mul_f32 v[88:89], v[88:89], v[88:89]
	v_add_f32_e32 v82, v84, v85
	v_add_f32_e32 v82, v88, v82
	v_add_f32_e32 v82, v89, v82
	v_mov_b32_e32 v84, 0
	s_nop 0
	v_add_f32_dpp v82, v82, v82 row_ror:8 row_mask:0xf bank_mask:0xf bound_ctrl:1
	s_nop 1
	v_add_f32_dpp v82, v82, v82 row_ror:4 row_mask:0xf bank_mask:0xf bound_ctrl:1
	s_nop 1
	v_add_f32_dpp v82, v82, v82 row_ror:2 row_mask:0xf bank_mask:0xf bound_ctrl:1
	s_nop 1
	v_mov_b32_dpp v84, v82 row_ror:1 row_mask:0xf bank_mask:0xf
	s_and_saveexec_b64 s[2:3], s[10:11]
	s_cbranch_execz .LBB0_417
	v_add_f32_e32 v82, v82, v84
	v_mul_f32_e32 v82, 0x49800000, v82
	v_trunc_f32_e32 v82, v82
	v_mul_f32_e32 v84, 0x2f800000, v82
	v_floor_f32_e32 v85, v84
	v_fmac_f32_e32 v82, 0xcf800000, v85
	v_cvt_u32_f32_e32 v84, v82
	v_cvt_u32_f32_e32 v85, v85
	v_lshl_add_u64 v[80:81], v[80:81], 3, s[0:1]
	global_atomic_add_x2 v[80:81], v[84:85], off
.LBB0_417:
	s_or_b64 exec, exec, s[2:3]
	v_add_u32_e32 v80, 35, v132
	v_ashrrev_i32_e32 v81, 31, v80
	v_lshlrev_b64 v[84:85], 12, v[80:81]
	v_lshl_add_u64 v[84:85], v[134:135], 0, v[84:85]
	v_mov_b32_e32 v82, v87
	v_mov_b32_e32 v90, v95
	v_mov_b32_e32 v88, v184
	v_mov_b32_e32 v89, v185
	v_lshlrev_b32_e32 v86, 16, v88
	v_and_b32_e32 v87, 0xffff0000, v88
	v_lshlrev_b32_e32 v88, 16, v89
	v_and_b32_e32 v89, 0xffff0000, v89
	v_pk_add_f32 v[82:83], v[82:83], v[86:87]
	v_pk_add_f32 v[86:87], v[90:91], v[88:89]
	v_cvt_pk_bf16_f32 v88, v82, v83
	v_pk_mul_f32 v[82:83], v[82:83], v[82:83]
	v_cvt_pk_bf16_f32 v89, v86, v87
	v_pk_mul_f32 v[86:87], v[86:87], v[86:87]
	v_add_f32_e32 v82, v82, v83
	v_add_f32_e32 v82, v86, v82
	v_add_f32_e32 v82, v87, v82
	v_mov_b32_e32 v83, 0
	global_store_dwordx2 v[84:85], v[88:89], off sc1
	v_add_f32_dpp v82, v82, v82 row_ror:8 row_mask:0xf bank_mask:0xf bound_ctrl:1
	s_nop 1
	v_add_f32_dpp v82, v82, v82 row_ror:4 row_mask:0xf bank_mask:0xf bound_ctrl:1
	s_nop 1
	v_add_f32_dpp v82, v82, v82 row_ror:2 row_mask:0xf bank_mask:0xf bound_ctrl:1
	s_nop 1
	v_mov_b32_dpp v83, v82 row_ror:1 row_mask:0xf bank_mask:0xf
	s_and_saveexec_b64 s[2:3], s[10:11]
	s_cbranch_execz .LBB0_419
	v_add_f32_e32 v82, v82, v83
	v_mul_f32_e32 v82, 0x49800000, v82
	v_trunc_f32_e32 v82, v82
	v_mul_f32_e32 v83, 0x2f800000, v82
	v_floor_f32_e32 v83, v83
	v_fmac_f32_e32 v82, 0xcf800000, v83
	v_cvt_u32_f32_e32 v82, v82
	v_cvt_u32_f32_e32 v83, v83
	v_lshl_add_u64 v[80:81], v[80:81], 3, s[0:1]
	global_atomic_add_x2 v[80:81], v[82:83], off
.LBB0_419:
	s_or_b64 exec, exec, s[2:3]
	v_add_u32_e32 v80, 48, v132
	v_ashrrev_i32_e32 v81, 31, v80
	v_lshlrev_b64 v[82:83], 12, v[80:81]
	v_lshl_add_u64 v[82:83], v[134:135], 0, v[82:83]
	v_mov_b32_e32 v88, v68
	v_mov_b32_e32 v89, v64
	v_mov_b32_e32 v68, 0
	v_mov_b32_e32 v84, v186
	v_mov_b32_e32 v85, v187
	v_lshlrev_b32_e32 v86, 16, v84
	v_and_b32_e32 v87, 0xffff0000, v84
	v_pk_add_f32 v[86:87], v[88:89], v[86:87]
	v_lshlrev_b32_e32 v84, 16, v85
	v_and_b32_e32 v85, 0xffff0000, v85
	v_mov_b32_e32 v88, v76
	v_mov_b32_e32 v89, v72
	v_pk_add_f32 v[84:85], v[88:89], v[84:85]
	v_cvt_pk_bf16_f32 v88, v86, v87
	v_cvt_pk_bf16_f32 v89, v84, v85
	global_store_dwordx2 v[82:83], v[88:89], off sc1
	v_pk_mul_f32 v[82:83], v[86:87], v[86:87]
	v_pk_mul_f32 v[84:85], v[84:85], v[84:85]
	v_add_f32_e32 v64, v82, v83
	v_add_f32_e32 v64, v84, v64
	v_add_f32_e32 v64, v85, v64
	s_nop 1
	v_add_f32_dpp v64, v64, v64 row_ror:8 row_mask:0xf bank_mask:0xf bound_ctrl:1
	s_nop 1
	v_add_f32_dpp v64, v64, v64 row_ror:4 row_mask:0xf bank_mask:0xf bound_ctrl:1
	s_nop 1
	v_add_f32_dpp v64, v64, v64 row_ror:2 row_mask:0xf bank_mask:0xf bound_ctrl:1
	s_nop 1
	v_mov_b32_dpp v68, v64 row_ror:1 row_mask:0xf bank_mask:0xf
	s_and_saveexec_b64 s[2:3], s[10:11]
	s_cbranch_execz .LBB0_421
	v_add_f32_e32 v64, v64, v68
	v_mul_f32_e32 v64, 0x49800000, v64
	v_trunc_f32_e32 v64, v64
	v_mul_f32_e32 v68, 0x2f800000, v64
	v_floor_f32_e32 v68, v68
	v_fmac_f32_e32 v64, 0xcf800000, v68
	v_cvt_u32_f32_e32 v82, v64
	v_cvt_u32_f32_e32 v83, v68
	v_lshl_add_u64 v[80:81], v[80:81], 3, s[0:1]
	global_atomic_add_x2 v[80:81], v[82:83], off
; __device__ __forceinline__ float row16_sum(float v) { DPP_ADD(v, 0x128); DPP_ADD(v, 0x124); DPP_ADD(v, 0x122); DPP_ADD(v, 0x121); return v; }
; template <int EPI, int N, int K>
; __device__ __forceinline__ void gemm_phase(const bf16_t* __restrict__ A, const bf16_t* __restrict__ Bt, const EpiArgs ea) {
;     ...
;           for (int j = 0; j < 4; ++j) {
;             const int row = brow + ai * 128 + wr * 64 + m * 16 + fq * 4 + j;
;             const u32x2 x2 = *(const u32x2*)(ea.outb + (size_t)row * DM + c0);
;             float4 xn;
;             xn.x = __builtin_bit_cast(float, x2[0] << 16) + acc[ai][0][m][0][j]; xn.y = __builtin_bit_cast(float, x2[0] & 0xffff0000u) + acc[ai][0][m][1][j];
;             xn.z = __builtin_bit_cast(float, x2[1] << 16) + acc[ai][1][m][0][j]; xn.w = __builtin_bit_cast(float, x2[1] & 0xffff0000u) + acc[ai][1][m][1][j];
;             u32x2 o = {pk2(xn.x, xn.y), pk2(xn.z, xn.w)};
;             st_wt(ea.outb + (size_t)row * DM + c0, o);
;             float ss = xn.x * xn.x + xn.y * xn.y + xn.z * xn.z + xn.w * xn.w;
;             ss = row16_sum(ss);
;             if (fr == 0) __hip_atomic_fetch_add(ea.rowsq_out + row, (rsq_t)(ss * RSQ_SCALE), __ATOMIC_RELAXED, __HIP_MEMORY_SCOPE_AGENT);
.LBB0_421:
	s_or_b64 exec, exec, s[2:3]
	v_add_u32_e32 v80, 49, v132
	v_ashrrev_i32_e32 v81, 31, v80
	v_lshlrev_b64 v[82:83], 12, v[80:81]
	v_lshl_add_u64 v[82:83], v[134:135], 0, v[82:83]
	v_mov_b32_e32 v64, v69
	v_mov_b32_e32 v72, v77
	v_mov_b32_e32 v84, v188
	v_mov_b32_e32 v85, v189
	v_lshlrev_b32_e32 v86, 16, v84
	v_and_b32_e32 v87, 0xffff0000, v84
	v_pk_add_f32 v[64:65], v[64:65], v[86:87]
	v_lshlrev_b32_e32 v68, 16, v85
	v_and_b32_e32 v69, 0xffff0000, v85
	v_pk_add_f32 v[68:69], v[72:73], v[68:69]
	v_cvt_pk_bf16_f32 v72, v64, v65
	v_pk_mul_f32 v[64:65], v[64:65], v[64:65]
	v_cvt_pk_bf16_f32 v73, v68, v69
	v_pk_mul_f32 v[68:69], v[68:69], v[68:69]
	v_add_f32_e32 v64, v64, v65
	v_add_f32_e32 v64, v68, v64
	v_add_f32_e32 v64, v69, v64
	v_mov_b32_e32 v65, 0
	global_store_dwordx2 v[82:83], v[72:73], off sc1
	v_add_f32_dpp v64, v64, v64 row_ror:8 row_mask:0xf bank_mask:0xf bound_ctrl:1
	s_nop 1
	v_add_f32_dpp v64, v64, v64 row_ror:4 row_mask:0xf bank_mask:0xf bound_ctrl:1
	s_nop 1
	v_add_f32_dpp v64, v64, v64 row_ror:2 row_mask:0xf bank_mask:0xf bound_ctrl:1
	s_nop 1
	v_mov_b32_dpp v65, v64 row_ror:1 row_mask:0xf bank_mask:0xf
	s_and_saveexec_b64 s[2:3], s[10:11]
	s_cbranch_execz .LBB0_423
	v_add_f32_e32 v64, v64, v65
	v_mul_f32_e32 v64, 0x49800000, v64
	v_trunc_f32_e32 v64, v64
	v_mul_f32_e32 v65, 0x2f800000, v64
	v_floor_f32_e32 v65, v65
	v_fmac_f32_e32 v64, 0xcf800000, v65
	v_cvt_u32_f32_e32 v64, v64
	v_cvt_u32_f32_e32 v65, v65
	v_lshl_add_u64 v[68:69], v[80:81], 3, s[0:1]
	global_atomic_add_x2 v[68:69], v[64:65], off
.LBB0_423:
	s_or_b64 exec, exec, s[2:3]
	v_add_u32_e32 v64, 50, v132
	v_ashrrev_i32_e32 v65, 31, v64
	v_lshlrev_b64 v[68:69], 12, v[64:65]
	v_lshl_add_u64 v[68:69], v[134:135], 0, v[68:69]
	v_mov_b32_e32 v80, v70
	v_mov_b32_e32 v81, v66
	v_mov_b32_e32 v72, v190
	v_mov_b32_e32 v73, v191
	v_lshlrev_b32_e32 v76, 16, v72
	v_and_b32_e32 v77, 0xffff0000, v72
	v_pk_add_f32 v[76:77], v[80:81], v[76:77]
	v_lshlrev_b32_e32 v72, 16, v73
	v_and_b32_e32 v73, 0xffff0000, v73
	v_mov_b32_e32 v80, v78
	v_mov_b32_e32 v81, v74
	v_pk_add_f32 v[72:73], v[80:81], v[72:73]
	v_cvt_pk_bf16_f32 v80, v76, v77
	v_cvt_pk_bf16_f32 v81, v72, v73
	global_store_dwordx2 v[68:69], v[80:81], off sc1
	v_pk_mul_f32 v[68:69], v[76:77], v[76:77]
	v_pk_mul_f32 v[72:73], v[72:73], v[72:73]
	v_add_f32_e32 v66, v68, v69
	v_add_f32_e32 v66, v72, v66
	v_add_f32_e32 v66, v73, v66
	v_mov_b32_e32 v68, 0
	s_nop 0
	v_add_f32_dpp v66, v66, v66 row_ror:8 row_mask:0xf bank_mask:0xf bound_ctrl:1
	s_nop 1
	v_add_f32_dpp v66, v66, v66 row_ror:4 row_mask:0xf bank_mask:0xf bound_ctrl:1
	s_nop 1
	v_add_f32_dpp v66, v66, v66 row_ror:2 row_mask:0xf bank_mask:0xf bound_ctrl:1
	s_nop 1
	v_mov_b32_dpp v68, v66 row_ror:1 row_mask:0xf bank_mask:0xf
	s_and_saveexec_b64 s[2:3], s[10:11]
	s_cbranch_execz .LBB0_425
	v_add_f32_e32 v66, v66, v68
	v_mul_f32_e32 v66, 0x49800000, v66
	v_trunc_f32_e32 v66, v66
	v_mul_f32_e32 v68, 0x2f800000, v66
	v_floor_f32_e32 v69, v68
	v_fmac_f32_e32 v66, 0xcf800000, v69
	v_cvt_u32_f32_e32 v68, v66
	v_cvt_u32_f32_e32 v69, v69
	v_lshl_add_u64 v[64:65], v[64:65], 3, s[0:1]
	global_atomic_add_x2 v[64:65], v[68:69], off
.LBB0_425:
	s_or_b64 exec, exec, s[2:3]
	v_add_u32_e32 v64, 51, v132
	v_ashrrev_i32_e32 v65, 31, v64
	v_lshlrev_b64 v[68:69], 12, v[64:65]
	v_lshl_add_u64 v[68:69], v[134:135], 0, v[68:69]
	v_mov_b32_e32 v66, v71
	v_mov_b32_e32 v74, v79
	v_mov_b32_e32 v72, v192
	v_mov_b32_e32 v73, v193
	v_lshlrev_b32_e32 v70, 16, v72
	v_and_b32_e32 v71, 0xffff0000, v72
	v_lshlrev_b32_e32 v72, 16, v73
	v_and_b32_e32 v73, 0xffff0000, v73
	v_pk_add_f32 v[66:67], v[66:67], v[70:71]
	v_pk_add_f32 v[70:71], v[74:75], v[72:73]
	v_cvt_pk_bf16_f32 v72, v66, v67
	v_pk_mul_f32 v[66:67], v[66:67], v[66:67]
	v_cvt_pk_bf16_f32 v73, v70, v71
	v_pk_mul_f32 v[70:71], v[70:71], v[70:71]
	v_add_f32_e32 v66, v66, v67
	v_add_f32_e32 v66, v70, v66
	v_add_f32_e32 v66, v71, v66
	v_mov_b32_e32 v67, 0
	global_store_dwordx2 v[68:69], v[72:73], off sc1
	v_add_f32_dpp v66, v66, v66 row_ror:8 row_mask:0xf bank_mask:0xf bound_ctrl:1
	s_nop 1
	v_add_f32_dpp v66, v66, v66 row_ror:4 row_mask:0xf bank_mask:0xf bound_ctrl:1
	s_nop 1
	v_add_f32_dpp v66, v66, v66 row_ror:2 row_mask:0xf bank_mask:0xf bound_ctrl:1
	s_nop 1
	v_mov_b32_dpp v67, v66 row_ror:1 row_mask:0xf bank_mask:0xf
	s_and_saveexec_b64 s[2:3], s[10:11]
	s_cbranch_execz .LBB0_427
	v_add_f32_e32 v66, v66, v67
	v_mul_f32_e32 v66, 0x49800000, v66
	v_trunc_f32_e32 v66, v66
	v_mul_f32_e32 v67, 0x2f800000, v66
	v_floor_f32_e32 v67, v67
	v_fmac_f32_e32 v66, 0xcf800000, v67
	v_cvt_u32_f32_e32 v66, v66
	v_cvt_u32_f32_e32 v67, v67
	v_lshl_add_u64 v[64:65], v[64:65], 3, s[0:1]
	global_atomic_add_x2 v[64:65], v[66:67], off
.LBB0_427:
	s_or_b64 exec, exec, s[2:3]
	v_add_u32_e32 v64, 0x80, v132
	v_ashrrev_i32_e32 v65, 31, v64
	v_lshlrev_b64 v[66:67], 12, v[64:65]
	v_lshl_add_u64 v[66:67], v[134:135], 0, v[66:67]
	v_mov_b32_e32 v72, v52
	v_mov_b32_e32 v73, v48
	v_mov_b32_e32 v52, 0
	v_mov_b32_e32 v68, v194
	v_mov_b32_e32 v69, v195
	v_lshlrev_b32_e32 v70, 16, v68
	v_and_b32_e32 v71, 0xffff0000, v68
	v_pk_add_f32 v[70:71], v[72:73], v[70:71]
	v_lshlrev_b32_e32 v68, 16, v69
	v_and_b32_e32 v69, 0xffff0000, v69
	v_mov_b32_e32 v72, v60
	v_mov_b32_e32 v73, v56
	v_pk_add_f32 v[68:69], v[72:73], v[68:69]
	v_cvt_pk_bf16_f32 v72, v70, v71
	v_cvt_pk_bf16_f32 v73, v68, v69
	global_store_dwordx2 v[66:67], v[72:73], off sc1
	v_pk_mul_f32 v[66:67], v[70:71], v[70:71]
	v_pk_mul_f32 v[68:69], v[68:69], v[68:69]
	v_add_f32_e32 v48, v66, v67
	v_add_f32_e32 v48, v68, v48
	v_add_f32_e32 v48, v69, v48
	s_nop 1
	v_add_f32_dpp v48, v48, v48 row_ror:8 row_mask:0xf bank_mask:0xf bound_ctrl:1
	s_nop 1
	v_add_f32_dpp v48, v48, v48 row_ror:4 row_mask:0xf bank_mask:0xf bound_ctrl:1
	s_nop 1
	v_add_f32_dpp v48, v48, v48 row_ror:2 row_mask:0xf bank_mask:0xf bound_ctrl:1
	s_nop 1
	v_mov_b32_dpp v52, v48 row_ror:1 row_mask:0xf bank_mask:0xf
	s_and_saveexec_b64 s[2:3], s[10:11]
	s_cbranch_execz .LBB0_429
	v_add_f32_e32 v48, v48, v52
	v_mul_f32_e32 v48, 0x49800000, v48
	v_trunc_f32_e32 v48, v48
	v_mul_f32_e32 v52, 0x2f800000, v48
	v_floor_f32_e32 v52, v52
	v_fmac_f32_e32 v48, 0xcf800000, v52
	v_cvt_u32_f32_e32 v66, v48
	v_cvt_u32_f32_e32 v67, v52
	v_lshl_add_u64 v[64:65], v[64:65], 3, s[0:1]
	global_atomic_add_x2 v[64:65], v[66:67], off
; __device__ __forceinline__ float row16_sum(float v) { DPP_ADD(v, 0x128); DPP_ADD(v, 0x124); DPP_ADD(v, 0x122); DPP_ADD(v, 0x121); return v; }
; template <int EPI, int N, int K>
; __device__ __forceinline__ void gemm_phase(const bf16_t* __restrict__ A, const bf16_t* __restrict__ Bt, const EpiArgs ea) {
;     ...
;           for (int j = 0; j < 4; ++j) {
;             const int row = brow + ai * 128 + wr * 64 + m * 16 + fq * 4 + j;
;             const u32x2 x2 = *(const u32x2*)(ea.outb + (size_t)row * DM + c0);
;             float4 xn;
;             xn.x = __builtin_bit_cast(float, x2[0] << 16) + acc[ai][0][m][0][j]; xn.y = __builtin_bit_cast(float, x2[0] & 0xffff0000u) + acc[ai][0][m][1][j];
;             xn.z = __builtin_bit_cast(float, x2[1] << 16) + acc[ai][1][m][0][j]; xn.w = __builtin_bit_cast(float, x2[1] & 0xffff0000u) + acc[ai][1][m][1][j];
;             u32x2 o = {pk2(xn.x, xn.y), pk2(xn.z, xn.w)};
;             st_wt(ea.outb + (size_t)row * DM + c0, o);
;             float ss = xn.x * xn.x + xn.y * xn.y + xn.z * xn.z + xn.w * xn.w;
;             ss = row16_sum(ss);
;             if (fr == 0) __hip_atomic_fetch_add(ea.rowsq_out + row, (rsq_t)(ss * RSQ_SCALE), __ATOMIC_RELAXED, __HIP_MEMORY_SCOPE_AGENT);
.LBB0_429:
	s_or_b64 exec, exec, s[2:3]
	v_add_u32_e32 v64, 0x81, v132
	v_ashrrev_i32_e32 v65, 31, v64
	v_lshlrev_b64 v[66:67], 12, v[64:65]
	v_lshl_add_u64 v[66:67], v[134:135], 0, v[66:67]
	v_mov_b32_e32 v48, v53
	v_mov_b32_e32 v56, v61
	v_mov_b32_e32 v68, v196
	v_mov_b32_e32 v69, v197
	v_lshlrev_b32_e32 v70, 16, v68
	v_and_b32_e32 v71, 0xffff0000, v68
	v_pk_add_f32 v[48:49], v[48:49], v[70:71]
	v_lshlrev_b32_e32 v52, 16, v69
	v_and_b32_e32 v53, 0xffff0000, v69
	v_pk_add_f32 v[52:53], v[56:57], v[52:53]
	v_cvt_pk_bf16_f32 v56, v48, v49
	v_pk_mul_f32 v[48:49], v[48:49], v[48:49]
	v_cvt_pk_bf16_f32 v57, v52, v53
	v_pk_mul_f32 v[52:53], v[52:53], v[52:53]
	v_add_f32_e32 v48, v48, v49
	v_add_f32_e32 v48, v52, v48
	v_add_f32_e32 v48, v53, v48
	v_mov_b32_e32 v49, 0
	global_store_dwordx2 v[66:67], v[56:57], off sc1
	v_add_f32_dpp v48, v48, v48 row_ror:8 row_mask:0xf bank_mask:0xf bound_ctrl:1
	s_nop 1
	v_add_f32_dpp v48, v48, v48 row_ror:4 row_mask:0xf bank_mask:0xf bound_ctrl:1
	s_nop 1
	v_add_f32_dpp v48, v48, v48 row_ror:2 row_mask:0xf bank_mask:0xf bound_ctrl:1
	s_nop 1
	v_mov_b32_dpp v49, v48 row_ror:1 row_mask:0xf bank_mask:0xf
	s_and_saveexec_b64 s[2:3], s[10:11]
	s_cbranch_execz .LBB0_431
	v_add_f32_e32 v48, v48, v49
	v_mul_f32_e32 v48, 0x49800000, v48
	v_trunc_f32_e32 v48, v48
	v_mul_f32_e32 v49, 0x2f800000, v48
	v_floor_f32_e32 v49, v49
	v_fmac_f32_e32 v48, 0xcf800000, v49
	v_cvt_u32_f32_e32 v48, v48
	v_cvt_u32_f32_e32 v49, v49
	v_lshl_add_u64 v[52:53], v[64:65], 3, s[0:1]
	global_atomic_add_x2 v[52:53], v[48:49], off
.LBB0_431:
	s_or_b64 exec, exec, s[2:3]
	v_add_u32_e32 v48, 0x82, v132
	v_ashrrev_i32_e32 v49, 31, v48
	v_lshlrev_b64 v[52:53], 12, v[48:49]
	v_lshl_add_u64 v[52:53], v[134:135], 0, v[52:53]
	v_mov_b32_e32 v64, v54
	v_mov_b32_e32 v65, v50
	v_mov_b32_e32 v56, v198
	v_mov_b32_e32 v57, v199
	v_lshlrev_b32_e32 v60, 16, v56
	v_and_b32_e32 v61, 0xffff0000, v56
	v_pk_add_f32 v[60:61], v[64:65], v[60:61]
	v_lshlrev_b32_e32 v56, 16, v57
	v_and_b32_e32 v57, 0xffff0000, v57
	v_mov_b32_e32 v64, v62
	v_mov_b32_e32 v65, v58
	v_pk_add_f32 v[56:57], v[64:65], v[56:57]
	v_cvt_pk_bf16_f32 v64, v60, v61
	v_cvt_pk_bf16_f32 v65, v56, v57
	global_store_dwordx2 v[52:53], v[64:65], off sc1
	v_pk_mul_f32 v[52:53], v[60:61], v[60:61]
	v_pk_mul_f32 v[56:57], v[56:57], v[56:57]
	v_add_f32_e32 v50, v52, v53
	v_add_f32_e32 v50, v56, v50
	v_add_f32_e32 v50, v57, v50
	v_mov_b32_e32 v52, 0
	s_nop 0
	v_add_f32_dpp v50, v50, v50 row_ror:8 row_mask:0xf bank_mask:0xf bound_ctrl:1
	s_nop 1
	v_add_f32_dpp v50, v50, v50 row_ror:4 row_mask:0xf bank_mask:0xf bound_ctrl:1
	s_nop 1
	v_add_f32_dpp v50, v50, v50 row_ror:2 row_mask:0xf bank_mask:0xf bound_ctrl:1
	s_nop 1
	v_mov_b32_dpp v52, v50 row_ror:1 row_mask:0xf bank_mask:0xf
	s_and_saveexec_b64 s[2:3], s[10:11]
	s_cbranch_execz .LBB0_433
	v_add_f32_e32 v50, v50, v52
	v_mul_f32_e32 v50, 0x49800000, v50
	v_trunc_f32_e32 v50, v50
	v_mul_f32_e32 v52, 0x2f800000, v50
	v_floor_f32_e32 v53, v52
	v_fmac_f32_e32 v50, 0xcf800000, v53
	v_cvt_u32_f32_e32 v52, v50
	v_cvt_u32_f32_e32 v53, v53
	v_lshl_add_u64 v[48:49], v[48:49], 3, s[0:1]
	global_atomic_add_x2 v[48:49], v[52:53], off
.LBB0_433:
	s_or_b64 exec, exec, s[2:3]
	v_add_u32_e32 v48, 0x83, v132
	v_ashrrev_i32_e32 v49, 31, v48
	v_lshlrev_b64 v[52:53], 12, v[48:49]
	v_lshl_add_u64 v[52:53], v[134:135], 0, v[52:53]
	v_mov_b32_e32 v50, v55
	v_mov_b32_e32 v58, v63
	v_mov_b32_e32 v56, v200
	v_mov_b32_e32 v57, v201
	v_lshlrev_b32_e32 v54, 16, v56
	v_and_b32_e32 v55, 0xffff0000, v56
	v_lshlrev_b32_e32 v56, 16, v57
	v_and_b32_e32 v57, 0xffff0000, v57
	v_pk_add_f32 v[50:51], v[50:51], v[54:55]
	v_pk_add_f32 v[54:55], v[58:59], v[56:57]
	v_cvt_pk_bf16_f32 v56, v50, v51
	v_pk_mul_f32 v[50:51], v[50:51], v[50:51]
	v_cvt_pk_bf16_f32 v57, v54, v55
	v_pk_mul_f32 v[54:55], v[54:55], v[54:55]
	v_add_f32_e32 v50, v50, v51
	v_add_f32_e32 v50, v54, v50
	v_add_f32_e32 v50, v55, v50
	v_mov_b32_e32 v51, 0
	global_store_dwordx2 v[52:53], v[56:57], off sc1
	v_add_f32_dpp v50, v50, v50 row_ror:8 row_mask:0xf bank_mask:0xf bound_ctrl:1
	s_nop 1
	v_add_f32_dpp v50, v50, v50 row_ror:4 row_mask:0xf bank_mask:0xf bound_ctrl:1
	s_nop 1
	v_add_f32_dpp v50, v50, v50 row_ror:2 row_mask:0xf bank_mask:0xf bound_ctrl:1
	s_nop 1
	v_mov_b32_dpp v51, v50 row_ror:1 row_mask:0xf bank_mask:0xf
	s_and_saveexec_b64 s[2:3], s[10:11]
	s_cbranch_execz .LBB0_435
	v_add_f32_e32 v50, v50, v51
	v_mul_f32_e32 v50, 0x49800000, v50
	v_trunc_f32_e32 v50, v50
	v_mul_f32_e32 v51, 0x2f800000, v50
	v_floor_f32_e32 v51, v51
	v_fmac_f32_e32 v50, 0xcf800000, v51
	v_cvt_u32_f32_e32 v50, v50
	v_cvt_u32_f32_e32 v51, v51
	v_lshl_add_u64 v[48:49], v[48:49], 3, s[0:1]
	global_atomic_add_x2 v[48:49], v[50:51], off
.LBB0_435:
	s_or_b64 exec, exec, s[2:3]
	v_add_u32_e32 v48, 0x90, v132
	v_ashrrev_i32_e32 v49, 31, v48
	v_lshlrev_b64 v[50:51], 12, v[48:49]
	v_lshl_add_u64 v[50:51], v[134:135], 0, v[50:51]
	v_mov_b32_e32 v56, v36
	v_mov_b32_e32 v57, v32
	v_mov_b32_e32 v36, 0
	v_mov_b32_e32 v52, v202
	v_mov_b32_e32 v53, v203
	v_lshlrev_b32_e32 v54, 16, v52
	v_and_b32_e32 v55, 0xffff0000, v52
	v_pk_add_f32 v[54:55], v[56:57], v[54:55]
	v_lshlrev_b32_e32 v52, 16, v53
	v_and_b32_e32 v53, 0xffff0000, v53
	v_mov_b32_e32 v56, v44
	v_mov_b32_e32 v57, v40
	v_pk_add_f32 v[52:53], v[56:57], v[52:53]
	v_cvt_pk_bf16_f32 v56, v54, v55
	v_cvt_pk_bf16_f32 v57, v52, v53
	global_store_dwordx2 v[50:51], v[56:57], off sc1
	v_pk_mul_f32 v[50:51], v[54:55], v[54:55]
	v_pk_mul_f32 v[52:53], v[52:53], v[52:53]
	v_add_f32_e32 v32, v50, v51
	v_add_f32_e32 v32, v52, v32
	v_add_f32_e32 v32, v53, v32
	s_nop 1
	v_add_f32_dpp v32, v32, v32 row_ror:8 row_mask:0xf bank_mask:0xf bound_ctrl:1
	s_nop 1
	v_add_f32_dpp v32, v32, v32 row_ror:4 row_mask:0xf bank_mask:0xf bound_ctrl:1
	s_nop 1
	v_add_f32_dpp v32, v32, v32 row_ror:2 row_mask:0xf bank_mask:0xf bound_ctrl:1
	s_nop 1
	v_mov_b32_dpp v36, v32 row_ror:1 row_mask:0xf bank_mask:0xf
	s_and_saveexec_b64 s[2:3], s[10:11]
	s_cbranch_execz .LBB0_437
	v_add_f32_e32 v32, v32, v36
	v_mul_f32_e32 v32, 0x49800000, v32
	v_trunc_f32_e32 v32, v32
	v_mul_f32_e32 v36, 0x2f800000, v32
	v_floor_f32_e32 v36, v36
	v_fmac_f32_e32 v32, 0xcf800000, v36
	v_cvt_u32_f32_e32 v50, v32
	v_cvt_u32_f32_e32 v51, v36
	v_lshl_add_u64 v[48:49], v[48:49], 3, s[0:1]
	global_atomic_add_x2 v[48:49], v[50:51], off
; __device__ __forceinline__ float row16_sum(float v) { DPP_ADD(v, 0x128); DPP_ADD(v, 0x124); DPP_ADD(v, 0x122); DPP_ADD(v, 0x121); return v; }
; template <int EPI, int N, int K>
; __device__ __forceinline__ void gemm_phase(const bf16_t* __restrict__ A, const bf16_t* __restrict__ Bt, const EpiArgs ea) {
;     ...
;           for (int j = 0; j < 4; ++j) {
;             const int row = brow + ai * 128 + wr * 64 + m * 16 + fq * 4 + j;
;             const u32x2 x2 = *(const u32x2*)(ea.outb + (size_t)row * DM + c0);
;             float4 xn;
;             xn.x = __builtin_bit_cast(float, x2[0] << 16) + acc[ai][0][m][0][j]; xn.y = __builtin_bit_cast(float, x2[0] & 0xffff0000u) + acc[ai][0][m][1][j];
;             xn.z = __builtin_bit_cast(float, x2[1] << 16) + acc[ai][1][m][0][j]; xn.w = __builtin_bit_cast(float, x2[1] & 0xffff0000u) + acc[ai][1][m][1][j];
;             u32x2 o = {pk2(xn.x, xn.y), pk2(xn.z, xn.w)};
;             st_wt(ea.outb + (size_t)row * DM + c0, o);
;             float ss = xn.x * xn.x + xn.y * xn.y + xn.z * xn.z + xn.w * xn.w;
;             ss = row16_sum(ss);
;             if (fr == 0) __hip_atomic_fetch_add(ea.rowsq_out + row, (rsq_t)(ss * RSQ_SCALE), __ATOMIC_RELAXED, __HIP_MEMORY_SCOPE_AGENT);
.LBB0_437:
	s_or_b64 exec, exec, s[2:3]
	v_add_u32_e32 v48, 0x91, v132
	v_ashrrev_i32_e32 v49, 31, v48
	v_lshlrev_b64 v[50:51], 12, v[48:49]
	v_lshl_add_u64 v[50:51], v[134:135], 0, v[50:51]
	v_mov_b32_e32 v32, v37
	v_mov_b32_e32 v40, v45
	v_mov_b32_e32 v52, v204
	v_mov_b32_e32 v53, v205
	v_lshlrev_b32_e32 v54, 16, v52
	v_and_b32_e32 v55, 0xffff0000, v52
	v_pk_add_f32 v[32:33], v[32:33], v[54:55]
	v_lshlrev_b32_e32 v36, 16, v53
	v_and_b32_e32 v37, 0xffff0000, v53
	v_pk_add_f32 v[36:37], v[40:41], v[36:37]
	v_cvt_pk_bf16_f32 v40, v32, v33
	v_pk_mul_f32 v[32:33], v[32:33], v[32:33]
	v_cvt_pk_bf16_f32 v41, v36, v37
	v_pk_mul_f32 v[36:37], v[36:37], v[36:37]
	v_add_f32_e32 v32, v32, v33
	v_add_f32_e32 v32, v36, v32
	v_add_f32_e32 v32, v37, v32
	v_mov_b32_e32 v33, 0
	global_store_dwordx2 v[50:51], v[40:41], off sc1
	v_add_f32_dpp v32, v32, v32 row_ror:8 row_mask:0xf bank_mask:0xf bound_ctrl:1
	s_nop 1
	v_add_f32_dpp v32, v32, v32 row_ror:4 row_mask:0xf bank_mask:0xf bound_ctrl:1
	s_nop 1
	v_add_f32_dpp v32, v32, v32 row_ror:2 row_mask:0xf bank_mask:0xf bound_ctrl:1
	s_nop 1
	v_mov_b32_dpp v33, v32 row_ror:1 row_mask:0xf bank_mask:0xf
	s_and_saveexec_b64 s[2:3], s[10:11]
	s_cbranch_execz .LBB0_439
	v_add_f32_e32 v32, v32, v33
	v_mul_f32_e32 v32, 0x49800000, v32
	v_trunc_f32_e32 v32, v32
	v_mul_f32_e32 v33, 0x2f800000, v32
	v_floor_f32_e32 v33, v33
	v_fmac_f32_e32 v32, 0xcf800000, v33
	v_cvt_u32_f32_e32 v32, v32
	v_cvt_u32_f32_e32 v33, v33
	v_lshl_add_u64 v[36:37], v[48:49], 3, s[0:1]
	global_atomic_add_x2 v[36:37], v[32:33], off
.LBB0_439:
	s_or_b64 exec, exec, s[2:3]
	v_add_u32_e32 v32, 0x92, v132
	v_ashrrev_i32_e32 v33, 31, v32
	v_lshlrev_b64 v[36:37], 12, v[32:33]
	v_lshl_add_u64 v[36:37], v[134:135], 0, v[36:37]
	v_mov_b32_e32 v48, v38
	v_mov_b32_e32 v49, v34
	v_mov_b32_e32 v40, v206
	v_mov_b32_e32 v41, v207
	v_lshlrev_b32_e32 v44, 16, v40
	v_and_b32_e32 v45, 0xffff0000, v40
	v_pk_add_f32 v[44:45], v[48:49], v[44:45]
	v_lshlrev_b32_e32 v40, 16, v41
	v_and_b32_e32 v41, 0xffff0000, v41
	v_mov_b32_e32 v48, v46
	v_mov_b32_e32 v49, v42
	v_pk_add_f32 v[40:41], v[48:49], v[40:41]
	v_cvt_pk_bf16_f32 v48, v44, v45
	v_cvt_pk_bf16_f32 v49, v40, v41
	global_store_dwordx2 v[36:37], v[48:49], off sc1
	v_pk_mul_f32 v[36:37], v[44:45], v[44:45]
	v_pk_mul_f32 v[40:41], v[40:41], v[40:41]
	v_add_f32_e32 v34, v36, v37
	v_add_f32_e32 v34, v40, v34
	v_add_f32_e32 v34, v41, v34
	v_mov_b32_e32 v36, 0
	s_nop 0
	v_add_f32_dpp v34, v34, v34 row_ror:8 row_mask:0xf bank_mask:0xf bound_ctrl:1
	s_nop 1
	v_add_f32_dpp v34, v34, v34 row_ror:4 row_mask:0xf bank_mask:0xf bound_ctrl:1
	s_nop 1
	v_add_f32_dpp v34, v34, v34 row_ror:2 row_mask:0xf bank_mask:0xf bound_ctrl:1
	s_nop 1
	v_mov_b32_dpp v36, v34 row_ror:1 row_mask:0xf bank_mask:0xf
	s_and_saveexec_b64 s[2:3], s[10:11]
	s_cbranch_execz .LBB0_441
	v_add_f32_e32 v34, v34, v36
	v_mul_f32_e32 v34, 0x49800000, v34
	v_trunc_f32_e32 v34, v34
	v_mul_f32_e32 v36, 0x2f800000, v34
	v_floor_f32_e32 v37, v36
	v_fmac_f32_e32 v34, 0xcf800000, v37
	v_cvt_u32_f32_e32 v36, v34
	v_cvt_u32_f32_e32 v37, v37
	v_lshl_add_u64 v[32:33], v[32:33], 3, s[0:1]
	global_atomic_add_x2 v[32:33], v[36:37], off
.LBB0_441:
	s_or_b64 exec, exec, s[2:3]
	v_add_u32_e32 v32, 0x93, v132
	v_ashrrev_i32_e32 v33, 31, v32
	v_lshlrev_b64 v[36:37], 12, v[32:33]
	v_lshl_add_u64 v[36:37], v[134:135], 0, v[36:37]
	v_mov_b32_e32 v34, v39
	v_mov_b32_e32 v42, v47
	v_mov_b32_e32 v40, v208
	v_mov_b32_e32 v41, v209
	v_lshlrev_b32_e32 v38, 16, v40
	v_and_b32_e32 v39, 0xffff0000, v40
	v_lshlrev_b32_e32 v40, 16, v41
	v_and_b32_e32 v41, 0xffff0000, v41
	v_pk_add_f32 v[34:35], v[34:35], v[38:39]
	v_pk_add_f32 v[38:39], v[42:43], v[40:41]
	v_cvt_pk_bf16_f32 v40, v34, v35
	v_pk_mul_f32 v[34:35], v[34:35], v[34:35]
	v_cvt_pk_bf16_f32 v41, v38, v39
	v_pk_mul_f32 v[38:39], v[38:39], v[38:39]
	v_add_f32_e32 v34, v34, v35
	v_add_f32_e32 v34, v38, v34
	v_add_f32_e32 v34, v39, v34
	v_mov_b32_e32 v35, 0
	global_store_dwordx2 v[36:37], v[40:41], off sc1
	v_add_f32_dpp v34, v34, v34 row_ror:8 row_mask:0xf bank_mask:0xf bound_ctrl:1
	s_nop 1
	v_add_f32_dpp v34, v34, v34 row_ror:4 row_mask:0xf bank_mask:0xf bound_ctrl:1
	s_nop 1
	v_add_f32_dpp v34, v34, v34 row_ror:2 row_mask:0xf bank_mask:0xf bound_ctrl:1
	s_nop 1
	v_mov_b32_dpp v35, v34 row_ror:1 row_mask:0xf bank_mask:0xf
	s_and_saveexec_b64 s[2:3], s[10:11]
	s_cbranch_execz .LBB0_443
	v_add_f32_e32 v34, v34, v35
	v_mul_f32_e32 v34, 0x49800000, v34
	v_trunc_f32_e32 v34, v34
	v_mul_f32_e32 v35, 0x2f800000, v34
	v_floor_f32_e32 v35, v35
	v_fmac_f32_e32 v34, 0xcf800000, v35
	v_cvt_u32_f32_e32 v34, v34
	v_cvt_u32_f32_e32 v35, v35
	v_lshl_add_u64 v[32:33], v[32:33], 3, s[0:1]
	global_atomic_add_x2 v[32:33], v[34:35], off
.LBB0_443:
	s_or_b64 exec, exec, s[2:3]
	v_add_u32_e32 v32, 0xa0, v132
	v_ashrrev_i32_e32 v33, 31, v32
	v_lshlrev_b64 v[34:35], 12, v[32:33]
	v_lshl_add_u64 v[34:35], v[134:135], 0, v[34:35]
	v_mov_b32_e32 v40, v20
	v_mov_b32_e32 v41, v16
	v_mov_b32_e32 v20, 0
	v_mov_b32_e32 v36, v210
	v_mov_b32_e32 v37, v211
	v_lshlrev_b32_e32 v38, 16, v36
	v_and_b32_e32 v39, 0xffff0000, v36
	v_pk_add_f32 v[38:39], v[40:41], v[38:39]
	v_lshlrev_b32_e32 v36, 16, v37
	v_and_b32_e32 v37, 0xffff0000, v37
	v_mov_b32_e32 v40, v28
	v_mov_b32_e32 v41, v24
	v_pk_add_f32 v[36:37], v[40:41], v[36:37]
	v_cvt_pk_bf16_f32 v40, v38, v39
	v_cvt_pk_bf16_f32 v41, v36, v37
	global_store_dwordx2 v[34:35], v[40:41], off sc1
	v_pk_mul_f32 v[34:35], v[38:39], v[38:39]
	v_pk_mul_f32 v[36:37], v[36:37], v[36:37]
	v_add_f32_e32 v16, v34, v35
	v_add_f32_e32 v16, v36, v16
	v_add_f32_e32 v16, v37, v16
	s_nop 1
	v_add_f32_dpp v16, v16, v16 row_ror:8 row_mask:0xf bank_mask:0xf bound_ctrl:1
	s_nop 1
	v_add_f32_dpp v16, v16, v16 row_ror:4 row_mask:0xf bank_mask:0xf bound_ctrl:1
	s_nop 1
	v_add_f32_dpp v16, v16, v16 row_ror:2 row_mask:0xf bank_mask:0xf bound_ctrl:1
	s_nop 1
	v_mov_b32_dpp v20, v16 row_ror:1 row_mask:0xf bank_mask:0xf
	s_and_saveexec_b64 s[2:3], s[10:11]
	s_cbranch_execz .LBB0_445
	v_add_f32_e32 v16, v16, v20
	v_mul_f32_e32 v16, 0x49800000, v16
	v_trunc_f32_e32 v16, v16
	v_mul_f32_e32 v20, 0x2f800000, v16
	v_floor_f32_e32 v20, v20
	v_fmac_f32_e32 v16, 0xcf800000, v20
	v_cvt_u32_f32_e32 v34, v16
	v_cvt_u32_f32_e32 v35, v20
	v_lshl_add_u64 v[32:33], v[32:33], 3, s[0:1]
	global_atomic_add_x2 v[32:33], v[34:35], off
; __device__ __forceinline__ float row16_sum(float v) { DPP_ADD(v, 0x128); DPP_ADD(v, 0x124); DPP_ADD(v, 0x122); DPP_ADD(v, 0x121); return v; }
; template <int EPI, int N, int K>
; __device__ __forceinline__ void gemm_phase(const bf16_t* __restrict__ A, const bf16_t* __restrict__ Bt, const EpiArgs ea) {
;     ...
;           for (int j = 0; j < 4; ++j) {
;             const int row = brow + ai * 128 + wr * 64 + m * 16 + fq * 4 + j;
;             const u32x2 x2 = *(const u32x2*)(ea.outb + (size_t)row * DM + c0);
;             float4 xn;
;             xn.x = __builtin_bit_cast(float, x2[0] << 16) + acc[ai][0][m][0][j]; xn.y = __builtin_bit_cast(float, x2[0] & 0xffff0000u) + acc[ai][0][m][1][j];
;             xn.z = __builtin_bit_cast(float, x2[1] << 16) + acc[ai][1][m][0][j]; xn.w = __builtin_bit_cast(float, x2[1] & 0xffff0000u) + acc[ai][1][m][1][j];
;             u32x2 o = {pk2(xn.x, xn.y), pk2(xn.z, xn.w)};
;             st_wt(ea.outb + (size_t)row * DM + c0, o);
;             float ss = xn.x * xn.x + xn.y * xn.y + xn.z * xn.z + xn.w * xn.w;
;             ss = row16_sum(ss);
;             if (fr == 0) __hip_atomic_fetch_add(ea.rowsq_out + row, (rsq_t)(ss * RSQ_SCALE), __ATOMIC_RELAXED, __HIP_MEMORY_SCOPE_AGENT);
.LBB0_445:
	s_or_b64 exec, exec, s[2:3]
	v_add_u32_e32 v32, 0xa1, v132
	v_ashrrev_i32_e32 v33, 31, v32
	v_lshlrev_b64 v[34:35], 12, v[32:33]
	v_lshl_add_u64 v[34:35], v[134:135], 0, v[34:35]
	v_mov_b32_e32 v16, v21
	v_mov_b32_e32 v24, v29
	v_mov_b32_e32 v36, v212
	v_mov_b32_e32 v37, v213
	v_lshlrev_b32_e32 v38, 16, v36
	v_and_b32_e32 v39, 0xffff0000, v36
	v_pk_add_f32 v[16:17], v[16:17], v[38:39]
	v_lshlrev_b32_e32 v20, 16, v37
	v_and_b32_e32 v21, 0xffff0000, v37
	v_pk_add_f32 v[20:21], v[24:25], v[20:21]
	v_cvt_pk_bf16_f32 v24, v16, v17
	v_pk_mul_f32 v[16:17], v[16:17], v[16:17]
	v_cvt_pk_bf16_f32 v25, v20, v21
	v_pk_mul_f32 v[20:21], v[20:21], v[20:21]
	v_add_f32_e32 v16, v16, v17
	v_add_f32_e32 v16, v20, v16
	v_add_f32_e32 v16, v21, v16
	v_mov_b32_e32 v17, 0
	global_store_dwordx2 v[34:35], v[24:25], off sc1
	v_add_f32_dpp v16, v16, v16 row_ror:8 row_mask:0xf bank_mask:0xf bound_ctrl:1
	s_nop 1
	v_add_f32_dpp v16, v16, v16 row_ror:4 row_mask:0xf bank_mask:0xf bound_ctrl:1
	s_nop 1
	v_add_f32_dpp v16, v16, v16 row_ror:2 row_mask:0xf bank_mask:0xf bound_ctrl:1
	s_nop 1
	v_mov_b32_dpp v17, v16 row_ror:1 row_mask:0xf bank_mask:0xf
	s_and_saveexec_b64 s[2:3], s[10:11]
	s_cbranch_execz .LBB0_447
	v_add_f32_e32 v16, v16, v17
	v_mul_f32_e32 v16, 0x49800000, v16
	v_trunc_f32_e32 v16, v16
	v_mul_f32_e32 v17, 0x2f800000, v16
	v_floor_f32_e32 v17, v17
	v_fmac_f32_e32 v16, 0xcf800000, v17
	v_cvt_u32_f32_e32 v16, v16
	v_cvt_u32_f32_e32 v17, v17
	v_lshl_add_u64 v[20:21], v[32:33], 3, s[0:1]
	global_atomic_add_x2 v[20:21], v[16:17], off
.LBB0_447:
	s_or_b64 exec, exec, s[2:3]
	v_add_u32_e32 v16, 0xa2, v132
	v_ashrrev_i32_e32 v17, 31, v16
	v_lshlrev_b64 v[20:21], 12, v[16:17]
	v_lshl_add_u64 v[20:21], v[134:135], 0, v[20:21]
	v_mov_b32_e32 v32, v22
	v_mov_b32_e32 v33, v18
	v_mov_b32_e32 v24, v214
	v_mov_b32_e32 v25, v215
	v_lshlrev_b32_e32 v28, 16, v24
	v_and_b32_e32 v29, 0xffff0000, v24
	v_pk_add_f32 v[28:29], v[32:33], v[28:29]
	v_lshlrev_b32_e32 v24, 16, v25
	v_and_b32_e32 v25, 0xffff0000, v25
	v_mov_b32_e32 v32, v30
	v_mov_b32_e32 v33, v26
	v_pk_add_f32 v[24:25], v[32:33], v[24:25]
	v_cvt_pk_bf16_f32 v32, v28, v29
	v_cvt_pk_bf16_f32 v33, v24, v25
	global_store_dwordx2 v[20:21], v[32:33], off sc1
	v_pk_mul_f32 v[20:21], v[28:29], v[28:29]
	v_pk_mul_f32 v[24:25], v[24:25], v[24:25]
	v_add_f32_e32 v18, v20, v21
	v_add_f32_e32 v18, v24, v18
	v_add_f32_e32 v18, v25, v18
	v_mov_b32_e32 v20, 0
	s_nop 0
	v_add_f32_dpp v18, v18, v18 row_ror:8 row_mask:0xf bank_mask:0xf bound_ctrl:1
	s_nop 1
	v_add_f32_dpp v18, v18, v18 row_ror:4 row_mask:0xf bank_mask:0xf bound_ctrl:1
	s_nop 1
	v_add_f32_dpp v18, v18, v18 row_ror:2 row_mask:0xf bank_mask:0xf bound_ctrl:1
	s_nop 1
	v_mov_b32_dpp v20, v18 row_ror:1 row_mask:0xf bank_mask:0xf
	s_and_saveexec_b64 s[2:3], s[10:11]
	s_cbranch_execz .LBB0_449
	v_add_f32_e32 v18, v18, v20
	v_mul_f32_e32 v18, 0x49800000, v18
	v_trunc_f32_e32 v18, v18
	v_mul_f32_e32 v20, 0x2f800000, v18
	v_floor_f32_e32 v21, v20
	v_fmac_f32_e32 v18, 0xcf800000, v21
	v_cvt_u32_f32_e32 v20, v18
	v_cvt_u32_f32_e32 v21, v21
	v_lshl_add_u64 v[16:17], v[16:17], 3, s[0:1]
	global_atomic_add_x2 v[16:17], v[20:21], off
.LBB0_449:
	s_or_b64 exec, exec, s[2:3]
	v_add_u32_e32 v16, 0xa3, v132
	v_ashrrev_i32_e32 v17, 31, v16
	v_lshlrev_b64 v[20:21], 12, v[16:17]
	v_lshl_add_u64 v[20:21], v[134:135], 0, v[20:21]
	v_mov_b32_e32 v18, v23
	v_mov_b32_e32 v26, v31
	v_mov_b32_e32 v24, v216
	v_mov_b32_e32 v25, v217
	v_lshlrev_b32_e32 v22, 16, v24
	v_and_b32_e32 v23, 0xffff0000, v24
	v_lshlrev_b32_e32 v24, 16, v25
	v_and_b32_e32 v25, 0xffff0000, v25
	v_pk_add_f32 v[18:19], v[18:19], v[22:23]
	v_pk_add_f32 v[22:23], v[26:27], v[24:25]
	v_cvt_pk_bf16_f32 v24, v18, v19
	v_pk_mul_f32 v[18:19], v[18:19], v[18:19]
	v_cvt_pk_bf16_f32 v25, v22, v23
	v_pk_mul_f32 v[22:23], v[22:23], v[22:23]
	v_add_f32_e32 v18, v18, v19
	v_add_f32_e32 v18, v22, v18
	v_add_f32_e32 v18, v23, v18
	v_mov_b32_e32 v19, 0
	global_store_dwordx2 v[20:21], v[24:25], off sc1
	v_add_f32_dpp v18, v18, v18 row_ror:8 row_mask:0xf bank_mask:0xf bound_ctrl:1
	s_nop 1
	v_add_f32_dpp v18, v18, v18 row_ror:4 row_mask:0xf bank_mask:0xf bound_ctrl:1
	s_nop 1
	v_add_f32_dpp v18, v18, v18 row_ror:2 row_mask:0xf bank_mask:0xf bound_ctrl:1
	s_nop 1
	v_mov_b32_dpp v19, v18 row_ror:1 row_mask:0xf bank_mask:0xf
	s_and_saveexec_b64 s[2:3], s[10:11]
	s_cbranch_execz .LBB0_451
	v_add_f32_e32 v18, v18, v19
	v_mul_f32_e32 v18, 0x49800000, v18
	v_trunc_f32_e32 v18, v18
	v_mul_f32_e32 v19, 0x2f800000, v18
	v_floor_f32_e32 v19, v19
	v_fmac_f32_e32 v18, 0xcf800000, v19
	v_cvt_u32_f32_e32 v18, v18
	v_cvt_u32_f32_e32 v19, v19
	v_lshl_add_u64 v[16:17], v[16:17], 3, s[0:1]
	global_atomic_add_x2 v[16:17], v[18:19], off
; __device__ __forceinline__ float row16_sum(float v) { DPP_ADD(v, 0x128); DPP_ADD(v, 0x124); DPP_ADD(v, 0x122); DPP_ADD(v, 0x121); return v; }
; #define TILE_RC(w_, brow_, bcol_) do { const int wg_ = ((w_) & 7) * qx + ((w_) >> 3); const int gid_ = wg_ / nig; \
;     brow_ = (gid_ * 8 + ((wg_ % nig) & 7)) * 256; bcol_ = ((wg_ % nig) >> 3) * 256; } while (0)
; #define ISSUE7(brow_, bcol_) do { \
;     STAGE_BX(SB_OFF(0, 0), 0, 0, bcol_); STAGE_AX(SA_OFF(0, 0), 0, 0, brow_); STAGE_BX(SB_OFF(0, 1), 1, 0, bcol_); STAGE_AX(SA_OFF(0, 1), 1, 0, brow_); \
;     STAGE_BX(SB_OFF(1, 0), 0, 1, bcol_); STAGE_AX(SA_OFF(1, 0), 0, 1, brow_); STAGE_BX(SB_OFF(1, 1), 1, 1, bcol_); } while (0)
; template <int EPI, int N, int K>
; __device__ __forceinline__ void gemm_phase(const bf16_t* __restrict__ A, const bf16_t* __restrict__ Bt, const EpiArgs ea) {
;     ...
;       if (wn < nwg) { int nbrow, nbcol; TILE_RC(wn, nbrow, nbcol); ISSUE7(nbrow, nbcol); }
;     ...
;           for (int j = 0; j < 4; ++j) {
;             const int row = brow + ai * 128 + wr * 64 + m * 16 + fq * 4 + j;
;             const u32x2 x2 = *(const u32x2*)(ea.outb + (size_t)row * DM + c0);
;             float4 xn;
;             xn.x = __builtin_bit_cast(float, x2[0] << 16) + acc[ai][0][m][0][j]; xn.y = __builtin_bit_cast(float, x2[0] & 0xffff0000u) + acc[ai][0][m][1][j];
;             xn.z = __builtin_bit_cast(float, x2[1] << 16) + acc[ai][1][m][0][j]; xn.w = __builtin_bit_cast(float, x2[1] & 0xffff0000u) + acc[ai][1][m][1][j];
;             u32x2 o = {pk2(xn.x, xn.y), pk2(xn.z, xn.w)};
;             st_wt(ea.outb + (size_t)row * DM + c0, o);
;             float ss = xn.x * xn.x + xn.y * xn.y + xn.z * xn.z + xn.w * xn.w;
;             ss = row16_sum(ss);
;             if (fr == 0) __hip_atomic_fetch_add(ea.rowsq_out + row, (rsq_t)(ss * RSQ_SCALE), __ATOMIC_RELAXED, __HIP_MEMORY_SCOPE_AGENT);
.LBB0_451:
	s_or_b64 exec, exec, s[2:3]
	v_add_u32_e32 v16, 0xb0, v132
	v_ashrrev_i32_e32 v17, 31, v16
	v_lshlrev_b64 v[18:19], 12, v[16:17]
	v_lshl_add_u64 v[18:19], v[134:135], 0, v[18:19]
	v_mov_b32_e32 v24, v8
	v_mov_b32_e32 v25, v12
	v_mov_b32_e32 v20, v218
	v_mov_b32_e32 v21, v219
	v_lshlrev_b32_e32 v22, 16, v20
	v_and_b32_e32 v23, 0xffff0000, v20
	v_pk_add_f32 v[22:23], v[24:25], v[22:23]
	v_lshlrev_b32_e32 v20, 16, v21
	v_and_b32_e32 v21, 0xffff0000, v21
	v_mov_b32_e32 v24, v4
	v_mov_b32_e32 v25, v0
	v_pk_add_f32 v[20:21], v[24:25], v[20:21]
	v_cvt_pk_bf16_f32 v24, v22, v23
	v_cvt_pk_bf16_f32 v25, v20, v21
	global_store_dwordx2 v[18:19], v[24:25], off sc1
	v_pk_mul_f32 v[18:19], v[22:23], v[22:23]
	v_pk_mul_f32 v[20:21], v[20:21], v[20:21]
	v_add_f32_e32 v0, v18, v19
	v_add_f32_e32 v0, v20, v0
	v_add_f32_e32 v0, v21, v0
	v_mov_b32_e32 v4, 0
	s_nop 0
	v_add_f32_dpp v0, v0, v0 row_ror:8 row_mask:0xf bank_mask:0xf bound_ctrl:1
	s_nop 1
	v_add_f32_dpp v0, v0, v0 row_ror:4 row_mask:0xf bank_mask:0xf bound_ctrl:1
	s_nop 1
	v_add_f32_dpp v0, v0, v0 row_ror:2 row_mask:0xf bank_mask:0xf bound_ctrl:1
	s_nop 1
	v_mov_b32_dpp v4, v0 row_ror:1 row_mask:0xf bank_mask:0xf
	s_and_saveexec_b64 s[2:3], s[10:11]
	s_cbranch_execz .LBB0_453
	v_add_f32_e32 v0, v0, v4
	v_mul_f32_e32 v0, 0x49800000, v0
	v_trunc_f32_e32 v0, v0
	v_mul_f32_e32 v4, 0x2f800000, v0
	v_floor_f32_e32 v4, v4
	v_fmac_f32_e32 v0, 0xcf800000, v4
	v_cvt_u32_f32_e32 v18, v0
	v_cvt_u32_f32_e32 v19, v4
	v_lshl_add_u64 v[16:17], v[16:17], 3, s[0:1]
	global_atomic_add_x2 v[16:17], v[18:19], off
.LBB0_453:
	s_or_b64 exec, exec, s[2:3]
	v_add_u32_e32 v16, 0xb1, v132
	v_ashrrev_i32_e32 v17, 31, v16
	v_lshlrev_b64 v[18:19], 12, v[16:17]
	v_lshl_add_u64 v[18:19], v[134:135], 0, v[18:19]
	v_mov_b32_e32 v12, v9
	v_mov_b32_e32 v0, v5
	v_mov_b32_e32 v20, v220
	v_mov_b32_e32 v21, v221
	v_lshlrev_b32_e32 v22, 16, v20
	v_and_b32_e32 v23, 0xffff0000, v20
	v_pk_add_f32 v[8:9], v[12:13], v[22:23]
	v_lshlrev_b32_e32 v12, 16, v21
	v_and_b32_e32 v13, 0xffff0000, v21
	v_pk_add_f32 v[0:1], v[0:1], v[12:13]
	v_cvt_pk_bf16_f32 v4, v8, v9
	v_cvt_pk_bf16_f32 v5, v0, v1
	global_store_dwordx2 v[18:19], v[4:5], off sc1
	v_pk_mul_f32 v[4:5], v[8:9], v[8:9]
	v_pk_mul_f32 v[0:1], v[0:1], v[0:1]
	v_add_f32_e32 v4, v4, v5
	v_add_f32_e32 v0, v0, v4
	v_add_f32_e32 v0, v1, v0
	v_mov_b32_e32 v1, 0
	s_nop 0
	v_add_f32_dpp v0, v0, v0 row_ror:8 row_mask:0xf bank_mask:0xf bound_ctrl:1
	s_nop 1
	v_add_f32_dpp v0, v0, v0 row_ror:4 row_mask:0xf bank_mask:0xf bound_ctrl:1
	s_nop 1
	v_add_f32_dpp v0, v0, v0 row_ror:2 row_mask:0xf bank_mask:0xf bound_ctrl:1
	s_nop 1
	v_mov_b32_dpp v1, v0 row_ror:1 row_mask:0xf bank_mask:0xf
	s_and_saveexec_b64 s[2:3], s[10:11]
	s_cbranch_execz .LBB0_455
	v_add_f32_e32 v0, v0, v1
	v_mul_f32_e32 v0, 0x49800000, v0
	v_trunc_f32_e32 v0, v0
	v_mul_f32_e32 v1, 0x2f800000, v0
	v_floor_f32_e32 v1, v1
	v_fmac_f32_e32 v0, 0xcf800000, v1
	v_cvt_u32_f32_e32 v0, v0
	v_cvt_u32_f32_e32 v1, v1
	v_lshl_add_u64 v[4:5], v[16:17], 3, s[0:1]
	global_atomic_add_x2 v[4:5], v[0:1], off
.LBB0_455:
	s_or_b64 exec, exec, s[2:3]
	v_add_u32_e32 v0, 0xb2, v132
	v_ashrrev_i32_e32 v1, 31, v0
	v_lshlrev_b64 v[4:5], 12, v[0:1]
	v_lshl_add_u64 v[4:5], v[134:135], 0, v[4:5]
	v_mov_b32_e32 v16, v10
	v_mov_b32_e32 v17, v14
	v_mov_b32_e32 v8, v222
	v_mov_b32_e32 v9, v223
	v_lshlrev_b32_e32 v12, 16, v8
	v_and_b32_e32 v13, 0xffff0000, v8
	v_pk_add_f32 v[12:13], v[16:17], v[12:13]
	v_lshlrev_b32_e32 v8, 16, v9
	v_and_b32_e32 v9, 0xffff0000, v9
	v_mov_b32_e32 v16, v6
	v_mov_b32_e32 v17, v2
	v_pk_add_f32 v[8:9], v[16:17], v[8:9]
	v_cvt_pk_bf16_f32 v16, v12, v13
	v_cvt_pk_bf16_f32 v17, v8, v9
	global_store_dwordx2 v[4:5], v[16:17], off sc1
	v_pk_mul_f32 v[4:5], v[12:13], v[12:13]
	v_pk_mul_f32 v[8:9], v[8:9], v[8:9]
	v_add_f32_e32 v2, v4, v5
	v_add_f32_e32 v2, v8, v2
	v_add_f32_e32 v2, v9, v2
	v_mov_b32_e32 v4, 0
	s_nop 0
	v_add_f32_dpp v2, v2, v2 row_ror:8 row_mask:0xf bank_mask:0xf bound_ctrl:1
	s_nop 1
	v_add_f32_dpp v2, v2, v2 row_ror:4 row_mask:0xf bank_mask:0xf bound_ctrl:1
	s_nop 1
	v_add_f32_dpp v2, v2, v2 row_ror:2 row_mask:0xf bank_mask:0xf bound_ctrl:1
	s_nop 1
	v_mov_b32_dpp v4, v2 row_ror:1 row_mask:0xf bank_mask:0xf
	s_and_saveexec_b64 s[2:3], s[10:11]
	s_cbranch_execz .LBB0_457
	v_add_f32_e32 v2, v2, v4
	v_mul_f32_e32 v2, 0x49800000, v2
	v_trunc_f32_e32 v2, v2
	v_mul_f32_e32 v4, 0x2f800000, v2
	v_floor_f32_e32 v5, v4
	v_fmac_f32_e32 v2, 0xcf800000, v5
	v_cvt_u32_f32_e32 v4, v2
	v_cvt_u32_f32_e32 v5, v5
	v_lshl_add_u64 v[0:1], v[0:1], 3, s[0:1]
	global_atomic_add_x2 v[0:1], v[4:5], off
.LBB0_457:
	s_or_b64 exec, exec, s[2:3]
	v_add_u32_e32 v0, 0xb3, v132
	v_ashrrev_i32_e32 v1, 31, v0
	v_lshlrev_b64 v[4:5], 12, v[0:1]
	v_lshl_add_u64 v[4:5], v[134:135], 0, v[4:5]
	v_mov_b32_e32 v14, v11
	v_mov_b32_e32 v2, v7
	v_mov_b32_e32 v8, v224
	v_mov_b32_e32 v9, v225
	v_lshlrev_b32_e32 v12, 16, v8
	v_and_b32_e32 v13, 0xffff0000, v8
	v_lshlrev_b32_e32 v8, 16, v9
	v_and_b32_e32 v9, 0xffff0000, v9
	v_pk_add_f32 v[10:11], v[14:15], v[12:13]
	v_pk_add_f32 v[2:3], v[2:3], v[8:9]
	v_cvt_pk_bf16_f32 v6, v10, v11
	v_cvt_pk_bf16_f32 v7, v2, v3
	global_store_dwordx2 v[4:5], v[6:7], off sc1
	v_pk_mul_f32 v[4:5], v[10:11], v[10:11]
	v_pk_mul_f32 v[2:3], v[2:3], v[2:3]
	v_add_f32_e32 v4, v4, v5
	v_add_f32_e32 v2, v2, v4
	v_add_f32_e32 v2, v3, v2
	v_mov_b32_e32 v3, 0
	s_nop 0
	v_add_f32_dpp v2, v2, v2 row_ror:8 row_mask:0xf bank_mask:0xf bound_ctrl:1
	s_nop 1
	v_add_f32_dpp v2, v2, v2 row_ror:4 row_mask:0xf bank_mask:0xf bound_ctrl:1
	s_nop 1
	v_add_f32_dpp v2, v2, v2 row_ror:2 row_mask:0xf bank_mask:0xf bound_ctrl:1
	s_nop 1
	v_mov_b32_dpp v3, v2 row_ror:1 row_mask:0xf bank_mask:0xf
	s_and_saveexec_b64 s[2:3], s[10:11]
	s_cbranch_execz .LBB0_384
	v_add_f32_e32 v2, v2, v3
	v_mul_f32_e32 v2, 0x49800000, v2
	v_trunc_f32_e32 v2, v2
	v_mul_f32_e32 v3, 0x2f800000, v2
	v_floor_f32_e32 v3, v3
	v_fmac_f32_e32 v2, 0xcf800000, v3
	v_cvt_u32_f32_e32 v2, v2
	v_cvt_u32_f32_e32 v3, v3
	v_lshl_add_u64 v[0:1], v[0:1], 3, s[0:1]
	global_atomic_add_x2 v[0:1], v[2:3], off
	s_branch .LBB0_384
.Lres_a_last:
	s_waitcnt vmcnt(0)
	s_branch .LBB0_395

; #define TILE_RC(w_, brow_, bcol_) do { const int wg_ = ((w_) & 7) * qx + ((w_) >> 3); const int gid_ = wg_ / nig; \
;     brow_ = (gid_ * 8 + ((wg_ % nig) & 7)) * 256; bcol_ = ((wg_ % nig) >> 3) * 256; } while (0)
; #define ISSUE7(brow_, bcol_) do { \
;     STAGE_BX(SB_OFF(0, 0), 0, 0, bcol_); STAGE_AX(SA_OFF(0, 0), 0, 0, brow_); STAGE_BX(SB_OFF(0, 1), 1, 0, bcol_); STAGE_AX(SA_OFF(0, 1), 1, 0, brow_); \
;     STAGE_BX(SB_OFF(1, 0), 0, 1, bcol_); STAGE_AX(SA_OFF(1, 0), 0, 1, brow_); STAGE_BX(SB_OFF(1, 1), 1, 1, bcol_); } while (0)
; template <int EPI, int N, int K>
; __device__ __forceinline__ void gemm_phase(const bf16_t* __restrict__ A, const bf16_t* __restrict__ Bt, const EpiArgs ea) {
;     ...
;     const int c0 = bcol + wc * 64 + fr * 4;
;     const int wn = w + gridDim.x;
;     if (EPI == EPI_RES) {
;       if (wn < nwg) { int nbrow, nbcol; TILE_RC(wn, nbrow, nbcol); ISSUE7(nbrow, nbcol); }
; #pragma unroll
;       for (int ai = 0; ai < 2; ++ai)
; #pragma unroll
;         for (int m = 0; m < 4; ++m)
; #pragma unroll
;           for (int j = 0; j < 4; ++j) {
;             const int row = brow + ai * 128 + wr * 64 + m * 16 + fq * 4 + j;
;             const u32x2 x2 = *(const u32x2*)(ea.outb + (size_t)row * DM + c0);
.LBB0_571:
	s_or_b64 exec, exec, s[2:3]
	s_and_b32 s2, s10, 0xffffff00
	v_readlane_b32 vcc_lo, v236, 14
	v_readlane_b32 vcc_hi, v236, 15
	v_add_u32_e32 v226, s29, v146
	v_add_u32_e32 v227, s2, v145
	v_lshlrev_b32_e32 v226, 12, v226
	v_lshl_add_u32 v226, v227, 1, v226
	s_nop 3
	global_load_dwordx2 v[162:163], v226, vcc
	v_add_u32_e32 v227, 0x1000, v226
	global_load_dwordx2 v[164:165], v227, vcc
	v_add_u32_e32 v228, 0x2000, v226
	global_load_dwordx2 v[166:167], v228, vcc
	v_add_u32_e32 v227, 0x3000, v226
	global_load_dwordx2 v[168:169], v227, vcc
	v_add_u32_e32 v228, 0x10000, v226
	global_load_dwordx2 v[170:171], v228, vcc
	v_add_u32_e32 v227, 0x11000, v226
	global_load_dwordx2 v[172:173], v227, vcc
	v_add_u32_e32 v228, 0x12000, v226
	global_load_dwordx2 v[174:175], v228, vcc
	v_add_u32_e32 v227, 0x13000, v226
	global_load_dwordx2 v[176:177], v227, vcc
	v_add_u32_e32 v228, 0x20000, v226
	global_load_dwordx2 v[178:179], v228, vcc
	v_add_u32_e32 v227, 0x21000, v226
	global_load_dwordx2 v[180:181], v227, vcc
	v_add_u32_e32 v228, 0x22000, v226
	global_load_dwordx2 v[182:183], v228, vcc
	v_add_u32_e32 v227, 0x23000, v226
	global_load_dwordx2 v[184:185], v227, vcc
	v_add_u32_e32 v228, 0x30000, v226
	global_load_dwordx2 v[186:187], v228, vcc
	v_add_u32_e32 v227, 0x31000, v226
	global_load_dwordx2 v[188:189], v227, vcc
	v_add_u32_e32 v228, 0x32000, v226
	global_load_dwordx2 v[190:191], v228, vcc
	v_add_u32_e32 v227, 0x33000, v226
	global_load_dwordx2 v[192:193], v227, vcc
	v_add_u32_e32 v228, 0x80000, v226
	global_load_dwordx2 v[194:195], v228, vcc
	v_add_u32_e32 v227, 0x81000, v226
	global_load_dwordx2 v[196:197], v227, vcc
	v_add_u32_e32 v228, 0x82000, v226
	global_load_dwordx2 v[198:199], v228, vcc
	v_add_u32_e32 v227, 0x83000, v226
	global_load_dwordx2 v[200:201], v227, vcc
	v_add_u32_e32 v228, 0x90000, v226
	global_load_dwordx2 v[202:203], v228, vcc
	v_add_u32_e32 v227, 0x91000, v226
	global_load_dwordx2 v[204:205], v227, vcc
	v_add_u32_e32 v228, 0x92000, v226
	global_load_dwordx2 v[206:207], v228, vcc
	v_add_u32_e32 v227, 0x93000, v226
	global_load_dwordx2 v[208:209], v227, vcc
	v_add_u32_e32 v228, 0xa0000, v226
	global_load_dwordx2 v[210:211], v228, vcc
	v_add_u32_e32 v227, 0xa1000, v226
	global_load_dwordx2 v[212:213], v227, vcc
	v_add_u32_e32 v228, 0xa2000, v226
	global_load_dwordx2 v[214:215], v228, vcc
	v_add_u32_e32 v227, 0xa3000, v226
	global_load_dwordx2 v[216:217], v227, vcc
	v_add_u32_e32 v228, 0xb0000, v226
	global_load_dwordx2 v[218:219], v228, vcc
	v_add_u32_e32 v227, 0xb1000, v226
	global_load_dwordx2 v[220:221], v227, vcc
	v_add_u32_e32 v228, 0xb2000, v226
	global_load_dwordx2 v[222:223], v228, vcc
	v_add_u32_e32 v227, 0xb3000, v226
	global_load_dwordx2 v[224:225], v227, vcc
	s_add_i32 s28, s28, s33
	s_cmpk_gt_i32 s28, 0x1ff
	s_cselect_b64 s[10:11], -1, 0
	s_and_b64 vcc, exec, s[10:11]
	s_cbranch_vccnz .Lres_b_last
	s_lshl_b32 s3, s28, 6
	s_and_b32 s3, s3, 0x1c0
	s_ashr_i32 s30, s28, 3
	s_add_i32 s3, s3, s30
	s_ashr_i32 s30, s3, 31
	s_lshr_b32 s30, s30, 26
	s_add_i32 s30, s3, s30
	s_and_b32 s31, s30, 0xffffffc0
	s_sub_i32 s3, s3, s31
	s_lshl_b32 s30, s30, 19
	s_lshl_b32 s31, s3, 22
	s_lshl_b32 s3, s3, 19
	s_and_b32 s30, s30, 0xfe000000
	s_and_b32 s31, s31, 0x1c00000
	s_and_b32 s3, s3, 0xffc00000
	s_mov_b32 m0, s13
	s_nop 0
	buffer_load_dwordx4 v144, s[80:83], s3 offen lds
	s_or_b32 s30, s31, s30
	s_or_b32 s31, s3, 0x200000
	s_mov_b32 m0, s14
	s_nop 0
	buffer_load_dwordx4 v144, s[80:83], s31 offen lds
	s_or_b32 s31, s30, 0x100000
	s_mov_b32 m0, s12
	s_nop 0
	buffer_load_dwordx4 v131, s[64:67], s30 offen lds
	s_nop 0
	s_mov_b32 m0, s15
	s_nop 0
	buffer_load_dwordx4 v131, s[64:67], s31 offen lds
	s_or_b32 s31, s3, 0x8000
	s_mov_b32 m0, s16
	s_nop 0
	buffer_load_dwordx4 v144, s[80:83], s31 offen lds
	s_or_b32 s31, s3, 0x208000
	s_mov_b32 m0, s17
	s_nop 0
	buffer_load_dwordx4 v144, s[80:83], s31 offen lds
	s_or_b32 s31, s30, 0x200000
	s_mov_b32 m0, s18
	s_nop 0
	buffer_load_dwordx4 v131, s[64:67], s31 offen lds
	s_or_b32 s31, s30, 0x300000
	s_mov_b32 m0, s19
	s_nop 0
	buffer_load_dwordx4 v131, s[64:67], s31 offen lds
	s_or_b32 s31, s3, 0x80
	s_mov_b32 m0, s20
	s_nop 0
	buffer_load_dwordx4 v144, s[80:83], s31 offen lds
	s_or_b32 s31, s3, 0x200080
	s_mov_b32 m0, s21
	s_nop 0
	buffer_load_dwordx4 v144, s[80:83], s31 offen lds
	s_or_b32 s31, s30, 0x80
	s_mov_b32 m0, s22
	s_nop 0
	buffer_load_dwordx4 v131, s[64:67], s31 offen lds
	s_or_b32 s30, s30, 0x100080
	s_mov_b32 m0, s23
	s_nop 0
	buffer_load_dwordx4 v131, s[64:67], s30 offen lds
	s_or_b32 s30, s3, 0x8080
	s_mov_b32 m0, s24
	s_nop 0
	buffer_load_dwordx4 v144, s[80:83], s30 offen lds
	s_or_b32 s3, s3, 0x208080
	s_mov_b32 m0, s25
	s_nop 0
	buffer_load_dwordx4 v144, s[80:83], s3 offen lds
	s_waitcnt vmcnt(14)
; __device__ __forceinline__ float row16_sum(float v) { DPP_ADD(v, 0x128); DPP_ADD(v, 0x124); DPP_ADD(v, 0x122); DPP_ADD(v, 0x121); return v; }
; template <int EPI, int N, int K>
; __device__ __forceinline__ void gemm_phase(const bf16_t* __restrict__ A, const bf16_t* __restrict__ Bt, const EpiArgs ea) {
;     ...
;           for (int j = 0; j < 4; ++j) {
;             const int row = brow + ai * 128 + wr * 64 + m * 16 + fq * 4 + j;
;             const u32x2 x2 = *(const u32x2*)(ea.outb + (size_t)row * DM + c0);
;             float4 xn;
;             xn.x = __builtin_bit_cast(float, x2[0] << 16) + acc[ai][0][m][0][j]; xn.y = __builtin_bit_cast(float, x2[0] & 0xffff0000u) + acc[ai][0][m][1][j];
;             xn.z = __builtin_bit_cast(float, x2[1] << 16) + acc[ai][1][m][0][j]; xn.w = __builtin_bit_cast(float, x2[1] & 0xffff0000u) + acc[ai][1][m][1][j];
;             u32x2 o = {pk2(xn.x, xn.y), pk2(xn.z, xn.w)};
;             st_wt(ea.outb + (size_t)row * DM + c0, o);
;             float ss = xn.x * xn.x + xn.y * xn.y + xn.z * xn.z + xn.w * xn.w;
;             ss = row16_sum(ss);
;             if (fr == 0) __hip_atomic_fetch_add(ea.rowsq_out + row, (rsq_t)(ss * RSQ_SCALE), __ATOMIC_RELAXED, __HIP_MEMORY_SCOPE_AGENT);
.LBB0_573:
	v_add_u32_e32 v134, s2, v145
	v_add_u32_e32 v132, s29, v146
	v_readlane_b32 s2, v236, 14
	v_ashrrev_i32_e32 v135, 31, v134
	v_readlane_b32 s3, v236, 15
	v_ashrrev_i32_e32 v133, 31, v132
	v_lshlrev_b64 v[136:137], 12, v[132:133]
	v_lshl_add_u64 v[134:135], v[134:135], 1, s[2:3]
	v_lshl_add_u64 v[136:137], v[134:135], 0, v[136:137]
	v_mov_b32_e32 v160, v116
	v_mov_b32_e32 v161, v112
	v_mov_b32_e32 v116, 0
	v_mov_b32_e32 v156, v162
	v_mov_b32_e32 v157, v163
	v_lshlrev_b32_e32 v158, 16, v156
	v_and_b32_e32 v159, 0xffff0000, v156
	v_pk_add_f32 v[158:159], v[160:161], v[158:159]
	v_lshlrev_b32_e32 v156, 16, v157
	v_and_b32_e32 v157, 0xffff0000, v157
	v_mov_b32_e32 v160, v124
	v_mov_b32_e32 v161, v120
	v_pk_add_f32 v[156:157], v[160:161], v[156:157]
	v_cvt_pk_bf16_f32 v160, v158, v159
	v_cvt_pk_bf16_f32 v161, v156, v157
	global_store_dwordx2 v[136:137], v[160:161], off sc1
	v_pk_mul_f32 v[136:137], v[158:159], v[158:159]
	v_pk_mul_f32 v[156:157], v[156:157], v[156:157]
	v_add_f32_e32 v112, v136, v137
	v_add_f32_e32 v112, v156, v112
	v_add_f32_e32 v112, v157, v112
	s_nop 1
	v_add_f32_dpp v112, v112, v112 row_ror:8 row_mask:0xf bank_mask:0xf bound_ctrl:1
	s_nop 1
	v_add_f32_dpp v112, v112, v112 row_ror:4 row_mask:0xf bank_mask:0xf bound_ctrl:1
	s_nop 1
	v_add_f32_dpp v112, v112, v112 row_ror:2 row_mask:0xf bank_mask:0xf bound_ctrl:1
	s_nop 1
	v_mov_b32_dpp v116, v112 row_ror:1 row_mask:0xf bank_mask:0xf
	s_and_saveexec_b64 s[2:3], s[8:9]
	s_cbranch_execz .LBB0_575
	v_add_f32_e32 v112, v112, v116
	v_mul_f32_e32 v112, 0x49800000, v112
	v_trunc_f32_e32 v112, v112
	v_mul_f32_e32 v116, 0x2f800000, v112
	v_floor_f32_e32 v116, v116
	v_fmac_f32_e32 v112, 0xcf800000, v116
	v_cvt_u32_f32_e32 v136, v112
	v_cvt_u32_f32_e32 v137, v116
	v_lshl_add_u64 v[156:157], v[132:133], 3, s[0:1]
	global_atomic_add_x2 v[156:157], v[136:137], off
.LBB0_575:
	s_or_b64 exec, exec, s[2:3]
	v_add_u32_e32 v136, 1, v132
	v_ashrrev_i32_e32 v137, 31, v136
	v_lshlrev_b64 v[156:157], 12, v[136:137]
	v_lshl_add_u64 v[156:157], v[134:135], 0, v[156:157]
	v_mov_b32_e32 v112, v117
	v_mov_b32_e32 v120, v125
	v_mov_b32_e32 v158, v164
	v_mov_b32_e32 v159, v165
	v_lshlrev_b32_e32 v160, 16, v158
	v_and_b32_e32 v161, 0xffff0000, v158
	v_pk_add_f32 v[112:113], v[112:113], v[160:161]
	v_lshlrev_b32_e32 v116, 16, v159
	v_and_b32_e32 v117, 0xffff0000, v159
	v_pk_add_f32 v[116:117], v[120:121], v[116:117]
	v_cvt_pk_bf16_f32 v120, v112, v113
	v_pk_mul_f32 v[112:113], v[112:113], v[112:113]
	v_cvt_pk_bf16_f32 v121, v116, v117
	v_pk_mul_f32 v[116:117], v[116:117], v[116:117]
	v_add_f32_e32 v112, v112, v113
	v_add_f32_e32 v112, v116, v112
	v_add_f32_e32 v112, v117, v112
	v_mov_b32_e32 v113, 0
	global_store_dwordx2 v[156:157], v[120:121], off sc1
	v_add_f32_dpp v112, v112, v112 row_ror:8 row_mask:0xf bank_mask:0xf bound_ctrl:1
	s_nop 1
	v_add_f32_dpp v112, v112, v112 row_ror:4 row_mask:0xf bank_mask:0xf bound_ctrl:1
	s_nop 1
	v_add_f32_dpp v112, v112, v112 row_ror:2 row_mask:0xf bank_mask:0xf bound_ctrl:1
	s_nop 1
	v_mov_b32_dpp v113, v112 row_ror:1 row_mask:0xf bank_mask:0xf
	s_and_saveexec_b64 s[2:3], s[8:9]
	s_cbranch_execz .LBB0_577
	v_add_f32_e32 v112, v112, v113
	v_mul_f32_e32 v112, 0x49800000, v112
	v_trunc_f32_e32 v112, v112
	v_mul_f32_e32 v113, 0x2f800000, v112
	v_floor_f32_e32 v113, v113
	v_fmac_f32_e32 v112, 0xcf800000, v113
	v_cvt_u32_f32_e32 v112, v112
	v_cvt_u32_f32_e32 v113, v113
	v_lshl_add_u64 v[116:117], v[136:137], 3, s[0:1]
	global_atomic_add_x2 v[116:117], v[112:113], off
.LBB0_577:
	s_or_b64 exec, exec, s[2:3]
	v_add_u32_e32 v112, 2, v132
	v_ashrrev_i32_e32 v113, 31, v112
	v_lshlrev_b64 v[116:117], 12, v[112:113]
	v_lshl_add_u64 v[116:117], v[134:135], 0, v[116:117]
	v_mov_b32_e32 v136, v118
	v_mov_b32_e32 v137, v114
	v_mov_b32_e32 v120, v166
	v_mov_b32_e32 v121, v167
	v_lshlrev_b32_e32 v124, 16, v120
	v_and_b32_e32 v125, 0xffff0000, v120
	v_pk_add_f32 v[124:125], v[136:137], v[124:125]
	v_lshlrev_b32_e32 v120, 16, v121
	v_and_b32_e32 v121, 0xffff0000, v121
	v_mov_b32_e32 v136, v126
	v_mov_b32_e32 v137, v122
	v_pk_add_f32 v[120:121], v[136:137], v[120:121]
	v_cvt_pk_bf16_f32 v136, v124, v125
	v_cvt_pk_bf16_f32 v137, v120, v121
	global_store_dwordx2 v[116:117], v[136:137], off sc1
	v_pk_mul_f32 v[116:117], v[124:125], v[124:125]
	v_pk_mul_f32 v[120:121], v[120:121], v[120:121]
	v_add_f32_e32 v114, v116, v117
	v_add_f32_e32 v114, v120, v114
	v_add_f32_e32 v114, v121, v114
	v_mov_b32_e32 v116, 0
	s_nop 0
	v_add_f32_dpp v114, v114, v114 row_ror:8 row_mask:0xf bank_mask:0xf bound_ctrl:1
	s_nop 1
	v_add_f32_dpp v114, v114, v114 row_ror:4 row_mask:0xf bank_mask:0xf bound_ctrl:1
	s_nop 1
	v_add_f32_dpp v114, v114, v114 row_ror:2 row_mask:0xf bank_mask:0xf bound_ctrl:1
	s_nop 1
	v_mov_b32_dpp v116, v114 row_ror:1 row_mask:0xf bank_mask:0xf
	s_and_saveexec_b64 s[2:3], s[8:9]
	s_cbranch_execz .LBB0_579
	v_add_f32_e32 v114, v114, v116
	v_mul_f32_e32 v114, 0x49800000, v114
	v_trunc_f32_e32 v114, v114
	v_mul_f32_e32 v116, 0x2f800000, v114
	v_floor_f32_e32 v117, v116
	v_fmac_f32_e32 v114, 0xcf800000, v117
	v_cvt_u32_f32_e32 v116, v114
	v_cvt_u32_f32_e32 v117, v117
	v_lshl_add_u64 v[112:113], v[112:113], 3, s[0:1]
	global_atomic_add_x2 v[112:113], v[116:117], off
; __device__ __forceinline__ float row16_sum(float v) { DPP_ADD(v, 0x128); DPP_ADD(v, 0x124); DPP_ADD(v, 0x122); DPP_ADD(v, 0x121); return v; }
; template <int EPI, int N, int K>
; __device__ __forceinline__ void gemm_phase(const bf16_t* __restrict__ A, const bf16_t* __restrict__ Bt, const EpiArgs ea) {
;     ...
;           for (int j = 0; j < 4; ++j) {
;             const int row = brow + ai * 128 + wr * 64 + m * 16 + fq * 4 + j;
;             const u32x2 x2 = *(const u32x2*)(ea.outb + (size_t)row * DM + c0);
;             float4 xn;
;             xn.x = __builtin_bit_cast(float, x2[0] << 16) + acc[ai][0][m][0][j]; xn.y = __builtin_bit_cast(float, x2[0] & 0xffff0000u) + acc[ai][0][m][1][j];
;             xn.z = __builtin_bit_cast(float, x2[1] << 16) + acc[ai][1][m][0][j]; xn.w = __builtin_bit_cast(float, x2[1] & 0xffff0000u) + acc[ai][1][m][1][j];
;             u32x2 o = {pk2(xn.x, xn.y), pk2(xn.z, xn.w)};
;             st_wt(ea.outb + (size_t)row * DM + c0, o);
;             float ss = xn.x * xn.x + xn.y * xn.y + xn.z * xn.z + xn.w * xn.w;
;             ss = row16_sum(ss);
;             if (fr == 0) __hip_atomic_fetch_add(ea.rowsq_out + row, (rsq_t)(ss * RSQ_SCALE), __ATOMIC_RELAXED, __HIP_MEMORY_SCOPE_AGENT);
.LBB0_579:
	s_or_b64 exec, exec, s[2:3]
	v_add_u32_e32 v112, 3, v132
	v_ashrrev_i32_e32 v113, 31, v112
	v_lshlrev_b64 v[116:117], 12, v[112:113]
	v_lshl_add_u64 v[116:117], v[134:135], 0, v[116:117]
	v_mov_b32_e32 v114, v119
	v_mov_b32_e32 v122, v127
	v_mov_b32_e32 v120, v168
	v_mov_b32_e32 v121, v169
	v_lshlrev_b32_e32 v118, 16, v120
	v_and_b32_e32 v119, 0xffff0000, v120
	v_lshlrev_b32_e32 v120, 16, v121
	v_and_b32_e32 v121, 0xffff0000, v121
	v_pk_add_f32 v[114:115], v[114:115], v[118:119]
	v_pk_add_f32 v[118:119], v[122:123], v[120:121]
	v_cvt_pk_bf16_f32 v120, v114, v115
	v_pk_mul_f32 v[114:115], v[114:115], v[114:115]
	v_cvt_pk_bf16_f32 v121, v118, v119
	v_pk_mul_f32 v[118:119], v[118:119], v[118:119]
	v_add_f32_e32 v114, v114, v115
	v_add_f32_e32 v114, v118, v114
	v_add_f32_e32 v114, v119, v114
	v_mov_b32_e32 v115, 0
	global_store_dwordx2 v[116:117], v[120:121], off sc1
	v_add_f32_dpp v114, v114, v114 row_ror:8 row_mask:0xf bank_mask:0xf bound_ctrl:1
	s_nop 1
	v_add_f32_dpp v114, v114, v114 row_ror:4 row_mask:0xf bank_mask:0xf bound_ctrl:1
	s_nop 1
	v_add_f32_dpp v114, v114, v114 row_ror:2 row_mask:0xf bank_mask:0xf bound_ctrl:1
	s_nop 1
	v_mov_b32_dpp v115, v114 row_ror:1 row_mask:0xf bank_mask:0xf
	s_and_saveexec_b64 s[2:3], s[8:9]
	s_cbranch_execz .LBB0_581
	v_add_f32_e32 v114, v114, v115
	v_mul_f32_e32 v114, 0x49800000, v114
	v_trunc_f32_e32 v114, v114
	v_mul_f32_e32 v115, 0x2f800000, v114
	v_floor_f32_e32 v115, v115
	v_fmac_f32_e32 v114, 0xcf800000, v115
	v_cvt_u32_f32_e32 v114, v114
	v_cvt_u32_f32_e32 v115, v115
	v_lshl_add_u64 v[112:113], v[112:113], 3, s[0:1]
	global_atomic_add_x2 v[112:113], v[114:115], off
.LBB0_581:
	s_or_b64 exec, exec, s[2:3]
	v_add_u32_e32 v112, 16, v132
	v_ashrrev_i32_e32 v113, 31, v112
	v_lshlrev_b64 v[114:115], 12, v[112:113]
	v_lshl_add_u64 v[114:115], v[134:135], 0, v[114:115]
	v_mov_b32_e32 v120, v100
	v_mov_b32_e32 v121, v96
	v_mov_b32_e32 v100, 0
	v_mov_b32_e32 v116, v170
	v_mov_b32_e32 v117, v171
	v_lshlrev_b32_e32 v118, 16, v116
	v_and_b32_e32 v119, 0xffff0000, v116
	v_pk_add_f32 v[118:119], v[120:121], v[118:119]
	v_lshlrev_b32_e32 v116, 16, v117
	v_and_b32_e32 v117, 0xffff0000, v117
	v_mov_b32_e32 v120, v108
	v_mov_b32_e32 v121, v104
	v_pk_add_f32 v[116:117], v[120:121], v[116:117]
	v_cvt_pk_bf16_f32 v120, v118, v119
	v_cvt_pk_bf16_f32 v121, v116, v117
	global_store_dwordx2 v[114:115], v[120:121], off sc1
	v_pk_mul_f32 v[114:115], v[118:119], v[118:119]
	v_pk_mul_f32 v[116:117], v[116:117], v[116:117]
	v_add_f32_e32 v96, v114, v115
	v_add_f32_e32 v96, v116, v96
	v_add_f32_e32 v96, v117, v96
	s_nop 1
	v_add_f32_dpp v96, v96, v96 row_ror:8 row_mask:0xf bank_mask:0xf bound_ctrl:1
	s_nop 1
	v_add_f32_dpp v96, v96, v96 row_ror:4 row_mask:0xf bank_mask:0xf bound_ctrl:1
	s_nop 1
	v_add_f32_dpp v96, v96, v96 row_ror:2 row_mask:0xf bank_mask:0xf bound_ctrl:1
	s_nop 1
	v_mov_b32_dpp v100, v96 row_ror:1 row_mask:0xf bank_mask:0xf
	s_and_saveexec_b64 s[2:3], s[8:9]
	s_cbranch_execz .LBB0_583
	v_add_f32_e32 v96, v96, v100
	v_mul_f32_e32 v96, 0x49800000, v96
	v_trunc_f32_e32 v96, v96
	v_mul_f32_e32 v100, 0x2f800000, v96
	v_floor_f32_e32 v100, v100
	v_fmac_f32_e32 v96, 0xcf800000, v100
	v_cvt_u32_f32_e32 v114, v96
	v_cvt_u32_f32_e32 v115, v100
	v_lshl_add_u64 v[112:113], v[112:113], 3, s[0:1]
	global_atomic_add_x2 v[112:113], v[114:115], off
.LBB0_583:
	s_or_b64 exec, exec, s[2:3]
	v_add_u32_e32 v112, 17, v132
	v_ashrrev_i32_e32 v113, 31, v112
	v_lshlrev_b64 v[114:115], 12, v[112:113]
	v_lshl_add_u64 v[114:115], v[134:135], 0, v[114:115]
	v_mov_b32_e32 v96, v101
	v_mov_b32_e32 v104, v109
	v_mov_b32_e32 v116, v172
	v_mov_b32_e32 v117, v173
	v_lshlrev_b32_e32 v118, 16, v116
	v_and_b32_e32 v119, 0xffff0000, v116
	v_pk_add_f32 v[96:97], v[96:97], v[118:119]
	v_lshlrev_b32_e32 v100, 16, v117
	v_and_b32_e32 v101, 0xffff0000, v117
	v_pk_add_f32 v[100:101], v[104:105], v[100:101]
	v_cvt_pk_bf16_f32 v104, v96, v97
	v_pk_mul_f32 v[96:97], v[96:97], v[96:97]
	v_cvt_pk_bf16_f32 v105, v100, v101
	v_pk_mul_f32 v[100:101], v[100:101], v[100:101]
	v_add_f32_e32 v96, v96, v97
	v_add_f32_e32 v96, v100, v96
	v_add_f32_e32 v96, v101, v96
	v_mov_b32_e32 v97, 0
	global_store_dwordx2 v[114:115], v[104:105], off sc1
	v_add_f32_dpp v96, v96, v96 row_ror:8 row_mask:0xf bank_mask:0xf bound_ctrl:1
	s_nop 1
	v_add_f32_dpp v96, v96, v96 row_ror:4 row_mask:0xf bank_mask:0xf bound_ctrl:1
	s_nop 1
	v_add_f32_dpp v96, v96, v96 row_ror:2 row_mask:0xf bank_mask:0xf bound_ctrl:1
	s_nop 1
	v_mov_b32_dpp v97, v96 row_ror:1 row_mask:0xf bank_mask:0xf
	s_and_saveexec_b64 s[2:3], s[8:9]
	s_cbranch_execz .LBB0_585
	v_add_f32_e32 v96, v96, v97
	v_mul_f32_e32 v96, 0x49800000, v96
	v_trunc_f32_e32 v96, v96
	v_mul_f32_e32 v97, 0x2f800000, v96
	v_floor_f32_e32 v97, v97
	v_fmac_f32_e32 v96, 0xcf800000, v97
	v_cvt_u32_f32_e32 v96, v96
	v_cvt_u32_f32_e32 v97, v97
	v_lshl_add_u64 v[100:101], v[112:113], 3, s[0:1]
	global_atomic_add_x2 v[100:101], v[96:97], off
; __device__ __forceinline__ float row16_sum(float v) { DPP_ADD(v, 0x128); DPP_ADD(v, 0x124); DPP_ADD(v, 0x122); DPP_ADD(v, 0x121); return v; }
; template <int EPI, int N, int K>
; __device__ __forceinline__ void gemm_phase(const bf16_t* __restrict__ A, const bf16_t* __restrict__ Bt, const EpiArgs ea) {
;     ...
;           for (int j = 0; j < 4; ++j) {
;             const int row = brow + ai * 128 + wr * 64 + m * 16 + fq * 4 + j;
;             const u32x2 x2 = *(const u32x2*)(ea.outb + (size_t)row * DM + c0);
;             float4 xn;
;             xn.x = __builtin_bit_cast(float, x2[0] << 16) + acc[ai][0][m][0][j]; xn.y = __builtin_bit_cast(float, x2[0] & 0xffff0000u) + acc[ai][0][m][1][j];
;             xn.z = __builtin_bit_cast(float, x2[1] << 16) + acc[ai][1][m][0][j]; xn.w = __builtin_bit_cast(float, x2[1] & 0xffff0000u) + acc[ai][1][m][1][j];
;             u32x2 o = {pk2(xn.x, xn.y), pk2(xn.z, xn.w)};
;             st_wt(ea.outb + (size_t)row * DM + c0, o);
;             float ss = xn.x * xn.x + xn.y * xn.y + xn.z * xn.z + xn.w * xn.w;
;             ss = row16_sum(ss);
;             if (fr == 0) __hip_atomic_fetch_add(ea.rowsq_out + row, (rsq_t)(ss * RSQ_SCALE), __ATOMIC_RELAXED, __HIP_MEMORY_SCOPE_AGENT);
.LBB0_585:
	s_or_b64 exec, exec, s[2:3]
	v_add_u32_e32 v96, 18, v132
	v_ashrrev_i32_e32 v97, 31, v96
	v_lshlrev_b64 v[100:101], 12, v[96:97]
	v_lshl_add_u64 v[100:101], v[134:135], 0, v[100:101]
	v_mov_b32_e32 v112, v102
	v_mov_b32_e32 v113, v98
	v_mov_b32_e32 v104, v174
	v_mov_b32_e32 v105, v175
	v_lshlrev_b32_e32 v108, 16, v104
	v_and_b32_e32 v109, 0xffff0000, v104
	v_pk_add_f32 v[108:109], v[112:113], v[108:109]
	v_lshlrev_b32_e32 v104, 16, v105
	v_and_b32_e32 v105, 0xffff0000, v105
	v_mov_b32_e32 v112, v110
	v_mov_b32_e32 v113, v106
	v_pk_add_f32 v[104:105], v[112:113], v[104:105]
	v_cvt_pk_bf16_f32 v112, v108, v109
	v_cvt_pk_bf16_f32 v113, v104, v105
	global_store_dwordx2 v[100:101], v[112:113], off sc1
	v_pk_mul_f32 v[100:101], v[108:109], v[108:109]
	v_pk_mul_f32 v[104:105], v[104:105], v[104:105]
	v_add_f32_e32 v98, v100, v101
	v_add_f32_e32 v98, v104, v98
	v_add_f32_e32 v98, v105, v98
	v_mov_b32_e32 v100, 0
	s_nop 0
	v_add_f32_dpp v98, v98, v98 row_ror:8 row_mask:0xf bank_mask:0xf bound_ctrl:1
	s_nop 1
	v_add_f32_dpp v98, v98, v98 row_ror:4 row_mask:0xf bank_mask:0xf bound_ctrl:1
	s_nop 1
	v_add_f32_dpp v98, v98, v98 row_ror:2 row_mask:0xf bank_mask:0xf bound_ctrl:1
	s_nop 1
	v_mov_b32_dpp v100, v98 row_ror:1 row_mask:0xf bank_mask:0xf
	s_and_saveexec_b64 s[2:3], s[8:9]
	s_cbranch_execz .LBB0_587
	v_add_f32_e32 v98, v98, v100
	v_mul_f32_e32 v98, 0x49800000, v98
	v_trunc_f32_e32 v98, v98
	v_mul_f32_e32 v100, 0x2f800000, v98
	v_floor_f32_e32 v101, v100
	v_fmac_f32_e32 v98, 0xcf800000, v101
	v_cvt_u32_f32_e32 v100, v98
	v_cvt_u32_f32_e32 v101, v101
	v_lshl_add_u64 v[96:97], v[96:97], 3, s[0:1]
	global_atomic_add_x2 v[96:97], v[100:101], off
.LBB0_587:
	s_or_b64 exec, exec, s[2:3]
	v_add_u32_e32 v96, 19, v132
	v_ashrrev_i32_e32 v97, 31, v96
	v_lshlrev_b64 v[100:101], 12, v[96:97]
	v_lshl_add_u64 v[100:101], v[134:135], 0, v[100:101]
	v_mov_b32_e32 v98, v103
	v_mov_b32_e32 v106, v111
	v_mov_b32_e32 v104, v176
	v_mov_b32_e32 v105, v177
	v_lshlrev_b32_e32 v102, 16, v104
	v_and_b32_e32 v103, 0xffff0000, v104
	v_lshlrev_b32_e32 v104, 16, v105
	v_and_b32_e32 v105, 0xffff0000, v105
	v_pk_add_f32 v[98:99], v[98:99], v[102:103]
	v_pk_add_f32 v[102:103], v[106:107], v[104:105]
	v_cvt_pk_bf16_f32 v104, v98, v99
	v_pk_mul_f32 v[98:99], v[98:99], v[98:99]
	v_cvt_pk_bf16_f32 v105, v102, v103
	v_pk_mul_f32 v[102:103], v[102:103], v[102:103]
	v_add_f32_e32 v98, v98, v99
	v_add_f32_e32 v98, v102, v98
	v_add_f32_e32 v98, v103, v98
	v_mov_b32_e32 v99, 0
	global_store_dwordx2 v[100:101], v[104:105], off sc1
	v_add_f32_dpp v98, v98, v98 row_ror:8 row_mask:0xf bank_mask:0xf bound_ctrl:1
	s_nop 1
	v_add_f32_dpp v98, v98, v98 row_ror:4 row_mask:0xf bank_mask:0xf bound_ctrl:1
	s_nop 1
	v_add_f32_dpp v98, v98, v98 row_ror:2 row_mask:0xf bank_mask:0xf bound_ctrl:1
	s_nop 1
	v_mov_b32_dpp v99, v98 row_ror:1 row_mask:0xf bank_mask:0xf
	s_and_saveexec_b64 s[2:3], s[8:9]
	s_cbranch_execz .LBB0_589
	v_add_f32_e32 v98, v98, v99
	v_mul_f32_e32 v98, 0x49800000, v98
	v_trunc_f32_e32 v98, v98
	v_mul_f32_e32 v99, 0x2f800000, v98
	v_floor_f32_e32 v99, v99
	v_fmac_f32_e32 v98, 0xcf800000, v99
	v_cvt_u32_f32_e32 v98, v98
	v_cvt_u32_f32_e32 v99, v99
	v_lshl_add_u64 v[96:97], v[96:97], 3, s[0:1]
	global_atomic_add_x2 v[96:97], v[98:99], off
.LBB0_589:
	s_or_b64 exec, exec, s[2:3]
	v_add_u32_e32 v96, 32, v132
	v_ashrrev_i32_e32 v97, 31, v96
	v_lshlrev_b64 v[98:99], 12, v[96:97]
	v_lshl_add_u64 v[98:99], v[134:135], 0, v[98:99]
	v_mov_b32_e32 v104, v84
	v_mov_b32_e32 v105, v80
	v_mov_b32_e32 v84, 0
	v_mov_b32_e32 v100, v178
	v_mov_b32_e32 v101, v179
	v_lshlrev_b32_e32 v102, 16, v100
	v_and_b32_e32 v103, 0xffff0000, v100
	v_pk_add_f32 v[102:103], v[104:105], v[102:103]
	v_lshlrev_b32_e32 v100, 16, v101
	v_and_b32_e32 v101, 0xffff0000, v101
	v_mov_b32_e32 v104, v92
	v_mov_b32_e32 v105, v88
	v_pk_add_f32 v[100:101], v[104:105], v[100:101]
	v_cvt_pk_bf16_f32 v104, v102, v103
	v_cvt_pk_bf16_f32 v105, v100, v101
	global_store_dwordx2 v[98:99], v[104:105], off sc1
	v_pk_mul_f32 v[98:99], v[102:103], v[102:103]
	v_pk_mul_f32 v[100:101], v[100:101], v[100:101]
	v_add_f32_e32 v80, v98, v99
	v_add_f32_e32 v80, v100, v80
	v_add_f32_e32 v80, v101, v80
	s_nop 1
	v_add_f32_dpp v80, v80, v80 row_ror:8 row_mask:0xf bank_mask:0xf bound_ctrl:1
	s_nop 1
	v_add_f32_dpp v80, v80, v80 row_ror:4 row_mask:0xf bank_mask:0xf bound_ctrl:1
	s_nop 1
	v_add_f32_dpp v80, v80, v80 row_ror:2 row_mask:0xf bank_mask:0xf bound_ctrl:1
	s_nop 1
	v_mov_b32_dpp v84, v80 row_ror:1 row_mask:0xf bank_mask:0xf
	s_and_saveexec_b64 s[2:3], s[8:9]
	s_cbranch_execz .LBB0_591
	v_add_f32_e32 v80, v80, v84
	v_mul_f32_e32 v80, 0x49800000, v80
	v_trunc_f32_e32 v80, v80
	v_mul_f32_e32 v84, 0x2f800000, v80
	v_floor_f32_e32 v84, v84
	v_fmac_f32_e32 v80, 0xcf800000, v84
	v_cvt_u32_f32_e32 v98, v80
	v_cvt_u32_f32_e32 v99, v84
	v_lshl_add_u64 v[96:97], v[96:97], 3, s[0:1]
	global_atomic_add_x2 v[96:97], v[98:99], off
; __device__ __forceinline__ float row16_sum(float v) { DPP_ADD(v, 0x128); DPP_ADD(v, 0x124); DPP_ADD(v, 0x122); DPP_ADD(v, 0x121); return v; }
; template <int EPI, int N, int K>
; __device__ __forceinline__ void gemm_phase(const bf16_t* __restrict__ A, const bf16_t* __restrict__ Bt, const EpiArgs ea) {
;     ...
;           for (int j = 0; j < 4; ++j) {
;             const int row = brow + ai * 128 + wr * 64 + m * 16 + fq * 4 + j;
;             const u32x2 x2 = *(const u32x2*)(ea.outb + (size_t)row * DM + c0);
;             float4 xn;
;             xn.x = __builtin_bit_cast(float, x2[0] << 16) + acc[ai][0][m][0][j]; xn.y = __builtin_bit_cast(float, x2[0] & 0xffff0000u) + acc[ai][0][m][1][j];
;             xn.z = __builtin_bit_cast(float, x2[1] << 16) + acc[ai][1][m][0][j]; xn.w = __builtin_bit_cast(float, x2[1] & 0xffff0000u) + acc[ai][1][m][1][j];
;             u32x2 o = {pk2(xn.x, xn.y), pk2(xn.z, xn.w)};
;             st_wt(ea.outb + (size_t)row * DM + c0, o);
;             float ss = xn.x * xn.x + xn.y * xn.y + xn.z * xn.z + xn.w * xn.w;
;             ss = row16_sum(ss);
;             if (fr == 0) __hip_atomic_fetch_add(ea.rowsq_out + row, (rsq_t)(ss * RSQ_SCALE), __ATOMIC_RELAXED, __HIP_MEMORY_SCOPE_AGENT);
.LBB0_591:
	s_or_b64 exec, exec, s[2:3]
	v_add_u32_e32 v96, 33, v132
	v_ashrrev_i32_e32 v97, 31, v96
	v_lshlrev_b64 v[98:99], 12, v[96:97]
	v_lshl_add_u64 v[98:99], v[134:135], 0, v[98:99]
	v_mov_b32_e32 v80, v85
	v_mov_b32_e32 v88, v93
	v_mov_b32_e32 v100, v180
	v_mov_b32_e32 v101, v181
	v_lshlrev_b32_e32 v102, 16, v100
	v_and_b32_e32 v103, 0xffff0000, v100
	v_pk_add_f32 v[80:81], v[80:81], v[102:103]
	v_lshlrev_b32_e32 v84, 16, v101
	v_and_b32_e32 v85, 0xffff0000, v101
	v_pk_add_f32 v[84:85], v[88:89], v[84:85]
	v_cvt_pk_bf16_f32 v88, v80, v81
	v_pk_mul_f32 v[80:81], v[80:81], v[80:81]
	v_cvt_pk_bf16_f32 v89, v84, v85
	v_pk_mul_f32 v[84:85], v[84:85], v[84:85]
	v_add_f32_e32 v80, v80, v81
	v_add_f32_e32 v80, v84, v80
	v_add_f32_e32 v80, v85, v80
	v_mov_b32_e32 v81, 0
	global_store_dwordx2 v[98:99], v[88:89], off sc1
	v_add_f32_dpp v80, v80, v80 row_ror:8 row_mask:0xf bank_mask:0xf bound_ctrl:1
	s_nop 1
	v_add_f32_dpp v80, v80, v80 row_ror:4 row_mask:0xf bank_mask:0xf bound_ctrl:1
	s_nop 1
	v_add_f32_dpp v80, v80, v80 row_ror:2 row_mask:0xf bank_mask:0xf bound_ctrl:1
	s_nop 1
	v_mov_b32_dpp v81, v80 row_ror:1 row_mask:0xf bank_mask:0xf
	s_and_saveexec_b64 s[2:3], s[8:9]
	s_cbranch_execz .LBB0_593
	v_add_f32_e32 v80, v80, v81
	v_mul_f32_e32 v80, 0x49800000, v80
	v_trunc_f32_e32 v80, v80
	v_mul_f32_e32 v81, 0x2f800000, v80
	v_floor_f32_e32 v81, v81
	v_fmac_f32_e32 v80, 0xcf800000, v81
	v_cvt_u32_f32_e32 v80, v80
	v_cvt_u32_f32_e32 v81, v81
	v_lshl_add_u64 v[84:85], v[96:97], 3, s[0:1]
	global_atomic_add_x2 v[84:85], v[80:81], off
.LBB0_593:
	s_or_b64 exec, exec, s[2:3]
	v_add_u32_e32 v80, 34, v132
	v_ashrrev_i32_e32 v81, 31, v80
	v_lshlrev_b64 v[84:85], 12, v[80:81]
	v_lshl_add_u64 v[84:85], v[134:135], 0, v[84:85]
	v_mov_b32_e32 v96, v86
	v_mov_b32_e32 v97, v82
	v_mov_b32_e32 v88, v182
	v_mov_b32_e32 v89, v183
	v_lshlrev_b32_e32 v92, 16, v88
	v_and_b32_e32 v93, 0xffff0000, v88
	v_pk_add_f32 v[92:93], v[96:97], v[92:93]
	v_lshlrev_b32_e32 v88, 16, v89
	v_and_b32_e32 v89, 0xffff0000, v89
	v_mov_b32_e32 v96, v94
	v_mov_b32_e32 v97, v90
	v_pk_add_f32 v[88:89], v[96:97], v[88:89]
	v_cvt_pk_bf16_f32 v96, v92, v93
	v_cvt_pk_bf16_f32 v97, v88, v89
	global_store_dwordx2 v[84:85], v[96:97], off sc1
	v_pk_mul_f32 v[84:85], v[92:93], v[92:93]
	v_pk_mul_f32 v[88:89], v[88:89], v[88:89]
	v_add_f32_e32 v82, v84, v85
	v_add_f32_e32 v82, v88, v82
	v_add_f32_e32 v82, v89, v82
	v_mov_b32_e32 v84, 0
	s_nop 0
	v_add_f32_dpp v82, v82, v82 row_ror:8 row_mask:0xf bank_mask:0xf bound_ctrl:1
	s_nop 1
	v_add_f32_dpp v82, v82, v82 row_ror:4 row_mask:0xf bank_mask:0xf bound_ctrl:1
	s_nop 1
	v_add_f32_dpp v82, v82, v82 row_ror:2 row_mask:0xf bank_mask:0xf bound_ctrl:1
	s_nop 1
	v_mov_b32_dpp v84, v82 row_ror:1 row_mask:0xf bank_mask:0xf
	s_and_saveexec_b64 s[2:3], s[8:9]
	s_cbranch_execz .LBB0_595
	v_add_f32_e32 v82, v82, v84
	v_mul_f32_e32 v82, 0x49800000, v82
	v_trunc_f32_e32 v82, v82
	v_mul_f32_e32 v84, 0x2f800000, v82
	v_floor_f32_e32 v85, v84
	v_fmac_f32_e32 v82, 0xcf800000, v85
	v_cvt_u32_f32_e32 v84, v82
	v_cvt_u32_f32_e32 v85, v85
	v_lshl_add_u64 v[80:81], v[80:81], 3, s[0:1]
	global_atomic_add_x2 v[80:81], v[84:85], off
.LBB0_595:
	s_or_b64 exec, exec, s[2:3]
	v_add_u32_e32 v80, 35, v132
	v_ashrrev_i32_e32 v81, 31, v80
	v_lshlrev_b64 v[84:85], 12, v[80:81]
	v_lshl_add_u64 v[84:85], v[134:135], 0, v[84:85]
	v_mov_b32_e32 v82, v87
	v_mov_b32_e32 v90, v95
	v_mov_b32_e32 v88, v184
	v_mov_b32_e32 v89, v185
	v_lshlrev_b32_e32 v86, 16, v88
	v_and_b32_e32 v87, 0xffff0000, v88
	v_lshlrev_b32_e32 v88, 16, v89
	v_and_b32_e32 v89, 0xffff0000, v89
	v_pk_add_f32 v[82:83], v[82:83], v[86:87]
	v_pk_add_f32 v[86:87], v[90:91], v[88:89]
	v_cvt_pk_bf16_f32 v88, v82, v83
	v_pk_mul_f32 v[82:83], v[82:83], v[82:83]
	v_cvt_pk_bf16_f32 v89, v86, v87
	v_pk_mul_f32 v[86:87], v[86:87], v[86:87]
	v_add_f32_e32 v82, v82, v83
	v_add_f32_e32 v82, v86, v82
	v_add_f32_e32 v82, v87, v82
	v_mov_b32_e32 v83, 0
	global_store_dwordx2 v[84:85], v[88:89], off sc1
	v_add_f32_dpp v82, v82, v82 row_ror:8 row_mask:0xf bank_mask:0xf bound_ctrl:1
	s_nop 1
	v_add_f32_dpp v82, v82, v82 row_ror:4 row_mask:0xf bank_mask:0xf bound_ctrl:1
	s_nop 1
	v_add_f32_dpp v82, v82, v82 row_ror:2 row_mask:0xf bank_mask:0xf bound_ctrl:1
	s_nop 1
	v_mov_b32_dpp v83, v82 row_ror:1 row_mask:0xf bank_mask:0xf
	s_and_saveexec_b64 s[2:3], s[8:9]
	s_cbranch_execz .LBB0_597
	v_add_f32_e32 v82, v82, v83
	v_mul_f32_e32 v82, 0x49800000, v82
	v_trunc_f32_e32 v82, v82
	v_mul_f32_e32 v83, 0x2f800000, v82
	v_floor_f32_e32 v83, v83
	v_fmac_f32_e32 v82, 0xcf800000, v83
	v_cvt_u32_f32_e32 v82, v82
	v_cvt_u32_f32_e32 v83, v83
	v_lshl_add_u64 v[80:81], v[80:81], 3, s[0:1]
	global_atomic_add_x2 v[80:81], v[82:83], off
.LBB0_597:
	s_or_b64 exec, exec, s[2:3]
	v_add_u32_e32 v80, 48, v132
	v_ashrrev_i32_e32 v81, 31, v80
	v_lshlrev_b64 v[82:83], 12, v[80:81]
	v_lshl_add_u64 v[82:83], v[134:135], 0, v[82:83]
	v_mov_b32_e32 v88, v68
	v_mov_b32_e32 v89, v64
	v_mov_b32_e32 v68, 0
	v_mov_b32_e32 v84, v186
	v_mov_b32_e32 v85, v187
	v_lshlrev_b32_e32 v86, 16, v84
	v_and_b32_e32 v87, 0xffff0000, v84
	v_pk_add_f32 v[86:87], v[88:89], v[86:87]
	v_lshlrev_b32_e32 v84, 16, v85
	v_and_b32_e32 v85, 0xffff0000, v85
	v_mov_b32_e32 v88, v76
	v_mov_b32_e32 v89, v72
	v_pk_add_f32 v[84:85], v[88:89], v[84:85]
	v_cvt_pk_bf16_f32 v88, v86, v87
	v_cvt_pk_bf16_f32 v89, v84, v85
	global_store_dwordx2 v[82:83], v[88:89], off sc1
	v_pk_mul_f32 v[82:83], v[86:87], v[86:87]
	v_pk_mul_f32 v[84:85], v[84:85], v[84:85]
	v_add_f32_e32 v64, v82, v83
	v_add_f32_e32 v64, v84, v64
	v_add_f32_e32 v64, v85, v64
	s_nop 1
	v_add_f32_dpp v64, v64, v64 row_ror:8 row_mask:0xf bank_mask:0xf bound_ctrl:1
	s_nop 1
	v_add_f32_dpp v64, v64, v64 row_ror:4 row_mask:0xf bank_mask:0xf bound_ctrl:1
	s_nop 1
	v_add_f32_dpp v64, v64, v64 row_ror:2 row_mask:0xf bank_mask:0xf bound_ctrl:1
	s_nop 1
	v_mov_b32_dpp v68, v64 row_ror:1 row_mask:0xf bank_mask:0xf
	s_and_saveexec_b64 s[2:3], s[8:9]
	s_cbranch_execz .LBB0_599
	v_add_f32_e32 v64, v64, v68
	v_mul_f32_e32 v64, 0x49800000, v64
	v_trunc_f32_e32 v64, v64
	v_mul_f32_e32 v68, 0x2f800000, v64
	v_floor_f32_e32 v68, v68
	v_fmac_f32_e32 v64, 0xcf800000, v68
	v_cvt_u32_f32_e32 v82, v64
	v_cvt_u32_f32_e32 v83, v68
	v_lshl_add_u64 v[80:81], v[80:81], 3, s[0:1]
	global_atomic_add_x2 v[80:81], v[82:83], off
; __device__ __forceinline__ float row16_sum(float v) { DPP_ADD(v, 0x128); DPP_ADD(v, 0x124); DPP_ADD(v, 0x122); DPP_ADD(v, 0x121); return v; }
; template <int EPI, int N, int K>
; __device__ __forceinline__ void gemm_phase(const bf16_t* __restrict__ A, const bf16_t* __restrict__ Bt, const EpiArgs ea) {
;     ...
;           for (int j = 0; j < 4; ++j) {
;             const int row = brow + ai * 128 + wr * 64 + m * 16 + fq * 4 + j;
;             const u32x2 x2 = *(const u32x2*)(ea.outb + (size_t)row * DM + c0);
;             float4 xn;
;             xn.x = __builtin_bit_cast(float, x2[0] << 16) + acc[ai][0][m][0][j]; xn.y = __builtin_bit_cast(float, x2[0] & 0xffff0000u) + acc[ai][0][m][1][j];
;             xn.z = __builtin_bit_cast(float, x2[1] << 16) + acc[ai][1][m][0][j]; xn.w = __builtin_bit_cast(float, x2[1] & 0xffff0000u) + acc[ai][1][m][1][j];
;             u32x2 o = {pk2(xn.x, xn.y), pk2(xn.z, xn.w)};
;             st_wt(ea.outb + (size_t)row * DM + c0, o);
;             float ss = xn.x * xn.x + xn.y * xn.y + xn.z * xn.z + xn.w * xn.w;
;             ss = row16_sum(ss);
;             if (fr == 0) __hip_atomic_fetch_add(ea.rowsq_out + row, (rsq_t)(ss * RSQ_SCALE), __ATOMIC_RELAXED, __HIP_MEMORY_SCOPE_AGENT);
.LBB0_599:
	s_or_b64 exec, exec, s[2:3]
	v_add_u32_e32 v80, 49, v132
	v_ashrrev_i32_e32 v81, 31, v80
	v_lshlrev_b64 v[82:83], 12, v[80:81]
	v_lshl_add_u64 v[82:83], v[134:135], 0, v[82:83]
	v_mov_b32_e32 v64, v69
	v_mov_b32_e32 v72, v77
	v_mov_b32_e32 v84, v188
	v_mov_b32_e32 v85, v189
	v_lshlrev_b32_e32 v86, 16, v84
	v_and_b32_e32 v87, 0xffff0000, v84
	v_pk_add_f32 v[64:65], v[64:65], v[86:87]
	v_lshlrev_b32_e32 v68, 16, v85
	v_and_b32_e32 v69, 0xffff0000, v85
	v_pk_add_f32 v[68:69], v[72:73], v[68:69]
	v_cvt_pk_bf16_f32 v72, v64, v65
	v_pk_mul_f32 v[64:65], v[64:65], v[64:65]
	v_cvt_pk_bf16_f32 v73, v68, v69
	v_pk_mul_f32 v[68:69], v[68:69], v[68:69]
	v_add_f32_e32 v64, v64, v65
	v_add_f32_e32 v64, v68, v64
	v_add_f32_e32 v64, v69, v64
	v_mov_b32_e32 v65, 0
	global_store_dwordx2 v[82:83], v[72:73], off sc1
	v_add_f32_dpp v64, v64, v64 row_ror:8 row_mask:0xf bank_mask:0xf bound_ctrl:1
	s_nop 1
	v_add_f32_dpp v64, v64, v64 row_ror:4 row_mask:0xf bank_mask:0xf bound_ctrl:1
	s_nop 1
	v_add_f32_dpp v64, v64, v64 row_ror:2 row_mask:0xf bank_mask:0xf bound_ctrl:1
	s_nop 1
	v_mov_b32_dpp v65, v64 row_ror:1 row_mask:0xf bank_mask:0xf
	s_and_saveexec_b64 s[2:3], s[8:9]
	s_cbranch_execz .LBB0_601
	v_add_f32_e32 v64, v64, v65
	v_mul_f32_e32 v64, 0x49800000, v64
	v_trunc_f32_e32 v64, v64
	v_mul_f32_e32 v65, 0x2f800000, v64
	v_floor_f32_e32 v65, v65
	v_fmac_f32_e32 v64, 0xcf800000, v65
	v_cvt_u32_f32_e32 v64, v64
	v_cvt_u32_f32_e32 v65, v65
	v_lshl_add_u64 v[68:69], v[80:81], 3, s[0:1]
	global_atomic_add_x2 v[68:69], v[64:65], off
.LBB0_601:
	s_or_b64 exec, exec, s[2:3]
	v_add_u32_e32 v64, 50, v132
	v_ashrrev_i32_e32 v65, 31, v64
	v_lshlrev_b64 v[68:69], 12, v[64:65]
	v_lshl_add_u64 v[68:69], v[134:135], 0, v[68:69]
	v_mov_b32_e32 v80, v70
	v_mov_b32_e32 v81, v66
	v_mov_b32_e32 v72, v190
	v_mov_b32_e32 v73, v191
	v_lshlrev_b32_e32 v76, 16, v72
	v_and_b32_e32 v77, 0xffff0000, v72
	v_pk_add_f32 v[76:77], v[80:81], v[76:77]
	v_lshlrev_b32_e32 v72, 16, v73
	v_and_b32_e32 v73, 0xffff0000, v73
	v_mov_b32_e32 v80, v78
	v_mov_b32_e32 v81, v74
	v_pk_add_f32 v[72:73], v[80:81], v[72:73]
	v_cvt_pk_bf16_f32 v80, v76, v77
	v_cvt_pk_bf16_f32 v81, v72, v73
	global_store_dwordx2 v[68:69], v[80:81], off sc1
	v_pk_mul_f32 v[68:69], v[76:77], v[76:77]
	v_pk_mul_f32 v[72:73], v[72:73], v[72:73]
	v_add_f32_e32 v66, v68, v69
	v_add_f32_e32 v66, v72, v66
	v_add_f32_e32 v66, v73, v66
	v_mov_b32_e32 v68, 0
	s_nop 0
	v_add_f32_dpp v66, v66, v66 row_ror:8 row_mask:0xf bank_mask:0xf bound_ctrl:1
	s_nop 1
	v_add_f32_dpp v66, v66, v66 row_ror:4 row_mask:0xf bank_mask:0xf bound_ctrl:1
	s_nop 1
	v_add_f32_dpp v66, v66, v66 row_ror:2 row_mask:0xf bank_mask:0xf bound_ctrl:1
	s_nop 1
	v_mov_b32_dpp v68, v66 row_ror:1 row_mask:0xf bank_mask:0xf
	s_and_saveexec_b64 s[2:3], s[8:9]
	s_cbranch_execz .LBB0_603
	v_add_f32_e32 v66, v66, v68
	v_mul_f32_e32 v66, 0x49800000, v66
	v_trunc_f32_e32 v66, v66
	v_mul_f32_e32 v68, 0x2f800000, v66
	v_floor_f32_e32 v69, v68
	v_fmac_f32_e32 v66, 0xcf800000, v69
	v_cvt_u32_f32_e32 v68, v66
	v_cvt_u32_f32_e32 v69, v69
	v_lshl_add_u64 v[64:65], v[64:65], 3, s[0:1]
	global_atomic_add_x2 v[64:65], v[68:69], off
.LBB0_603:
	s_or_b64 exec, exec, s[2:3]
	v_add_u32_e32 v64, 51, v132
	v_ashrrev_i32_e32 v65, 31, v64
	v_lshlrev_b64 v[68:69], 12, v[64:65]
	v_lshl_add_u64 v[68:69], v[134:135], 0, v[68:69]
	v_mov_b32_e32 v66, v71
	v_mov_b32_e32 v74, v79
	v_mov_b32_e32 v72, v192
	v_mov_b32_e32 v73, v193
	v_lshlrev_b32_e32 v70, 16, v72
	v_and_b32_e32 v71, 0xffff0000, v72
	v_lshlrev_b32_e32 v72, 16, v73
	v_and_b32_e32 v73, 0xffff0000, v73
	v_pk_add_f32 v[66:67], v[66:67], v[70:71]
	v_pk_add_f32 v[70:71], v[74:75], v[72:73]
	v_cvt_pk_bf16_f32 v72, v66, v67
	v_pk_mul_f32 v[66:67], v[66:67], v[66:67]
	v_cvt_pk_bf16_f32 v73, v70, v71
	v_pk_mul_f32 v[70:71], v[70:71], v[70:71]
	v_add_f32_e32 v66, v66, v67
	v_add_f32_e32 v66, v70, v66
	v_add_f32_e32 v66, v71, v66
	v_mov_b32_e32 v67, 0
	global_store_dwordx2 v[68:69], v[72:73], off sc1
	v_add_f32_dpp v66, v66, v66 row_ror:8 row_mask:0xf bank_mask:0xf bound_ctrl:1
	s_nop 1
	v_add_f32_dpp v66, v66, v66 row_ror:4 row_mask:0xf bank_mask:0xf bound_ctrl:1
	s_nop 1
	v_add_f32_dpp v66, v66, v66 row_ror:2 row_mask:0xf bank_mask:0xf bound_ctrl:1
	s_nop 1
	v_mov_b32_dpp v67, v66 row_ror:1 row_mask:0xf bank_mask:0xf
	s_and_saveexec_b64 s[2:3], s[8:9]
	s_cbranch_execz .LBB0_605
	v_add_f32_e32 v66, v66, v67
	v_mul_f32_e32 v66, 0x49800000, v66
	v_trunc_f32_e32 v66, v66
	v_mul_f32_e32 v67, 0x2f800000, v66
	v_floor_f32_e32 v67, v67
	v_fmac_f32_e32 v66, 0xcf800000, v67
	v_cvt_u32_f32_e32 v66, v66
	v_cvt_u32_f32_e32 v67, v67
	v_lshl_add_u64 v[64:65], v[64:65], 3, s[0:1]
	global_atomic_add_x2 v[64:65], v[66:67], off
.LBB0_605:
	s_or_b64 exec, exec, s[2:3]
	v_add_u32_e32 v64, 0x80, v132
	v_ashrrev_i32_e32 v65, 31, v64
	v_lshlrev_b64 v[66:67], 12, v[64:65]
	v_lshl_add_u64 v[66:67], v[134:135], 0, v[66:67]
	v_mov_b32_e32 v72, v52
	v_mov_b32_e32 v73, v48
	v_mov_b32_e32 v52, 0
	v_mov_b32_e32 v68, v194
	v_mov_b32_e32 v69, v195
	v_lshlrev_b32_e32 v70, 16, v68
	v_and_b32_e32 v71, 0xffff0000, v68
	v_pk_add_f32 v[70:71], v[72:73], v[70:71]
	v_lshlrev_b32_e32 v68, 16, v69
	v_and_b32_e32 v69, 0xffff0000, v69
	v_mov_b32_e32 v72, v60
	v_mov_b32_e32 v73, v56
	v_pk_add_f32 v[68:69], v[72:73], v[68:69]
	v_cvt_pk_bf16_f32 v72, v70, v71
	v_cvt_pk_bf16_f32 v73, v68, v69
	global_store_dwordx2 v[66:67], v[72:73], off sc1
	v_pk_mul_f32 v[66:67], v[70:71], v[70:71]
	v_pk_mul_f32 v[68:69], v[68:69], v[68:69]
	v_add_f32_e32 v48, v66, v67
	v_add_f32_e32 v48, v68, v48
	v_add_f32_e32 v48, v69, v48
	s_nop 1
	v_add_f32_dpp v48, v48, v48 row_ror:8 row_mask:0xf bank_mask:0xf bound_ctrl:1
	s_nop 1
	v_add_f32_dpp v48, v48, v48 row_ror:4 row_mask:0xf bank_mask:0xf bound_ctrl:1
	s_nop 1
	v_add_f32_dpp v48, v48, v48 row_ror:2 row_mask:0xf bank_mask:0xf bound_ctrl:1
	s_nop 1
	v_mov_b32_dpp v52, v48 row_ror:1 row_mask:0xf bank_mask:0xf
	s_and_saveexec_b64 s[2:3], s[8:9]
	s_cbranch_execz .LBB0_607
	v_add_f32_e32 v48, v48, v52
	v_mul_f32_e32 v48, 0x49800000, v48
	v_trunc_f32_e32 v48, v48
	v_mul_f32_e32 v52, 0x2f800000, v48
	v_floor_f32_e32 v52, v52
	v_fmac_f32_e32 v48, 0xcf800000, v52
	v_cvt_u32_f32_e32 v66, v48
	v_cvt_u32_f32_e32 v67, v52
	v_lshl_add_u64 v[64:65], v[64:65], 3, s[0:1]
	global_atomic_add_x2 v[64:65], v[66:67], off
; __device__ __forceinline__ float row16_sum(float v) { DPP_ADD(v, 0x128); DPP_ADD(v, 0x124); DPP_ADD(v, 0x122); DPP_ADD(v, 0x121); return v; }
; template <int EPI, int N, int K>
; __device__ __forceinline__ void gemm_phase(const bf16_t* __restrict__ A, const bf16_t* __restrict__ Bt, const EpiArgs ea) {
;     ...
;           for (int j = 0; j < 4; ++j) {
;             const int row = brow + ai * 128 + wr * 64 + m * 16 + fq * 4 + j;
;             const u32x2 x2 = *(const u32x2*)(ea.outb + (size_t)row * DM + c0);
;             float4 xn;
;             xn.x = __builtin_bit_cast(float, x2[0] << 16) + acc[ai][0][m][0][j]; xn.y = __builtin_bit_cast(float, x2[0] & 0xffff0000u) + acc[ai][0][m][1][j];
;             xn.z = __builtin_bit_cast(float, x2[1] << 16) + acc[ai][1][m][0][j]; xn.w = __builtin_bit_cast(float, x2[1] & 0xffff0000u) + acc[ai][1][m][1][j];
;             u32x2 o = {pk2(xn.x, xn.y), pk2(xn.z, xn.w)};
;             st_wt(ea.outb + (size_t)row * DM + c0, o);
;             float ss = xn.x * xn.x + xn.y * xn.y + xn.z * xn.z + xn.w * xn.w;
;             ss = row16_sum(ss);
;             if (fr == 0) __hip_atomic_fetch_add(ea.rowsq_out + row, (rsq_t)(ss * RSQ_SCALE), __ATOMIC_RELAXED, __HIP_MEMORY_SCOPE_AGENT);
.LBB0_607:
	s_or_b64 exec, exec, s[2:3]
	v_add_u32_e32 v64, 0x81, v132
	v_ashrrev_i32_e32 v65, 31, v64
	v_lshlrev_b64 v[66:67], 12, v[64:65]
	v_lshl_add_u64 v[66:67], v[134:135], 0, v[66:67]
	v_mov_b32_e32 v48, v53
	v_mov_b32_e32 v56, v61
	v_mov_b32_e32 v68, v196
	v_mov_b32_e32 v69, v197
	v_lshlrev_b32_e32 v70, 16, v68
	v_and_b32_e32 v71, 0xffff0000, v68
	v_pk_add_f32 v[48:49], v[48:49], v[70:71]
	v_lshlrev_b32_e32 v52, 16, v69
	v_and_b32_e32 v53, 0xffff0000, v69
	v_pk_add_f32 v[52:53], v[56:57], v[52:53]
	v_cvt_pk_bf16_f32 v56, v48, v49
	v_pk_mul_f32 v[48:49], v[48:49], v[48:49]
	v_cvt_pk_bf16_f32 v57, v52, v53
	v_pk_mul_f32 v[52:53], v[52:53], v[52:53]
	v_add_f32_e32 v48, v48, v49
	v_add_f32_e32 v48, v52, v48
	v_add_f32_e32 v48, v53, v48
	v_mov_b32_e32 v49, 0
	global_store_dwordx2 v[66:67], v[56:57], off sc1
	v_add_f32_dpp v48, v48, v48 row_ror:8 row_mask:0xf bank_mask:0xf bound_ctrl:1
	s_nop 1
	v_add_f32_dpp v48, v48, v48 row_ror:4 row_mask:0xf bank_mask:0xf bound_ctrl:1
	s_nop 1
	v_add_f32_dpp v48, v48, v48 row_ror:2 row_mask:0xf bank_mask:0xf bound_ctrl:1
	s_nop 1
	v_mov_b32_dpp v49, v48 row_ror:1 row_mask:0xf bank_mask:0xf
	s_and_saveexec_b64 s[2:3], s[8:9]
	s_cbranch_execz .LBB0_609
	v_add_f32_e32 v48, v48, v49
	v_mul_f32_e32 v48, 0x49800000, v48
	v_trunc_f32_e32 v48, v48
	v_mul_f32_e32 v49, 0x2f800000, v48
	v_floor_f32_e32 v49, v49
	v_fmac_f32_e32 v48, 0xcf800000, v49
	v_cvt_u32_f32_e32 v48, v48
	v_cvt_u32_f32_e32 v49, v49
	v_lshl_add_u64 v[52:53], v[64:65], 3, s[0:1]
	global_atomic_add_x2 v[52:53], v[48:49], off
.LBB0_609:
	s_or_b64 exec, exec, s[2:3]
	v_add_u32_e32 v48, 0x82, v132
	v_ashrrev_i32_e32 v49, 31, v48
	v_lshlrev_b64 v[52:53], 12, v[48:49]
	v_lshl_add_u64 v[52:53], v[134:135], 0, v[52:53]
	v_mov_b32_e32 v64, v54
	v_mov_b32_e32 v65, v50
	v_mov_b32_e32 v56, v198
	v_mov_b32_e32 v57, v199
	v_lshlrev_b32_e32 v60, 16, v56
	v_and_b32_e32 v61, 0xffff0000, v56
	v_pk_add_f32 v[60:61], v[64:65], v[60:61]
	v_lshlrev_b32_e32 v56, 16, v57
	v_and_b32_e32 v57, 0xffff0000, v57
	v_mov_b32_e32 v64, v62
	v_mov_b32_e32 v65, v58
	v_pk_add_f32 v[56:57], v[64:65], v[56:57]
	v_cvt_pk_bf16_f32 v64, v60, v61
	v_cvt_pk_bf16_f32 v65, v56, v57
	global_store_dwordx2 v[52:53], v[64:65], off sc1
	v_pk_mul_f32 v[52:53], v[60:61], v[60:61]
	v_pk_mul_f32 v[56:57], v[56:57], v[56:57]
	v_add_f32_e32 v50, v52, v53
	v_add_f32_e32 v50, v56, v50
	v_add_f32_e32 v50, v57, v50
	v_mov_b32_e32 v52, 0
	s_nop 0
	v_add_f32_dpp v50, v50, v50 row_ror:8 row_mask:0xf bank_mask:0xf bound_ctrl:1
	s_nop 1
	v_add_f32_dpp v50, v50, v50 row_ror:4 row_mask:0xf bank_mask:0xf bound_ctrl:1
	s_nop 1
	v_add_f32_dpp v50, v50, v50 row_ror:2 row_mask:0xf bank_mask:0xf bound_ctrl:1
	s_nop 1
	v_mov_b32_dpp v52, v50 row_ror:1 row_mask:0xf bank_mask:0xf
	s_and_saveexec_b64 s[2:3], s[8:9]
	s_cbranch_execz .LBB0_611
	v_add_f32_e32 v50, v50, v52
	v_mul_f32_e32 v50, 0x49800000, v50
	v_trunc_f32_e32 v50, v50
	v_mul_f32_e32 v52, 0x2f800000, v50
	v_floor_f32_e32 v53, v52
	v_fmac_f32_e32 v50, 0xcf800000, v53
	v_cvt_u32_f32_e32 v52, v50
	v_cvt_u32_f32_e32 v53, v53
	v_lshl_add_u64 v[48:49], v[48:49], 3, s[0:1]
	global_atomic_add_x2 v[48:49], v[52:53], off
.LBB0_611:
	s_or_b64 exec, exec, s[2:3]
	v_add_u32_e32 v48, 0x83, v132
	v_ashrrev_i32_e32 v49, 31, v48
	v_lshlrev_b64 v[52:53], 12, v[48:49]
	v_lshl_add_u64 v[52:53], v[134:135], 0, v[52:53]
	v_mov_b32_e32 v50, v55
	v_mov_b32_e32 v58, v63
	v_mov_b32_e32 v56, v200
	v_mov_b32_e32 v57, v201
	v_lshlrev_b32_e32 v54, 16, v56
	v_and_b32_e32 v55, 0xffff0000, v56
	v_lshlrev_b32_e32 v56, 16, v57
	v_and_b32_e32 v57, 0xffff0000, v57
	v_pk_add_f32 v[50:51], v[50:51], v[54:55]
	v_pk_add_f32 v[54:55], v[58:59], v[56:57]
	v_cvt_pk_bf16_f32 v56, v50, v51
	v_pk_mul_f32 v[50:51], v[50:51], v[50:51]
	v_cvt_pk_bf16_f32 v57, v54, v55
	v_pk_mul_f32 v[54:55], v[54:55], v[54:55]
	v_add_f32_e32 v50, v50, v51
	v_add_f32_e32 v50, v54, v50
	v_add_f32_e32 v50, v55, v50
	v_mov_b32_e32 v51, 0
	global_store_dwordx2 v[52:53], v[56:57], off sc1
	v_add_f32_dpp v50, v50, v50 row_ror:8 row_mask:0xf bank_mask:0xf bound_ctrl:1
	s_nop 1
	v_add_f32_dpp v50, v50, v50 row_ror:4 row_mask:0xf bank_mask:0xf bound_ctrl:1
	s_nop 1
	v_add_f32_dpp v50, v50, v50 row_ror:2 row_mask:0xf bank_mask:0xf bound_ctrl:1
	s_nop 1
	v_mov_b32_dpp v51, v50 row_ror:1 row_mask:0xf bank_mask:0xf
	s_and_saveexec_b64 s[2:3], s[8:9]
	s_cbranch_execz .LBB0_613
	v_add_f32_e32 v50, v50, v51
	v_mul_f32_e32 v50, 0x49800000, v50
	v_trunc_f32_e32 v50, v50
	v_mul_f32_e32 v51, 0x2f800000, v50
	v_floor_f32_e32 v51, v51
	v_fmac_f32_e32 v50, 0xcf800000, v51
	v_cvt_u32_f32_e32 v50, v50
	v_cvt_u32_f32_e32 v51, v51
	v_lshl_add_u64 v[48:49], v[48:49], 3, s[0:1]
	global_atomic_add_x2 v[48:49], v[50:51], off
.LBB0_613:
	s_or_b64 exec, exec, s[2:3]
	v_add_u32_e32 v48, 0x90, v132
	v_ashrrev_i32_e32 v49, 31, v48
	v_lshlrev_b64 v[50:51], 12, v[48:49]
	v_lshl_add_u64 v[50:51], v[134:135], 0, v[50:51]
	v_mov_b32_e32 v56, v36
	v_mov_b32_e32 v57, v32
	v_mov_b32_e32 v36, 0
	v_mov_b32_e32 v52, v202
	v_mov_b32_e32 v53, v203
	v_lshlrev_b32_e32 v54, 16, v52
	v_and_b32_e32 v55, 0xffff0000, v52
	v_pk_add_f32 v[54:55], v[56:57], v[54:55]
	v_lshlrev_b32_e32 v52, 16, v53
	v_and_b32_e32 v53, 0xffff0000, v53
	v_mov_b32_e32 v56, v44
	v_mov_b32_e32 v57, v40
	v_pk_add_f32 v[52:53], v[56:57], v[52:53]
	v_cvt_pk_bf16_f32 v56, v54, v55
	v_cvt_pk_bf16_f32 v57, v52, v53
	global_store_dwordx2 v[50:51], v[56:57], off sc1
	v_pk_mul_f32 v[50:51], v[54:55], v[54:55]
	v_pk_mul_f32 v[52:53], v[52:53], v[52:53]
	v_add_f32_e32 v32, v50, v51
	v_add_f32_e32 v32, v52, v32
	v_add_f32_e32 v32, v53, v32
	s_nop 1
	v_add_f32_dpp v32, v32, v32 row_ror:8 row_mask:0xf bank_mask:0xf bound_ctrl:1
	s_nop 1
	v_add_f32_dpp v32, v32, v32 row_ror:4 row_mask:0xf bank_mask:0xf bound_ctrl:1
	s_nop 1
	v_add_f32_dpp v32, v32, v32 row_ror:2 row_mask:0xf bank_mask:0xf bound_ctrl:1
	s_nop 1
	v_mov_b32_dpp v36, v32 row_ror:1 row_mask:0xf bank_mask:0xf
	s_and_saveexec_b64 s[2:3], s[8:9]
	s_cbranch_execz .LBB0_615
	v_add_f32_e32 v32, v32, v36
	v_mul_f32_e32 v32, 0x49800000, v32
	v_trunc_f32_e32 v32, v32
	v_mul_f32_e32 v36, 0x2f800000, v32
	v_floor_f32_e32 v36, v36
	v_fmac_f32_e32 v32, 0xcf800000, v36
	v_cvt_u32_f32_e32 v50, v32
	v_cvt_u32_f32_e32 v51, v36
	v_lshl_add_u64 v[48:49], v[48:49], 3, s[0:1]
	global_atomic_add_x2 v[48:49], v[50:51], off
; __device__ __forceinline__ float row16_sum(float v) { DPP_ADD(v, 0x128); DPP_ADD(v, 0x124); DPP_ADD(v, 0x122); DPP_ADD(v, 0x121); return v; }
; template <int EPI, int N, int K>
; __device__ __forceinline__ void gemm_phase(const bf16_t* __restrict__ A, const bf16_t* __restrict__ Bt, const EpiArgs ea) {
;     ...
;           for (int j = 0; j < 4; ++j) {
;             const int row = brow + ai * 128 + wr * 64 + m * 16 + fq * 4 + j;
;             const u32x2 x2 = *(const u32x2*)(ea.outb + (size_t)row * DM + c0);
;             float4 xn;
;             xn.x = __builtin_bit_cast(float, x2[0] << 16) + acc[ai][0][m][0][j]; xn.y = __builtin_bit_cast(float, x2[0] & 0xffff0000u) + acc[ai][0][m][1][j];
;             xn.z = __builtin_bit_cast(float, x2[1] << 16) + acc[ai][1][m][0][j]; xn.w = __builtin_bit_cast(float, x2[1] & 0xffff0000u) + acc[ai][1][m][1][j];
;             u32x2 o = {pk2(xn.x, xn.y), pk2(xn.z, xn.w)};
;             st_wt(ea.outb + (size_t)row * DM + c0, o);
;             float ss = xn.x * xn.x + xn.y * xn.y + xn.z * xn.z + xn.w * xn.w;
;             ss = row16_sum(ss);
;             if (fr == 0) __hip_atomic_fetch_add(ea.rowsq_out + row, (rsq_t)(ss * RSQ_SCALE), __ATOMIC_RELAXED, __HIP_MEMORY_SCOPE_AGENT);
.LBB0_615:
	s_or_b64 exec, exec, s[2:3]
	v_add_u32_e32 v48, 0x91, v132
	v_ashrrev_i32_e32 v49, 31, v48
	v_lshlrev_b64 v[50:51], 12, v[48:49]
	v_lshl_add_u64 v[50:51], v[134:135], 0, v[50:51]
	v_mov_b32_e32 v32, v37
	v_mov_b32_e32 v40, v45
	v_mov_b32_e32 v52, v204
	v_mov_b32_e32 v53, v205
	v_lshlrev_b32_e32 v54, 16, v52
	v_and_b32_e32 v55, 0xffff0000, v52
	v_pk_add_f32 v[32:33], v[32:33], v[54:55]
	v_lshlrev_b32_e32 v36, 16, v53
	v_and_b32_e32 v37, 0xffff0000, v53
	v_pk_add_f32 v[36:37], v[40:41], v[36:37]
	v_cvt_pk_bf16_f32 v40, v32, v33
	v_pk_mul_f32 v[32:33], v[32:33], v[32:33]
	v_cvt_pk_bf16_f32 v41, v36, v37
	v_pk_mul_f32 v[36:37], v[36:37], v[36:37]
	v_add_f32_e32 v32, v32, v33
	v_add_f32_e32 v32, v36, v32
	v_add_f32_e32 v32, v37, v32
	v_mov_b32_e32 v33, 0
	global_store_dwordx2 v[50:51], v[40:41], off sc1
	v_add_f32_dpp v32, v32, v32 row_ror:8 row_mask:0xf bank_mask:0xf bound_ctrl:1
	s_nop 1
	v_add_f32_dpp v32, v32, v32 row_ror:4 row_mask:0xf bank_mask:0xf bound_ctrl:1
	s_nop 1
	v_add_f32_dpp v32, v32, v32 row_ror:2 row_mask:0xf bank_mask:0xf bound_ctrl:1
	s_nop 1
	v_mov_b32_dpp v33, v32 row_ror:1 row_mask:0xf bank_mask:0xf
	s_and_saveexec_b64 s[2:3], s[8:9]
	s_cbranch_execz .LBB0_617
	v_add_f32_e32 v32, v32, v33
	v_mul_f32_e32 v32, 0x49800000, v32
	v_trunc_f32_e32 v32, v32
	v_mul_f32_e32 v33, 0x2f800000, v32
	v_floor_f32_e32 v33, v33
	v_fmac_f32_e32 v32, 0xcf800000, v33
	v_cvt_u32_f32_e32 v32, v32
	v_cvt_u32_f32_e32 v33, v33
	v_lshl_add_u64 v[36:37], v[48:49], 3, s[0:1]
	global_atomic_add_x2 v[36:37], v[32:33], off
.LBB0_617:
	s_or_b64 exec, exec, s[2:3]
	v_add_u32_e32 v32, 0x92, v132
	v_ashrrev_i32_e32 v33, 31, v32
	v_lshlrev_b64 v[36:37], 12, v[32:33]
	v_lshl_add_u64 v[36:37], v[134:135], 0, v[36:37]
	v_mov_b32_e32 v48, v38
	v_mov_b32_e32 v49, v34
	v_mov_b32_e32 v40, v206
	v_mov_b32_e32 v41, v207
	v_lshlrev_b32_e32 v44, 16, v40
	v_and_b32_e32 v45, 0xffff0000, v40
	v_pk_add_f32 v[44:45], v[48:49], v[44:45]
	v_lshlrev_b32_e32 v40, 16, v41
	v_and_b32_e32 v41, 0xffff0000, v41
	v_mov_b32_e32 v48, v46
	v_mov_b32_e32 v49, v42
	v_pk_add_f32 v[40:41], v[48:49], v[40:41]
	v_cvt_pk_bf16_f32 v48, v44, v45
	v_cvt_pk_bf16_f32 v49, v40, v41
	global_store_dwordx2 v[36:37], v[48:49], off sc1
	v_pk_mul_f32 v[36:37], v[44:45], v[44:45]
	v_pk_mul_f32 v[40:41], v[40:41], v[40:41]
	v_add_f32_e32 v34, v36, v37
	v_add_f32_e32 v34, v40, v34
	v_add_f32_e32 v34, v41, v34
	v_mov_b32_e32 v36, 0
	s_nop 0
	v_add_f32_dpp v34, v34, v34 row_ror:8 row_mask:0xf bank_mask:0xf bound_ctrl:1
	s_nop 1
	v_add_f32_dpp v34, v34, v34 row_ror:4 row_mask:0xf bank_mask:0xf bound_ctrl:1
	s_nop 1
	v_add_f32_dpp v34, v34, v34 row_ror:2 row_mask:0xf bank_mask:0xf bound_ctrl:1
	s_nop 1
	v_mov_b32_dpp v36, v34 row_ror:1 row_mask:0xf bank_mask:0xf
	s_and_saveexec_b64 s[2:3], s[8:9]
	s_cbranch_execz .LBB0_619
	v_add_f32_e32 v34, v34, v36
	v_mul_f32_e32 v34, 0x49800000, v34
	v_trunc_f32_e32 v34, v34
	v_mul_f32_e32 v36, 0x2f800000, v34
	v_floor_f32_e32 v37, v36
	v_fmac_f32_e32 v34, 0xcf800000, v37
	v_cvt_u32_f32_e32 v36, v34
	v_cvt_u32_f32_e32 v37, v37
	v_lshl_add_u64 v[32:33], v[32:33], 3, s[0:1]
	global_atomic_add_x2 v[32:33], v[36:37], off
.LBB0_619:
	s_or_b64 exec, exec, s[2:3]
	v_add_u32_e32 v32, 0x93, v132
	v_ashrrev_i32_e32 v33, 31, v32
	v_lshlrev_b64 v[36:37], 12, v[32:33]
	v_lshl_add_u64 v[36:37], v[134:135], 0, v[36:37]
	v_mov_b32_e32 v34, v39
	v_mov_b32_e32 v42, v47
	v_mov_b32_e32 v40, v208
	v_mov_b32_e32 v41, v209
	v_lshlrev_b32_e32 v38, 16, v40
	v_and_b32_e32 v39, 0xffff0000, v40
	v_lshlrev_b32_e32 v40, 16, v41
	v_and_b32_e32 v41, 0xffff0000, v41
	v_pk_add_f32 v[34:35], v[34:35], v[38:39]
	v_pk_add_f32 v[38:39], v[42:43], v[40:41]
	v_cvt_pk_bf16_f32 v40, v34, v35
	v_pk_mul_f32 v[34:35], v[34:35], v[34:35]
	v_cvt_pk_bf16_f32 v41, v38, v39
	v_pk_mul_f32 v[38:39], v[38:39], v[38:39]
	v_add_f32_e32 v34, v34, v35
	v_add_f32_e32 v34, v38, v34
	v_add_f32_e32 v34, v39, v34
	v_mov_b32_e32 v35, 0
	global_store_dwordx2 v[36:37], v[40:41], off sc1
	v_add_f32_dpp v34, v34, v34 row_ror:8 row_mask:0xf bank_mask:0xf bound_ctrl:1
	s_nop 1
	v_add_f32_dpp v34, v34, v34 row_ror:4 row_mask:0xf bank_mask:0xf bound_ctrl:1
	s_nop 1
	v_add_f32_dpp v34, v34, v34 row_ror:2 row_mask:0xf bank_mask:0xf bound_ctrl:1
	s_nop 1
	v_mov_b32_dpp v35, v34 row_ror:1 row_mask:0xf bank_mask:0xf
	s_and_saveexec_b64 s[2:3], s[8:9]
	s_cbranch_execz .LBB0_621
	v_add_f32_e32 v34, v34, v35
	v_mul_f32_e32 v34, 0x49800000, v34
	v_trunc_f32_e32 v34, v34
	v_mul_f32_e32 v35, 0x2f800000, v34
	v_floor_f32_e32 v35, v35
	v_fmac_f32_e32 v34, 0xcf800000, v35
	v_cvt_u32_f32_e32 v34, v34
	v_cvt_u32_f32_e32 v35, v35
	v_lshl_add_u64 v[32:33], v[32:33], 3, s[0:1]
	global_atomic_add_x2 v[32:33], v[34:35], off
.LBB0_621:
	s_or_b64 exec, exec, s[2:3]
	v_add_u32_e32 v32, 0xa0, v132
	v_ashrrev_i32_e32 v33, 31, v32
	v_lshlrev_b64 v[34:35], 12, v[32:33]
	v_lshl_add_u64 v[34:35], v[134:135], 0, v[34:35]
	v_mov_b32_e32 v40, v20
	v_mov_b32_e32 v41, v16
	v_mov_b32_e32 v20, 0
	v_mov_b32_e32 v36, v210
	v_mov_b32_e32 v37, v211
	v_lshlrev_b32_e32 v38, 16, v36
	v_and_b32_e32 v39, 0xffff0000, v36
	v_pk_add_f32 v[38:39], v[40:41], v[38:39]
	v_lshlrev_b32_e32 v36, 16, v37
	v_and_b32_e32 v37, 0xffff0000, v37
	v_mov_b32_e32 v40, v28
	v_mov_b32_e32 v41, v24
	v_pk_add_f32 v[36:37], v[40:41], v[36:37]
	v_cvt_pk_bf16_f32 v40, v38, v39
	v_cvt_pk_bf16_f32 v41, v36, v37
	global_store_dwordx2 v[34:35], v[40:41], off sc1
	v_pk_mul_f32 v[34:35], v[38:39], v[38:39]
	v_pk_mul_f32 v[36:37], v[36:37], v[36:37]
	v_add_f32_e32 v16, v34, v35
	v_add_f32_e32 v16, v36, v16
	v_add_f32_e32 v16, v37, v16
	s_nop 1
	v_add_f32_dpp v16, v16, v16 row_ror:8 row_mask:0xf bank_mask:0xf bound_ctrl:1
	s_nop 1
	v_add_f32_dpp v16, v16, v16 row_ror:4 row_mask:0xf bank_mask:0xf bound_ctrl:1
	s_nop 1
	v_add_f32_dpp v16, v16, v16 row_ror:2 row_mask:0xf bank_mask:0xf bound_ctrl:1
	s_nop 1
	v_mov_b32_dpp v20, v16 row_ror:1 row_mask:0xf bank_mask:0xf
	s_and_saveexec_b64 s[2:3], s[8:9]
	s_cbranch_execz .LBB0_623
	v_add_f32_e32 v16, v16, v20
	v_mul_f32_e32 v16, 0x49800000, v16
	v_trunc_f32_e32 v16, v16
	v_mul_f32_e32 v20, 0x2f800000, v16
	v_floor_f32_e32 v20, v20
	v_fmac_f32_e32 v16, 0xcf800000, v20
	v_cvt_u32_f32_e32 v34, v16
	v_cvt_u32_f32_e32 v35, v20
	v_lshl_add_u64 v[32:33], v[32:33], 3, s[0:1]
	global_atomic_add_x2 v[32:33], v[34:35], off
; __device__ __forceinline__ float row16_sum(float v) { DPP_ADD(v, 0x128); DPP_ADD(v, 0x124); DPP_ADD(v, 0x122); DPP_ADD(v, 0x121); return v; }
; template <int EPI, int N, int K>
; __device__ __forceinline__ void gemm_phase(const bf16_t* __restrict__ A, const bf16_t* __restrict__ Bt, const EpiArgs ea) {
;     ...
;           for (int j = 0; j < 4; ++j) {
;             const int row = brow + ai * 128 + wr * 64 + m * 16 + fq * 4 + j;
;             const u32x2 x2 = *(const u32x2*)(ea.outb + (size_t)row * DM + c0);
;             float4 xn;
;             xn.x = __builtin_bit_cast(float, x2[0] << 16) + acc[ai][0][m][0][j]; xn.y = __builtin_bit_cast(float, x2[0] & 0xffff0000u) + acc[ai][0][m][1][j];
;             xn.z = __builtin_bit_cast(float, x2[1] << 16) + acc[ai][1][m][0][j]; xn.w = __builtin_bit_cast(float, x2[1] & 0xffff0000u) + acc[ai][1][m][1][j];
;             u32x2 o = {pk2(xn.x, xn.y), pk2(xn.z, xn.w)};
;             st_wt(ea.outb + (size_t)row * DM + c0, o);
;             float ss = xn.x * xn.x + xn.y * xn.y + xn.z * xn.z + xn.w * xn.w;
;             ss = row16_sum(ss);
;             if (fr == 0) __hip_atomic_fetch_add(ea.rowsq_out + row, (rsq_t)(ss * RSQ_SCALE), __ATOMIC_RELAXED, __HIP_MEMORY_SCOPE_AGENT);
.LBB0_623:
	s_or_b64 exec, exec, s[2:3]
	v_add_u32_e32 v32, 0xa1, v132
	v_ashrrev_i32_e32 v33, 31, v32
	v_lshlrev_b64 v[34:35], 12, v[32:33]
	v_lshl_add_u64 v[34:35], v[134:135], 0, v[34:35]
	v_mov_b32_e32 v16, v21
	v_mov_b32_e32 v24, v29
	v_mov_b32_e32 v36, v212
	v_mov_b32_e32 v37, v213
	v_lshlrev_b32_e32 v38, 16, v36
	v_and_b32_e32 v39, 0xffff0000, v36
	v_pk_add_f32 v[16:17], v[16:17], v[38:39]
	v_lshlrev_b32_e32 v20, 16, v37
	v_and_b32_e32 v21, 0xffff0000, v37
	v_pk_add_f32 v[20:21], v[24:25], v[20:21]
	v_cvt_pk_bf16_f32 v24, v16, v17
	v_pk_mul_f32 v[16:17], v[16:17], v[16:17]
	v_cvt_pk_bf16_f32 v25, v20, v21
	v_pk_mul_f32 v[20:21], v[20:21], v[20:21]
	v_add_f32_e32 v16, v16, v17
	v_add_f32_e32 v16, v20, v16
	v_add_f32_e32 v16, v21, v16
	v_mov_b32_e32 v17, 0
	global_store_dwordx2 v[34:35], v[24:25], off sc1
	v_add_f32_dpp v16, v16, v16 row_ror:8 row_mask:0xf bank_mask:0xf bound_ctrl:1
	s_nop 1
	v_add_f32_dpp v16, v16, v16 row_ror:4 row_mask:0xf bank_mask:0xf bound_ctrl:1
	s_nop 1
	v_add_f32_dpp v16, v16, v16 row_ror:2 row_mask:0xf bank_mask:0xf bound_ctrl:1
	s_nop 1
	v_mov_b32_dpp v17, v16 row_ror:1 row_mask:0xf bank_mask:0xf
	s_and_saveexec_b64 s[2:3], s[8:9]
	s_cbranch_execz .LBB0_625
	v_add_f32_e32 v16, v16, v17
	v_mul_f32_e32 v16, 0x49800000, v16
	v_trunc_f32_e32 v16, v16
	v_mul_f32_e32 v17, 0x2f800000, v16
	v_floor_f32_e32 v17, v17
	v_fmac_f32_e32 v16, 0xcf800000, v17
	v_cvt_u32_f32_e32 v16, v16
	v_cvt_u32_f32_e32 v17, v17
	v_lshl_add_u64 v[20:21], v[32:33], 3, s[0:1]
	global_atomic_add_x2 v[20:21], v[16:17], off
.LBB0_625:
	s_or_b64 exec, exec, s[2:3]
	v_add_u32_e32 v16, 0xa2, v132
	v_ashrrev_i32_e32 v17, 31, v16
	v_lshlrev_b64 v[20:21], 12, v[16:17]
	v_lshl_add_u64 v[20:21], v[134:135], 0, v[20:21]
	v_mov_b32_e32 v32, v22
	v_mov_b32_e32 v33, v18
	v_mov_b32_e32 v24, v214
	v_mov_b32_e32 v25, v215
	v_lshlrev_b32_e32 v28, 16, v24
	v_and_b32_e32 v29, 0xffff0000, v24
	v_pk_add_f32 v[28:29], v[32:33], v[28:29]
	v_lshlrev_b32_e32 v24, 16, v25
	v_and_b32_e32 v25, 0xffff0000, v25
	v_mov_b32_e32 v32, v30
	v_mov_b32_e32 v33, v26
	v_pk_add_f32 v[24:25], v[32:33], v[24:25]
	v_cvt_pk_bf16_f32 v32, v28, v29
	v_cvt_pk_bf16_f32 v33, v24, v25
	global_store_dwordx2 v[20:21], v[32:33], off sc1
	v_pk_mul_f32 v[20:21], v[28:29], v[28:29]
	v_pk_mul_f32 v[24:25], v[24:25], v[24:25]
	v_add_f32_e32 v18, v20, v21
	v_add_f32_e32 v18, v24, v18
	v_add_f32_e32 v18, v25, v18
	v_mov_b32_e32 v20, 0
	s_nop 0
	v_add_f32_dpp v18, v18, v18 row_ror:8 row_mask:0xf bank_mask:0xf bound_ctrl:1
	s_nop 1
	v_add_f32_dpp v18, v18, v18 row_ror:4 row_mask:0xf bank_mask:0xf bound_ctrl:1
	s_nop 1
	v_add_f32_dpp v18, v18, v18 row_ror:2 row_mask:0xf bank_mask:0xf bound_ctrl:1
	s_nop 1
	v_mov_b32_dpp v20, v18 row_ror:1 row_mask:0xf bank_mask:0xf
	s_and_saveexec_b64 s[2:3], s[8:9]
	s_cbranch_execz .LBB0_627
	v_add_f32_e32 v18, v18, v20
	v_mul_f32_e32 v18, 0x49800000, v18
	v_trunc_f32_e32 v18, v18
	v_mul_f32_e32 v20, 0x2f800000, v18
	v_floor_f32_e32 v21, v20
	v_fmac_f32_e32 v18, 0xcf800000, v21
	v_cvt_u32_f32_e32 v20, v18
	v_cvt_u32_f32_e32 v21, v21
	v_lshl_add_u64 v[16:17], v[16:17], 3, s[0:1]
	global_atomic_add_x2 v[16:17], v[20:21], off
.LBB0_627:
	s_or_b64 exec, exec, s[2:3]
	v_add_u32_e32 v16, 0xa3, v132
	v_ashrrev_i32_e32 v17, 31, v16
	v_lshlrev_b64 v[20:21], 12, v[16:17]
	v_lshl_add_u64 v[20:21], v[134:135], 0, v[20:21]
	v_mov_b32_e32 v18, v23
	v_mov_b32_e32 v26, v31
	v_mov_b32_e32 v24, v216
	v_mov_b32_e32 v25, v217
	v_lshlrev_b32_e32 v22, 16, v24
	v_and_b32_e32 v23, 0xffff0000, v24
	v_lshlrev_b32_e32 v24, 16, v25
	v_and_b32_e32 v25, 0xffff0000, v25
	v_pk_add_f32 v[18:19], v[18:19], v[22:23]
	v_pk_add_f32 v[22:23], v[26:27], v[24:25]
	v_cvt_pk_bf16_f32 v24, v18, v19
	v_pk_mul_f32 v[18:19], v[18:19], v[18:19]
	v_cvt_pk_bf16_f32 v25, v22, v23
	v_pk_mul_f32 v[22:23], v[22:23], v[22:23]
	v_add_f32_e32 v18, v18, v19
	v_add_f32_e32 v18, v22, v18
	v_add_f32_e32 v18, v23, v18
	v_mov_b32_e32 v19, 0
	global_store_dwordx2 v[20:21], v[24:25], off sc1
	v_add_f32_dpp v18, v18, v18 row_ror:8 row_mask:0xf bank_mask:0xf bound_ctrl:1
	s_nop 1
	v_add_f32_dpp v18, v18, v18 row_ror:4 row_mask:0xf bank_mask:0xf bound_ctrl:1
	s_nop 1
	v_add_f32_dpp v18, v18, v18 row_ror:2 row_mask:0xf bank_mask:0xf bound_ctrl:1
	s_nop 1
	v_mov_b32_dpp v19, v18 row_ror:1 row_mask:0xf bank_mask:0xf
	s_and_saveexec_b64 s[2:3], s[8:9]
	s_cbranch_execz .LBB0_629
	v_add_f32_e32 v18, v18, v19
	v_mul_f32_e32 v18, 0x49800000, v18
	v_trunc_f32_e32 v18, v18
	v_mul_f32_e32 v19, 0x2f800000, v18
	v_floor_f32_e32 v19, v19
	v_fmac_f32_e32 v18, 0xcf800000, v19
	v_cvt_u32_f32_e32 v18, v18
	v_cvt_u32_f32_e32 v19, v19
	v_lshl_add_u64 v[16:17], v[16:17], 3, s[0:1]
	global_atomic_add_x2 v[16:17], v[18:19], off
; __device__ __forceinline__ float row16_sum(float v) { DPP_ADD(v, 0x128); DPP_ADD(v, 0x124); DPP_ADD(v, 0x122); DPP_ADD(v, 0x121); return v; }
; template <int EPI, int N, int K>
; __device__ __forceinline__ void gemm_phase(const bf16_t* __restrict__ A, const bf16_t* __restrict__ Bt, const EpiArgs ea) {
;     ...
;           for (int j = 0; j < 4; ++j) {
;             const int row = brow + ai * 128 + wr * 64 + m * 16 + fq * 4 + j;
;             const u32x2 x2 = *(const u32x2*)(ea.outb + (size_t)row * DM + c0);
;             float4 xn;
;             xn.x = __builtin_bit_cast(float, x2[0] << 16) + acc[ai][0][m][0][j]; xn.y = __builtin_bit_cast(float, x2[0] & 0xffff0000u) + acc[ai][0][m][1][j];
;             xn.z = __builtin_bit_cast(float, x2[1] << 16) + acc[ai][1][m][0][j]; xn.w = __builtin_bit_cast(float, x2[1] & 0xffff0000u) + acc[ai][1][m][1][j];
;             u32x2 o = {pk2(xn.x, xn.y), pk2(xn.z, xn.w)};
;             st_wt(ea.outb + (size_t)row * DM + c0, o);
;             float ss = xn.x * xn.x + xn.y * xn.y + xn.z * xn.z + xn.w * xn.w;
;             ss = row16_sum(ss);
;             if (fr == 0) __hip_atomic_fetch_add(ea.rowsq_out + row, (rsq_t)(ss * RSQ_SCALE), __ATOMIC_RELAXED, __HIP_MEMORY_SCOPE_AGENT);
.LBB0_629:
	s_or_b64 exec, exec, s[2:3]
	v_add_u32_e32 v16, 0xb0, v132
	v_ashrrev_i32_e32 v17, 31, v16
	v_lshlrev_b64 v[18:19], 12, v[16:17]
	v_lshl_add_u64 v[18:19], v[134:135], 0, v[18:19]
	v_mov_b32_e32 v24, v8
	v_mov_b32_e32 v25, v12
	v_mov_b32_e32 v20, v218
	v_mov_b32_e32 v21, v219
	v_lshlrev_b32_e32 v22, 16, v20
	v_and_b32_e32 v23, 0xffff0000, v20
	v_pk_add_f32 v[22:23], v[24:25], v[22:23]
	v_lshlrev_b32_e32 v20, 16, v21
	v_and_b32_e32 v21, 0xffff0000, v21
	v_mov_b32_e32 v24, v4
	v_mov_b32_e32 v25, v0
	v_pk_add_f32 v[20:21], v[24:25], v[20:21]
	v_cvt_pk_bf16_f32 v24, v22, v23
	v_cvt_pk_bf16_f32 v25, v20, v21
	global_store_dwordx2 v[18:19], v[24:25], off sc1
	v_pk_mul_f32 v[18:19], v[22:23], v[22:23]
	v_pk_mul_f32 v[20:21], v[20:21], v[20:21]
	v_add_f32_e32 v0, v18, v19
	v_add_f32_e32 v0, v20, v0
	v_add_f32_e32 v0, v21, v0
	v_mov_b32_e32 v4, 0
	s_nop 0
	v_add_f32_dpp v0, v0, v0 row_ror:8 row_mask:0xf bank_mask:0xf bound_ctrl:1
	s_nop 1
	v_add_f32_dpp v0, v0, v0 row_ror:4 row_mask:0xf bank_mask:0xf bound_ctrl:1
	s_nop 1
	v_add_f32_dpp v0, v0, v0 row_ror:2 row_mask:0xf bank_mask:0xf bound_ctrl:1
	s_nop 1
	v_mov_b32_dpp v4, v0 row_ror:1 row_mask:0xf bank_mask:0xf
	s_and_saveexec_b64 s[2:3], s[8:9]
	s_cbranch_execz .LBB0_631
	v_add_f32_e32 v0, v0, v4
	v_mul_f32_e32 v0, 0x49800000, v0
	v_trunc_f32_e32 v0, v0
	v_mul_f32_e32 v4, 0x2f800000, v0
	v_floor_f32_e32 v4, v4
	v_fmac_f32_e32 v0, 0xcf800000, v4
	v_cvt_u32_f32_e32 v18, v0
	v_cvt_u32_f32_e32 v19, v4
	v_lshl_add_u64 v[16:17], v[16:17], 3, s[0:1]
	global_atomic_add_x2 v[16:17], v[18:19], off
.LBB0_631:
	s_or_b64 exec, exec, s[2:3]
	v_add_u32_e32 v16, 0xb1, v132
	v_ashrrev_i32_e32 v17, 31, v16
	v_lshlrev_b64 v[18:19], 12, v[16:17]
	v_lshl_add_u64 v[18:19], v[134:135], 0, v[18:19]
	v_mov_b32_e32 v12, v9
	v_mov_b32_e32 v0, v5
	v_mov_b32_e32 v20, v220
	v_mov_b32_e32 v21, v221
	v_lshlrev_b32_e32 v22, 16, v20
	v_and_b32_e32 v23, 0xffff0000, v20
	v_pk_add_f32 v[8:9], v[12:13], v[22:23]
	v_lshlrev_b32_e32 v12, 16, v21
	v_and_b32_e32 v13, 0xffff0000, v21
	v_pk_add_f32 v[0:1], v[0:1], v[12:13]
	v_cvt_pk_bf16_f32 v4, v8, v9
	v_cvt_pk_bf16_f32 v5, v0, v1
	global_store_dwordx2 v[18:19], v[4:5], off sc1
	v_pk_mul_f32 v[4:5], v[8:9], v[8:9]
	v_pk_mul_f32 v[0:1], v[0:1], v[0:1]
	v_add_f32_e32 v4, v4, v5
	v_add_f32_e32 v0, v0, v4
	v_add_f32_e32 v0, v1, v0
	v_mov_b32_e32 v1, 0
	s_nop 0
	v_add_f32_dpp v0, v0, v0 row_ror:8 row_mask:0xf bank_mask:0xf bound_ctrl:1
	s_nop 1
	v_add_f32_dpp v0, v0, v0 row_ror:4 row_mask:0xf bank_mask:0xf bound_ctrl:1
	s_nop 1
	v_add_f32_dpp v0, v0, v0 row_ror:2 row_mask:0xf bank_mask:0xf bound_ctrl:1
	s_nop 1
	v_mov_b32_dpp v1, v0 row_ror:1 row_mask:0xf bank_mask:0xf
	s_and_saveexec_b64 s[2:3], s[8:9]
	s_cbranch_execz .LBB0_633
	v_add_f32_e32 v0, v0, v1
	v_mul_f32_e32 v0, 0x49800000, v0
	v_trunc_f32_e32 v0, v0
	v_mul_f32_e32 v1, 0x2f800000, v0
	v_floor_f32_e32 v1, v1
	v_fmac_f32_e32 v0, 0xcf800000, v1
	v_cvt_u32_f32_e32 v0, v0
	v_cvt_u32_f32_e32 v1, v1
	v_lshl_add_u64 v[4:5], v[16:17], 3, s[0:1]
	global_atomic_add_x2 v[4:5], v[0:1], off
.LBB0_633:
	s_or_b64 exec, exec, s[2:3]
	v_add_u32_e32 v0, 0xb2, v132
	v_ashrrev_i32_e32 v1, 31, v0
	v_lshlrev_b64 v[4:5], 12, v[0:1]
	v_lshl_add_u64 v[4:5], v[134:135], 0, v[4:5]
	v_mov_b32_e32 v16, v10
	v_mov_b32_e32 v17, v14
	v_mov_b32_e32 v8, v222
	v_mov_b32_e32 v9, v223
	v_lshlrev_b32_e32 v12, 16, v8
	v_and_b32_e32 v13, 0xffff0000, v8
	v_pk_add_f32 v[12:13], v[16:17], v[12:13]
	v_lshlrev_b32_e32 v8, 16, v9
	v_and_b32_e32 v9, 0xffff0000, v9
	v_mov_b32_e32 v16, v6
	v_mov_b32_e32 v17, v2
	v_pk_add_f32 v[8:9], v[16:17], v[8:9]
	v_cvt_pk_bf16_f32 v16, v12, v13
	v_cvt_pk_bf16_f32 v17, v8, v9
	global_store_dwordx2 v[4:5], v[16:17], off sc1
	v_pk_mul_f32 v[4:5], v[12:13], v[12:13]
	v_pk_mul_f32 v[8:9], v[8:9], v[8:9]
	v_add_f32_e32 v2, v4, v5
	v_add_f32_e32 v2, v8, v2
	v_add_f32_e32 v2, v9, v2
	v_mov_b32_e32 v4, 0
	s_nop 0
	v_add_f32_dpp v2, v2, v2 row_ror:8 row_mask:0xf bank_mask:0xf bound_ctrl:1
	s_nop 1
	v_add_f32_dpp v2, v2, v2 row_ror:4 row_mask:0xf bank_mask:0xf bound_ctrl:1
	s_nop 1
	v_add_f32_dpp v2, v2, v2 row_ror:2 row_mask:0xf bank_mask:0xf bound_ctrl:1
	s_nop 1
	v_mov_b32_dpp v4, v2 row_ror:1 row_mask:0xf bank_mask:0xf
	s_and_saveexec_b64 s[2:3], s[8:9]
	s_cbranch_execz .LBB0_635
	v_add_f32_e32 v2, v2, v4
	v_mul_f32_e32 v2, 0x49800000, v2
	v_trunc_f32_e32 v2, v2
	v_mul_f32_e32 v4, 0x2f800000, v2
	v_floor_f32_e32 v5, v4
	v_fmac_f32_e32 v2, 0xcf800000, v5
	v_cvt_u32_f32_e32 v4, v2
	v_cvt_u32_f32_e32 v5, v5
	v_lshl_add_u64 v[0:1], v[0:1], 3, s[0:1]
	global_atomic_add_x2 v[0:1], v[4:5], off
.LBB0_635:
	s_or_b64 exec, exec, s[2:3]
	v_add_u32_e32 v0, 0xb3, v132
	v_ashrrev_i32_e32 v1, 31, v0
	v_lshlrev_b64 v[4:5], 12, v[0:1]
	v_lshl_add_u64 v[4:5], v[134:135], 0, v[4:5]
	v_mov_b32_e32 v14, v11
	v_mov_b32_e32 v2, v7
	v_mov_b32_e32 v8, v224
	v_mov_b32_e32 v9, v225
	v_lshlrev_b32_e32 v12, 16, v8
	v_and_b32_e32 v13, 0xffff0000, v8
	v_lshlrev_b32_e32 v8, 16, v9
	v_and_b32_e32 v9, 0xffff0000, v9
	v_pk_add_f32 v[10:11], v[14:15], v[12:13]
	v_pk_add_f32 v[2:3], v[2:3], v[8:9]
	v_cvt_pk_bf16_f32 v6, v10, v11
	v_cvt_pk_bf16_f32 v7, v2, v3
	global_store_dwordx2 v[4:5], v[6:7], off sc1
	v_pk_mul_f32 v[4:5], v[10:11], v[10:11]
	v_pk_mul_f32 v[2:3], v[2:3], v[2:3]
	v_add_f32_e32 v4, v4, v5
	v_add_f32_e32 v2, v2, v4
	v_add_f32_e32 v2, v3, v2
	v_mov_b32_e32 v3, 0
	s_nop 0
	v_add_f32_dpp v2, v2, v2 row_ror:8 row_mask:0xf bank_mask:0xf bound_ctrl:1
	s_nop 1
	v_add_f32_dpp v2, v2, v2 row_ror:4 row_mask:0xf bank_mask:0xf bound_ctrl:1
	s_nop 1
	v_add_f32_dpp v2, v2, v2 row_ror:2 row_mask:0xf bank_mask:0xf bound_ctrl:1
	s_nop 1
	v_mov_b32_dpp v3, v2 row_ror:1 row_mask:0xf bank_mask:0xf
	s_and_saveexec_b64 s[2:3], s[8:9]
	s_cbranch_execz .LBB0_562
	v_add_f32_e32 v2, v2, v3
	v_mul_f32_e32 v2, 0x49800000, v2
	v_trunc_f32_e32 v2, v2
	v_mul_f32_e32 v3, 0x2f800000, v2
	v_floor_f32_e32 v3, v3
	v_fmac_f32_e32 v2, 0xcf800000, v3
	v_cvt_u32_f32_e32 v2, v2
	v_cvt_u32_f32_e32 v3, v3
	v_lshl_add_u64 v[0:1], v[0:1], 3, s[0:1]
	global_atomic_add_x2 v[0:1], v[2:3], off
	s_branch .LBB0_562
